# ctx split-K items store per-split partial tiles (plain stores into the dead V^T buffer) instead of 64 f32 atomics per lane; the following LayerNorm row pass adds the four partials to the ctx rows
# baseline (speedup 1.0000x reference)
.LBB0_684:
	s_and_b64 vcc, exec, s[60:61]
	s_mov_b64 s[96:97], s[62:63]
	s_cbranch_vccz .LBB0_945
	s_mov_b32 s54, s94
	s_cmp_gt_i32 s54, 63
	s_cbranch_scc1 .LBB0_945
	s_add_u32 s62, s14, 0xe000
	s_addc_u32 s63, s15, 0
	v_lshrrev_b32_e32 v0, 3, v142
	s_and_b32 s64, s54, 3
	s_lshl_b32 s64, s64, 21
	s_add_u32 s64, s64, 0xbfea000
	s_add_u32 s64, s4, s64
	s_addc_u32 s65, s5, 0
	v_and_b32_e32 v84, 31, v142
	v_and_b32_e32 v85, 4, v0
	s_lshl_b32 s76, s54, 8
	s_lshl_b32 s90, s54, 5
	s_branch .LBB0_688
.LBB0_687:
	s_or_b64 exec, exec, s[0:1]
	v_ashrrev_i32_e32 v31, 31, v30
	v_lshlrev_b64 v[2:3], 12, v[30:31]
	v_lshl_add_u64 v[0:1], v[0:1], 0, v[2:3]
	v_lshl_add_u64 v[0:1], v[0:1], 0, v[176:177]
	v_mul_f32_e32 v2, v15, v50
	global_store_dword v[0:1], v2, off offset:128
	v_readlane_b32 s0, v255, 10
	s_add_i32 s76, s76, s0
	v_readlane_b32 s0, v255, 11
	s_add_i32 s54, s54, s36
	s_add_i32 s90, s90, s0
	s_cmp_lt_i32 s54, 64
	s_cbranch_scc0 .LBB0_944
.LBB0_688:
	s_and_b32 s0, s76, 0x300
	s_lshr_b32 s4, s54, 5
	s_lshl_b32 s0, s0, 1
	s_add_u32 s2, s42, s0
	s_addc_u32 s3, s43, 0
	v_mov_b32_e32 v12, v190
	s_mulk_i32 s4, 0x2100
	s_add_u32 s6, s58, s0
	s_addc_u32 s7, s59, 0
	v_ashrrev_i32_e32 v8, 3, v12
	v_lshrrev_b32_e32 v0, 4, v12
	s_and_b32 s0, s90, 0x380
	v_xor_b32_e32 v13, v0, v12
	v_add_u32_e32 v14, s4, v8
	v_add_u32_e32 v2, 64, v14
	v_mov_b64_e32 v[0:1], s[2:3]
	v_add_u32_e32 v4, 0x80, v14
	v_add_u32_e32 v6, 0xc0, v14
	v_add_u32_e32 v15, s0, v8
	v_mov_b64_e32 v[8:9], s[6:7]
	v_lshlrev_b32_e32 v13, 4, v13
	v_mad_i64_i32 v[2:3], s[2:3], v2, s78, v[0:1]
	v_mad_i64_i32 v[4:5], s[2:3], v4, s78, v[0:1]
	v_mad_i64_i32 v[6:7], s[2:3], v6, s78, v[0:1]
	v_mad_i64_i32 v[10:11], s[2:3], v15, s78, v[8:9]
	v_add_u32_e32 v15, 64, v15
	v_mad_i64_i32 v[0:1], s[2:3], v14, s78, v[0:1]
	v_and_b32_e32 v176, 0x70, v13
	v_mad_i64_i32 v[8:9], s[2:3], v15, s78, v[8:9]
	v_lshrrev_b32_e32 v15, 5, v12
	v_lshl_add_u64 v[74:75], v[0:1], 0, v[176:177]
	v_lshrrev_b32_e32 v0, 1, v12
	v_lshlrev_b32_e32 v1, 7, v12
	v_xor_b32_e32 v0, v15, v0
	v_lshl_add_u64 v[72:73], v[2:3], 0, v[176:177]
	v_and_b32_e32 v1, 0xf80, v1
	v_lshlrev_b32_e32 v0, 4, v0
	v_lshlrev_b32_e32 v2, 3, v12
	v_and_b32_e32 v0, 16, v0
	v_and_or_b32 v1, v2, s81, v1
	v_or_b32_e32 v87, v1, v0
	v_bitop3_b32 v79, v1, 32, v0 bitop3:0x36
	v_bitop3_b32 v78, v1, 64, v0 bitop3:0x36
	v_bitop3_b32 v77, v1, s81, v0 bitop3:0x36
	v_ashrrev_i32_e32 v0, 1, v12
	v_lshl_add_u32 v2, v12, 4, 0
	v_and_b32_e32 v86, 0xffffffc0, v0
	v_readfirstlane_b32 s7, v2
	v_add_u32_e32 v0, 0x2000, v2
	s_mov_b32 m0, s7
	v_readfirstlane_b32 s1, v0
	v_add_u32_e32 v0, 0x4000, v2
	global_load_lds_dwordx4 v[74:75], off
	s_mov_b32 m0, s1
	v_readfirstlane_b32 s3, v0
	v_add_u32_e32 v0, 0x6000, v2
	v_lshl_add_u64 v[70:71], v[4:5], 0, v[176:177]
	global_load_lds_dwordx4 v[72:73], off
	s_mov_b32 m0, s3
	v_readfirstlane_b32 s2, v0
	v_add_u32_e32 v0, 0x8000, v2
	v_lshl_add_u64 v[68:69], v[6:7], 0, v[176:177]
	global_load_lds_dwordx4 v[70:71], off
	s_mov_b32 m0, s2
	v_readfirstlane_b32 s6, v0
	v_add_u32_e32 v0, 0xa000, v2
	v_lshl_add_u64 v[66:67], v[10:11], 0, v[176:177]
	global_load_lds_dwordx4 v[68:69], off
	s_mov_b32 m0, s6
	v_readfirstlane_b32 s5, v0
	v_add_u32_e32 v3, 0xc000, v2
	v_lshl_add_u64 v[64:65], v[8:9], 0, v[176:177]
	global_load_lds_dwordx4 v[66:67], off
	s_mov_b32 m0, s5
	v_readfirstlane_b32 s8, v3
	v_add_u32_e32 v3, 0xe000, v2
	global_load_lds_dwordx4 v[64:65], off
	v_lshl_add_u64 v[0:1], v[74:75], 0, s[66:67]
	s_mov_b32 m0, s8
	v_readfirstlane_b32 s8, v3
	v_add_u32_e32 v3, 0x10000, v2
	global_load_lds_dwordx4 v[0:1], off
	v_lshl_add_u64 v[0:1], v[72:73], 0, s[66:67]
	s_mov_b32 m0, s8
	v_readfirstlane_b32 s8, v3
	v_add_u32_e32 v3, 0x12000, v2
	global_load_lds_dwordx4 v[0:1], off
	v_lshl_add_u64 v[0:1], v[70:71], 0, s[66:67]
	s_mov_b32 m0, s8
	v_readfirstlane_b32 s8, v3
	v_add_u32_e32 v3, 0x14000, v2
	global_load_lds_dwordx4 v[0:1], off
	v_lshl_add_u64 v[0:1], v[68:69], 0, s[66:67]
	s_mov_b32 m0, s8
	v_readfirstlane_b32 s8, v3
	v_add_u32_e32 v3, 0x16000, v2
	global_load_lds_dwordx4 v[0:1], off
	v_lshl_add_u64 v[0:1], v[66:67], 0, s[66:67]
	s_mov_b32 m0, s8
	v_readfirstlane_b32 s8, v3
	v_add_u32_e32 v3, 0x18000, v2
	global_load_lds_dwordx4 v[0:1], off
	v_lshl_add_u64 v[0:1], v[64:65], 0, s[66:67]
	s_mov_b32 m0, s8
	v_readfirstlane_b32 s8, v3
	v_add_u32_e32 v3, 0x1a000, v2
	global_load_lds_dwordx4 v[0:1], off
	v_lshl_add_u64 v[0:1], v[74:75], 0, s[70:71]
	s_mov_b32 m0, s8
	v_readfirstlane_b32 s8, v3
	v_add_u32_e32 v3, 0x1c000, v2
	s_waitcnt vmcnt(6)
	s_barrier
	global_load_lds_dwordx4 v[0:1], off
	v_lshl_add_u64 v[0:1], v[72:73], 0, s[70:71]
	s_mov_b32 m0, s8
	v_readfirstlane_b32 s8, v3
	v_add_u32_e32 v3, 0x1e000, v2
	global_load_lds_dwordx4 v[0:1], off
	v_lshl_add_u64 v[0:1], v[70:71], 0, s[70:71]
	s_mov_b32 m0, s8
	v_readfirstlane_b32 s8, v3
	v_add_u32_e32 v3, 0x20000, v2
	global_load_lds_dwordx4 v[0:1], off
	v_lshl_add_u64 v[0:1], v[68:69], 0, s[70:71]
	s_mov_b32 m0, s8
	v_readfirstlane_b32 s8, v3
	v_add_u32_e32 v2, 0x22000, v2
	global_load_lds_dwordx4 v[0:1], off
	v_lshl_add_u64 v[0:1], v[66:67], 0, s[70:71]
	s_mov_b32 m0, s8
	v_readfirstlane_b32 s8, v2
	global_load_lds_dwordx4 v[0:1], off
	v_lshl_add_u64 v[0:1], v[64:65], 0, s[70:71]
	s_mov_b32 m0, s8
	v_and_b32_e32 v76, 64, v12
	global_load_lds_dwordx4 v[0:1], off
	v_lshlrev_b32_e32 v116, 7, v86
	v_lshlrev_b32_e32 v117, 7, v76
	v_add_u32_e32 v118, 0, v116
	v_add_u32_e32 v120, 0, v117
	v_add_u32_e32 v119, v118, v87
	v_add_u32_e32 v121, v120, v87
	v_add_u32_e32 v122, v118, v79
	v_add_u32_e32 v123, v120, v79
	ds_read_b128 v[0:3], v119
	ds_read_b128 v[4:7], v121 offset:32768
	ds_read_b128 v[8:11], v119 offset:4096
	ds_read_b128 v[12:15], v121 offset:36864
	ds_read_b128 v[80:83], v122
	ds_read_b128 v[88:91], v123 offset:32768
	ds_read_b128 v[92:95], v122 offset:4096
	ds_read_b128 v[96:99], v123 offset:36864
	s_waitcnt lgkmcnt(0)
	v_mfma_f32_32x32x16_bf16 v[48:63], v[0:3], v[4:7], 0
	v_add_u32_e32 v124, v118, v78
	v_add_u32_e32 v125, v120, v78
	ds_read_b128 v[100:103], v124
	ds_read_b128 v[104:107], v125 offset:32768
	ds_read_b128 v[108:111], v124 offset:4096
	ds_read_b128 v[112:115], v125 offset:36864
	v_mfma_f32_32x32x16_bf16 v[32:47], v[0:3], v[12:15], 0
	v_mfma_f32_32x32x16_bf16 v[16:31], v[8:11], v[4:7], 0
	v_mfma_f32_32x32x16_bf16 v[0:15], v[8:11], v[12:15], 0
	v_mfma_f32_32x32x16_bf16 v[48:63], v[80:83], v[88:91], v[48:63]
	v_add_u32_e32 v118, v118, v77
	v_add_u32_e32 v126, v120, v77
	v_mfma_f32_32x32x16_bf16 v[32:47], v[80:83], v[96:99], v[32:47]
	ds_read_b128 v[80:83], v118
	v_mfma_f32_32x32x16_bf16 v[16:31], v[92:95], v[88:91], v[16:31]
	v_mfma_f32_32x32x16_bf16 v[0:15], v[92:95], v[96:99], v[0:15]
	ds_read_b128 v[88:91], v126 offset:32768
	ds_read_b128 v[92:95], v118 offset:4096
	ds_read_b128 v[96:99], v126 offset:36864
	s_mov_b32 m0, s7
	v_lshl_add_u64 v[74:75], v[74:75], 0, s[72:73]
	s_waitcnt vmcnt(6)
	s_barrier
	global_load_lds_dwordx4 v[74:75], off
	v_lshl_add_u64 v[72:73], v[72:73], 0, s[72:73]
	s_mov_b32 m0, s1
	v_lshl_add_u64 v[70:71], v[70:71], 0, s[72:73]
	global_load_lds_dwordx4 v[72:73], off
	s_mov_b32 m0, s3
	v_lshl_add_u64 v[68:69], v[68:69], 0, s[72:73]
	global_load_lds_dwordx4 v[70:71], off
	s_mov_b32 m0, s2
	v_lshl_add_u64 v[66:67], v[66:67], 0, s[72:73]
	global_load_lds_dwordx4 v[68:69], off
	s_mov_b32 m0, s6
	v_lshl_add_u64 v[64:65], v[64:65], 0, s[72:73]
	global_load_lds_dwordx4 v[66:67], off
	s_mov_b32 m0, s5
	s_waitcnt lgkmcnt(0)
	v_mfma_f32_32x32x16_bf16 v[48:63], v[100:103], v[104:107], v[48:63]
	global_load_lds_dwordx4 v[64:65], off
	v_mfma_f32_32x32x16_bf16 v[32:47], v[100:103], v[112:115], v[32:47]
	v_mfma_f32_32x32x16_bf16 v[16:31], v[108:111], v[104:107], v[16:31]
	v_mfma_f32_32x32x16_bf16 v[0:15], v[108:111], v[112:115], v[0:15]
	v_add_u32_e32 v112, 0xc000, v120
	v_add_u32_e32 v108, v112, v79
	v_mfma_f32_32x32x16_bf16 v[48:63], v[80:83], v[88:91], v[48:63]
	v_mfma_f32_32x32x16_bf16 v[32:47], v[80:83], v[96:99], v[32:47]
	v_add_u32_e32 v80, v112, v87
	ds_read_b128 v[64:67], v119 offset:49152
	ds_read_b128 v[68:71], v119 offset:53248
	ds_read_b128 v[72:75], v80 offset:32768
	ds_read_b128 v[80:83], v80 offset:36864
	v_mfma_f32_32x32x16_bf16 v[16:31], v[92:95], v[88:91], v[16:31]
	ds_read_b128 v[88:91], v122 offset:49152
	ds_read_b128 v[100:103], v122 offset:53248
	ds_read_b128 v[104:107], v108 offset:32768
	ds_read_b128 v[108:111], v108 offset:36864
	v_mfma_f32_32x32x16_bf16 v[0:15], v[92:95], v[96:99], v[0:15]
	s_waitcnt lgkmcnt(0)
	v_mfma_f32_32x32x16_bf16 v[48:63], v[64:67], v[72:75], v[48:63]
	v_mfma_f32_32x32x16_bf16 v[32:47], v[64:67], v[80:83], v[32:47]
	ds_read_b128 v[64:67], v124 offset:49152
	v_mfma_f32_32x32x16_bf16 v[16:31], v[68:71], v[72:75], v[16:31]
	v_mfma_f32_32x32x16_bf16 v[0:15], v[68:71], v[80:83], v[0:15]
	v_add_u32_e32 v80, v112, v78
	ds_read_b128 v[68:71], v80 offset:32768
	ds_read_b128 v[72:75], v124 offset:53248
	ds_read_b128 v[80:83], v80 offset:36864
	v_mfma_f32_32x32x16_bf16 v[48:63], v[88:91], v[104:107], v[48:63]
	v_mfma_f32_32x32x16_bf16 v[32:47], v[88:91], v[108:111], v[32:47]
	ds_read_b128 v[88:91], v118 offset:49152
	v_mfma_f32_32x32x16_bf16 v[16:31], v[100:103], v[104:107], v[16:31]
	v_mfma_f32_32x32x16_bf16 v[0:15], v[100:103], v[108:111], v[0:15]
	v_add_u32_e32 v100, v112, v77
	ds_read_b128 v[92:95], v100 offset:32768
	ds_read_b128 v[96:99], v118 offset:53248
	ds_read_b128 v[100:103], v100 offset:36864
	s_waitcnt lgkmcnt(0)
	v_mfma_f32_32x32x16_bf16 v[48:63], v[64:67], v[68:71], v[48:63]
	s_add_i32 s1, 0, 0x18000
	v_add_u32_e32 v104, s1, v116
	v_add_u32_e32 v105, s1, v117
	s_waitcnt vmcnt(6)
	s_barrier
	v_mfma_f32_32x32x16_bf16 v[32:47], v[64:67], v[80:83], v[32:47]
	v_mfma_f32_32x32x16_bf16 v[16:31], v[72:75], v[68:71], v[16:31]
	v_mfma_f32_32x32x16_bf16 v[0:15], v[72:75], v[80:83], v[0:15]
	v_add_u32_e32 v72, v104, v87
	v_add_u32_e32 v80, v105, v87
	v_add_u32_e32 v87, v104, v79
	v_add_u32_e32 v79, v105, v79
	ds_read_b128 v[64:67], v72
	ds_read_b128 v[68:71], v80 offset:32768
	ds_read_b128 v[72:75], v72 offset:4096
	ds_read_b128 v[80:83], v80 offset:36864
	v_mfma_f32_32x32x16_bf16 v[48:63], v[88:91], v[92:95], v[48:63]
	v_mfma_f32_32x32x16_bf16 v[32:47], v[88:91], v[100:103], v[32:47]
	ds_read_b128 v[88:91], v87
	v_mfma_f32_32x32x16_bf16 v[16:31], v[96:99], v[92:95], v[16:31]
	v_mfma_f32_32x32x16_bf16 v[0:15], v[96:99], v[100:103], v[0:15]
	ds_read_b128 v[92:95], v79 offset:32768
	ds_read_b128 v[96:99], v87 offset:4096
	ds_read_b128 v[100:103], v79 offset:36864
	s_waitcnt lgkmcnt(0)
	v_mfma_f32_32x32x16_bf16 v[48:63], v[64:67], v[68:71], v[48:63]
	v_mfma_f32_32x32x16_bf16 v[32:47], v[64:67], v[80:83], v[32:47]
	v_mfma_f32_32x32x16_bf16 v[16:31], v[72:75], v[68:71], v[16:31]
	v_mfma_f32_32x32x16_bf16 v[0:15], v[72:75], v[80:83], v[0:15]
	v_add_u32_e32 v72, v104, v78
	v_add_u32_e32 v78, v105, v78
	ds_read_b128 v[64:67], v72
	ds_read_b128 v[68:71], v78 offset:32768
	ds_read_b128 v[72:75], v72 offset:4096
	ds_read_b128 v[78:81], v78 offset:36864
	v_mfma_f32_32x32x16_bf16 v[48:63], v[88:91], v[92:95], v[48:63]
	v_add_u32_e32 v82, v104, v77
	v_add_u32_e32 v77, v105, v77
	v_mfma_f32_32x32x16_bf16 v[32:47], v[88:91], v[100:103], v[32:47]
	ds_read_b128 v[88:91], v82
	v_mfma_f32_32x32x16_bf16 v[16:31], v[96:99], v[92:95], v[16:31]
	v_mfma_f32_32x32x16_bf16 v[0:15], v[96:99], v[100:103], v[0:15]
	ds_read_b128 v[92:95], v77 offset:32768
	ds_read_b128 v[96:99], v82 offset:4096
	ds_read_b128 v[100:103], v77 offset:36864
	s_waitcnt lgkmcnt(0)
	v_mfma_f32_32x32x16_bf16 v[48:63], v[64:67], v[68:71], v[48:63]
	s_waitcnt vmcnt(0)
	s_barrier
	v_mfma_f32_32x32x16_bf16 v[32:47], v[64:67], v[78:81], v[32:47]
	v_mfma_f32_32x32x16_bf16 v[16:31], v[72:75], v[68:71], v[16:31]
	v_mfma_f32_32x32x16_bf16 v[0:15], v[72:75], v[78:81], v[0:15]
	v_mfma_f32_32x32x16_bf16 v[48:63], v[88:91], v[92:95], v[48:63]
	v_mfma_f32_32x32x16_bf16 v[32:47], v[88:91], v[100:103], v[32:47]
	v_mfma_f32_32x32x16_bf16 v[16:31], v[96:99], v[92:95], v[16:31]
	v_mfma_f32_32x32x16_bf16 v[0:15], v[96:99], v[100:103], v[0:15]
	ds_read_b128 v[64:67], v119
	ds_read_b128 v[68:71], v121 offset:32768
	ds_read_b128 v[72:75], v119 offset:4096
	ds_read_b128 v[78:81], v121 offset:36864
	ds_read_b128 v[88:91], v122
	ds_read_b128 v[92:95], v123 offset:32768
	ds_read_b128 v[96:99], v122 offset:4096
	ds_read_b128 v[100:103], v123 offset:36864
	s_waitcnt lgkmcnt(0)
	v_mfma_f32_32x32x16_bf16 v[48:63], v[64:67], v[68:71], v[48:63]
	v_mfma_f32_32x32x16_bf16 v[32:47], v[64:67], v[78:81], v[32:47]
	v_mfma_f32_32x32x16_bf16 v[16:31], v[72:75], v[68:71], v[16:31]
	v_mfma_f32_32x32x16_bf16 v[0:15], v[72:75], v[78:81], v[0:15]
	ds_read_b128 v[64:67], v124
	ds_read_b128 v[68:71], v125 offset:32768
	ds_read_b128 v[72:75], v124 offset:4096
	ds_read_b128 v[78:81], v125 offset:36864
	v_mfma_f32_32x32x16_bf16 v[48:63], v[88:91], v[92:95], v[48:63]
	v_mfma_f32_32x32x16_bf16 v[32:47], v[88:91], v[100:103], v[32:47]
	v_mfma_f32_32x32x16_bf16 v[16:31], v[96:99], v[92:95], v[16:31]
	v_mfma_f32_32x32x16_bf16 v[0:15], v[96:99], v[100:103], v[0:15]
	ds_read_b128 v[88:91], v118
	ds_read_b128 v[92:95], v126 offset:32768
	ds_read_b128 v[96:99], v118 offset:4096
	ds_read_b128 v[100:103], v126 offset:36864
	s_waitcnt lgkmcnt(0)
	v_mfma_f32_32x32x16_bf16 v[48:63], v[64:67], v[68:71], v[48:63]
	s_waitcnt vmcnt(0)
	s_barrier
	v_mfma_f32_32x32x16_bf16 v[32:47], v[64:67], v[78:81], v[32:47]
	v_or3_b32 v64, s0, v84, v76
	v_lshlrev_b32_e32 v176, 2, v64
	global_load_dword v65, v176, s[62:63]
	v_add_u32_e32 v64, s4, v86
	v_or_b32_e32 v64, v64, v85
	v_mul_hi_i32 v66, v64, s35
	v_lshrrev_b32_e32 v67, 31, v66
	v_mfma_f32_32x32x16_bf16 v[16:31], v[72:75], v[68:71], v[16:31]
	v_ashrrev_i32_e32 v66, 11, v66
	v_add_u32_e32 v67, v66, v67
	v_mad_i32_i24 v70, v67, s33, v64
	v_lshlrev_b32_e32 v68, 13, v67
	v_cmp_lt_i32_e32 vcc, s82, v70
	v_add3_u32 v64, v68, v70, s79
	v_mfma_f32_32x32x16_bf16 v[0:15], v[72:75], v[78:81], v[0:15]
	v_mfma_f32_32x32x16_bf16 v[48:63], v[88:91], v[92:95], v[48:63]
	v_mfma_f32_32x32x16_bf16 v[32:47], v[88:91], v[100:103], v[32:47]
	v_mfma_f32_32x32x16_bf16 v[16:31], v[96:99], v[92:95], v[16:31]
	v_mfma_f32_32x32x16_bf16 v[0:15], v[96:99], v[100:103], v[0:15]
	s_load_dwordx2 s[92:93], s[40:41], 0xe8
	s_waitcnt lgkmcnt(0)
	s_and_saveexec_b64 s[0:1], vcc
	s_xor_b64 s[0:1], exec, s[0:1]
	s_mov_b64 s[2:3], s[92:93]
	v_add3_u32 v66, v68, v70, s79
	s_or_saveexec_b64 s[0:1], s[0:1]
	s_waitcnt lgkmcnt(0)
	v_mov_b64_e32 v[68:69], s[2:3]
	v_lshl_add_u32 v88, v67, 8, v70
	s_xor_b64 exec, exec, s[0:1]
	v_lshl_add_u32 v66, v67, 8, v70
	v_mov_b64_e32 v[68:69], s[64:65]
	s_or_b64 exec, exec, s[0:1]
	v_ashrrev_i32_e32 v67, 31, v66
	v_lshlrev_b64 v[66:67], 12, v[66:67]
	v_lshl_add_u64 v[66:67], v[68:69], 0, v[66:67]
	v_lshl_add_u64 v[66:67], v[66:67], 0, v[176:177]
	s_waitcnt vmcnt(0)
	v_mul_f32_e32 v48, v48, v65
	global_store_dword v[66:67], v48, off
	v_or_b32_e32 v87, s4, v85
	v_add3_u32 v66, v86, v87, 1
	v_mul_hi_i32 v48, v66, s35
	v_lshrrev_b32_e32 v67, 31, v48
	v_ashrrev_i32_e32 v48, 11, v48
	v_add_u32_e32 v48, v48, v67
	v_mad_i32_i24 v69, v48, s33, v66
	v_lshlrev_b32_e32 v67, 13, v48
	v_cmp_lt_i32_e64 s[2:3], s82, v69
	v_add3_u32 v66, v67, v69, s79
	s_and_saveexec_b64 s[0:1], s[2:3]
	s_xor_b64 s[0:1], exec, s[0:1]
	s_mov_b64 s[4:5], s[92:93]
	v_add3_u32 v68, v67, v69, s79
	s_or_saveexec_b64 s[0:1], s[0:1]
	s_waitcnt lgkmcnt(0)
	v_mov_b64_e32 v[70:71], s[4:5]
	v_lshl_add_u32 v67, v48, 8, v69
	s_xor_b64 exec, exec, s[0:1]
	v_lshl_add_u32 v68, v48, 8, v69
	v_mov_b64_e32 v[70:71], s[64:65]
	s_or_b64 exec, exec, s[0:1]
	v_ashrrev_i32_e32 v69, 31, v68
	v_lshlrev_b64 v[68:69], 12, v[68:69]
	v_lshl_add_u64 v[68:69], v[70:71], 0, v[68:69]
	v_lshl_add_u64 v[68:69], v[68:69], 0, v[176:177]
	v_mul_f32_e32 v48, v49, v65
	global_store_dword v[68:69], v48, off
	v_add3_u32 v48, v86, v87, 2
	v_mul_hi_i32 v49, v48, s35
	v_lshrrev_b32_e32 v68, 31, v49
	v_ashrrev_i32_e32 v49, 11, v49
	v_add_u32_e32 v49, v49, v68
	v_mad_i32_i24 v72, v49, s33, v48
	v_lshlrev_b32_e32 v69, 13, v49
	v_cmp_lt_i32_e64 s[4:5], s82, v72
	v_add3_u32 v68, v69, v72, s79
	s_and_saveexec_b64 s[0:1], s[4:5]
	s_xor_b64 s[0:1], exec, s[0:1]
	s_mov_b64 s[6:7], s[92:93]
	v_add3_u32 v48, v69, v72, s79
	s_or_saveexec_b64 s[0:1], s[0:1]
	s_waitcnt lgkmcnt(0)
	v_mov_b64_e32 v[70:71], s[6:7]
	v_lshl_add_u32 v69, v49, 8, v72
	s_xor_b64 exec, exec, s[0:1]
	v_lshl_add_u32 v48, v49, 8, v72
	v_mov_b64_e32 v[70:71], s[64:65]
	s_or_b64 exec, exec, s[0:1]
	v_ashrrev_i32_e32 v49, 31, v48
	v_lshlrev_b64 v[48:49], 12, v[48:49]
	v_lshl_add_u64 v[48:49], v[70:71], 0, v[48:49]
	v_lshl_add_u64 v[48:49], v[48:49], 0, v[176:177]
	v_mul_f32_e32 v50, v50, v65
	global_store_dword v[48:49], v50, off
	v_add3_u32 v48, v86, v87, 3
	v_mul_hi_i32 v49, v48, s35
	v_lshrrev_b32_e32 v50, 31, v49
	v_ashrrev_i32_e32 v49, 11, v49
	v_add_u32_e32 v49, v49, v50
	v_mad_i32_i24 v72, v49, s33, v48
	v_lshlrev_b32_e32 v70, 13, v49
	v_cmp_lt_i32_e64 s[6:7], s82, v72
	v_add3_u32 v50, v70, v72, s79
	s_and_saveexec_b64 s[0:1], s[6:7]
	s_xor_b64 s[0:1], exec, s[0:1]
	s_mov_b64 s[8:9], s[92:93]
	v_add3_u32 v48, v70, v72, s79
	s_or_saveexec_b64 s[0:1], s[0:1]
	s_waitcnt lgkmcnt(0)
	v_mov_b64_e32 v[70:71], s[8:9]
	v_lshl_add_u32 v89, v49, 8, v72
	s_xor_b64 exec, exec, s[0:1]
	v_lshl_add_u32 v48, v49, 8, v72
	v_mov_b64_e32 v[70:71], s[64:65]
	s_or_b64 exec, exec, s[0:1]
	v_ashrrev_i32_e32 v49, 31, v48
	v_lshlrev_b64 v[48:49], 12, v[48:49]
	v_lshl_add_u64 v[48:49], v[70:71], 0, v[48:49]
	v_lshl_add_u64 v[48:49], v[48:49], 0, v[176:177]
	v_mul_f32_e32 v51, v51, v65
	global_store_dword v[48:49], v51, off
	v_add3_u32 v48, v86, v87, 8
	v_mul_hi_i32 v49, v48, s35
	v_lshrrev_b32_e32 v51, 31, v49
	v_ashrrev_i32_e32 v49, 11, v49
	v_add_u32_e32 v49, v49, v51
	v_mad_i32_i24 v51, v49, s33, v48
	v_lshlrev_b32_e32 v71, 13, v49
	v_cmp_lt_i32_e64 s[8:9], s82, v51
	v_add3_u32 v70, v71, v51, s79
	s_and_saveexec_b64 s[0:1], s[8:9]
	s_xor_b64 s[0:1], exec, s[0:1]
	s_mov_b64 s[10:11], s[92:93]
	v_add3_u32 v48, v71, v51, s79
	s_or_saveexec_b64 s[0:1], s[0:1]
	s_waitcnt lgkmcnt(0)
	v_mov_b64_e32 v[72:73], s[10:11]
	v_lshl_add_u32 v71, v49, 8, v51
	s_xor_b64 exec, exec, s[0:1]
	v_lshl_add_u32 v48, v49, 8, v51
	v_mov_b64_e32 v[72:73], s[64:65]
	s_or_b64 exec, exec, s[0:1]
	v_ashrrev_i32_e32 v49, 31, v48
	v_lshlrev_b64 v[48:49], 12, v[48:49]
	v_lshl_add_u64 v[48:49], v[72:73], 0, v[48:49]
	v_lshl_add_u64 v[48:49], v[48:49], 0, v[176:177]
	v_mul_f32_e32 v51, v52, v65
	global_store_dword v[48:49], v51, off
	v_add3_u32 v48, v86, v87, 9
	v_mul_hi_i32 v49, v48, s35
	v_lshrrev_b32_e32 v51, 31, v49
	v_ashrrev_i32_e32 v49, 11, v49
	v_add_u32_e32 v49, v49, v51
	v_mad_i32_i24 v51, v49, s33, v48
	v_lshlrev_b32_e32 v72, 13, v49
	v_cmp_lt_i32_e64 s[10:11], s82, v51
	v_add3_u32 v52, v72, v51, s79
	s_and_saveexec_b64 s[0:1], s[10:11]
	s_xor_b64 s[0:1], exec, s[0:1]
	s_mov_b64 s[12:13], s[92:93]
	v_add3_u32 v48, v72, v51, s79
	s_or_saveexec_b64 s[0:1], s[0:1]
	s_waitcnt lgkmcnt(0)
	v_mov_b64_e32 v[72:73], s[12:13]
	v_lshl_add_u32 v90, v49, 8, v51
	s_xor_b64 exec, exec, s[0:1]
	v_lshl_add_u32 v48, v49, 8, v51
	v_mov_b64_e32 v[72:73], s[64:65]
	s_or_b64 exec, exec, s[0:1]
	v_ashrrev_i32_e32 v49, 31, v48
	v_lshlrev_b64 v[48:49], 12, v[48:49]
	v_lshl_add_u64 v[48:49], v[72:73], 0, v[48:49]
	v_lshl_add_u64 v[48:49], v[48:49], 0, v[176:177]
	v_mul_f32_e32 v51, v53, v65
	global_store_dword v[48:49], v51, off
	v_add3_u32 v48, v86, v87, 10
	v_mul_hi_i32 v49, v48, s35
	v_lshrrev_b32_e32 v51, 31, v49
	v_ashrrev_i32_e32 v49, 11, v49
	v_add_u32_e32 v49, v49, v51
	v_mad_i32_i24 v51, v49, s33, v48
	v_lshlrev_b32_e32 v53, 13, v49
	v_cmp_lt_i32_e64 s[12:13], s82, v51
	v_add3_u32 v72, v53, v51, s79
	s_and_saveexec_b64 s[0:1], s[12:13]
	s_xor_b64 s[0:1], exec, s[0:1]
	s_mov_b64 s[14:15], s[92:93]
	v_add3_u32 v48, v53, v51, s79
	s_or_saveexec_b64 s[0:1], s[0:1]
	s_waitcnt lgkmcnt(0)
	v_mov_b64_e32 v[74:75], s[14:15]
	v_lshl_add_u32 v73, v49, 8, v51
	s_xor_b64 exec, exec, s[0:1]
	v_lshl_add_u32 v48, v49, 8, v51
	v_mov_b64_e32 v[74:75], s[64:65]
	s_or_b64 exec, exec, s[0:1]
	v_ashrrev_i32_e32 v49, 31, v48
	v_lshlrev_b64 v[48:49], 12, v[48:49]
	v_lshl_add_u64 v[48:49], v[74:75], 0, v[48:49]
	v_lshl_add_u64 v[48:49], v[48:49], 0, v[176:177]
	v_mul_f32_e32 v51, v54, v65
	global_store_dword v[48:49], v51, off
	v_add3_u32 v48, v86, v87, 11
	v_mul_hi_i32 v49, v48, s35
	v_lshrrev_b32_e32 v51, 31, v49
	v_ashrrev_i32_e32 v49, 11, v49
	v_add_u32_e32 v49, v49, v51
	v_mad_i32_i24 v51, v49, s33, v48
	v_lshlrev_b32_e32 v53, 13, v49
	v_cmp_lt_i32_e64 s[14:15], s82, v51
	v_add3_u32 v54, v53, v51, s79
	s_and_saveexec_b64 s[0:1], s[14:15]
	s_xor_b64 s[0:1], exec, s[0:1]
	s_mov_b64 s[16:17], s[92:93]
	v_add3_u32 v48, v53, v51, s79
	s_or_saveexec_b64 s[0:1], s[0:1]
	s_waitcnt lgkmcnt(0)
	v_mov_b64_e32 v[74:75], s[16:17]
	v_lshl_add_u32 v91, v49, 8, v51
	s_xor_b64 exec, exec, s[0:1]
	v_lshl_add_u32 v48, v49, 8, v51
	v_mov_b64_e32 v[74:75], s[64:65]
	s_or_b64 exec, exec, s[0:1]
	v_ashrrev_i32_e32 v49, 31, v48
	v_lshlrev_b64 v[48:49], 12, v[48:49]
	v_lshl_add_u64 v[48:49], v[74:75], 0, v[48:49]
	v_lshl_add_u64 v[48:49], v[48:49], 0, v[176:177]
	v_mul_f32_e32 v51, v55, v65
	global_store_dword v[48:49], v51, off
	v_add3_u32 v48, v86, v87, 16
	v_mul_hi_i32 v49, v48, s35
	v_lshrrev_b32_e32 v51, 31, v49
	v_ashrrev_i32_e32 v49, 11, v49
	v_add_u32_e32 v49, v49, v51
	v_mad_i32_i24 v51, v49, s33, v48
	v_lshlrev_b32_e32 v53, 13, v49
	v_cmp_lt_i32_e64 s[16:17], s82, v51
	v_add3_u32 v74, v53, v51, s79
	s_and_saveexec_b64 s[0:1], s[16:17]
	s_xor_b64 s[0:1], exec, s[0:1]
	s_mov_b64 s[18:19], s[92:93]
	v_add3_u32 v48, v53, v51, s79
	s_or_saveexec_b64 s[0:1], s[0:1]
	s_waitcnt lgkmcnt(0)
	v_mov_b64_e32 v[76:77], s[18:19]
	v_lshl_add_u32 v75, v49, 8, v51
	s_xor_b64 exec, exec, s[0:1]
	v_lshl_add_u32 v48, v49, 8, v51
	v_mov_b64_e32 v[76:77], s[64:65]
	s_or_b64 exec, exec, s[0:1]
	v_ashrrev_i32_e32 v49, 31, v48
	v_lshlrev_b64 v[48:49], 12, v[48:49]
	v_lshl_add_u64 v[48:49], v[76:77], 0, v[48:49]
	v_lshl_add_u64 v[48:49], v[48:49], 0, v[176:177]
	v_mul_f32_e32 v51, v56, v65
	global_store_dword v[48:49], v51, off
	v_add3_u32 v48, v86, v87, 17
	v_mul_hi_i32 v49, v48, s35
	v_lshrrev_b32_e32 v51, 31, v49
	v_ashrrev_i32_e32 v49, 11, v49
	v_add_u32_e32 v49, v49, v51
	v_mad_i32_i24 v51, v49, s33, v48
	v_lshlrev_b32_e32 v53, 13, v49
	v_cmp_lt_i32_e64 s[18:19], s82, v51
	v_add3_u32 v56, v53, v51, s79
	s_and_saveexec_b64 s[0:1], s[18:19]
	s_xor_b64 s[0:1], exec, s[0:1]
	s_mov_b64 s[20:21], s[92:93]
	v_add3_u32 v48, v53, v51, s79
	s_or_saveexec_b64 s[0:1], s[0:1]
	s_waitcnt lgkmcnt(0)
	v_mov_b64_e32 v[76:77], s[20:21]
	v_lshl_add_u32 v92, v49, 8, v51
	s_xor_b64 exec, exec, s[0:1]
	v_lshl_add_u32 v48, v49, 8, v51
	v_mov_b64_e32 v[76:77], s[64:65]
	s_or_b64 exec, exec, s[0:1]
	v_ashrrev_i32_e32 v49, 31, v48
	v_lshlrev_b64 v[48:49], 12, v[48:49]
	v_lshl_add_u64 v[48:49], v[76:77], 0, v[48:49]
	v_lshl_add_u64 v[48:49], v[48:49], 0, v[176:177]
	v_mul_f32_e32 v51, v57, v65
	global_store_dword v[48:49], v51, off
	v_add3_u32 v48, v86, v87, 18
	v_mul_hi_i32 v49, v48, s35
	v_lshrrev_b32_e32 v51, 31, v49
	v_ashrrev_i32_e32 v49, 11, v49
	v_add_u32_e32 v49, v49, v51
	v_mad_i32_i24 v51, v49, s33, v48
	v_lshlrev_b32_e32 v53, 13, v49
	v_cmp_lt_i32_e64 s[20:21], s82, v51
	v_add3_u32 v76, v53, v51, s79
	s_and_saveexec_b64 s[0:1], s[20:21]
	s_xor_b64 s[0:1], exec, s[0:1]
	s_mov_b64 s[22:23], s[92:93]
	v_add3_u32 v48, v53, v51, s79
	s_or_saveexec_b64 s[0:1], s[0:1]
	s_waitcnt lgkmcnt(0)
	v_mov_b64_e32 v[78:79], s[22:23]
	v_lshl_add_u32 v77, v49, 8, v51
	s_xor_b64 exec, exec, s[0:1]
	v_lshl_add_u32 v48, v49, 8, v51
	v_mov_b64_e32 v[78:79], s[64:65]
	s_or_b64 exec, exec, s[0:1]
	v_ashrrev_i32_e32 v49, 31, v48
	v_lshlrev_b64 v[48:49], 12, v[48:49]
	v_lshl_add_u64 v[48:49], v[78:79], 0, v[48:49]
	v_lshl_add_u64 v[48:49], v[48:49], 0, v[176:177]
	v_mul_f32_e32 v51, v58, v65
	global_store_dword v[48:49], v51, off
	v_add3_u32 v48, v86, v87, 19
	v_mul_hi_i32 v49, v48, s35
	v_lshrrev_b32_e32 v51, 31, v49
	v_ashrrev_i32_e32 v49, 11, v49
	v_add_u32_e32 v49, v49, v51
	v_mad_i32_i24 v51, v49, s33, v48
	v_lshlrev_b32_e32 v53, 13, v49
	v_cmp_lt_i32_e64 s[22:23], s82, v51
	v_add3_u32 v58, v53, v51, s79
	s_and_saveexec_b64 s[0:1], s[22:23]
	s_xor_b64 s[0:1], exec, s[0:1]
	s_mov_b64 s[24:25], s[92:93]
	v_add3_u32 v48, v53, v51, s79
	s_or_saveexec_b64 s[0:1], s[0:1]
	s_waitcnt lgkmcnt(0)
	v_mov_b64_e32 v[78:79], s[24:25]
	v_lshl_add_u32 v93, v49, 8, v51
	s_xor_b64 exec, exec, s[0:1]
	v_lshl_add_u32 v48, v49, 8, v51
	v_mov_b64_e32 v[78:79], s[64:65]
	s_or_b64 exec, exec, s[0:1]
	v_ashrrev_i32_e32 v49, 31, v48
	v_lshlrev_b64 v[48:49], 12, v[48:49]
	v_lshl_add_u64 v[48:49], v[78:79], 0, v[48:49]
	v_lshl_add_u64 v[48:49], v[48:49], 0, v[176:177]
	v_mul_f32_e32 v51, v59, v65
	global_store_dword v[48:49], v51, off
	v_add3_u32 v48, v86, v87, 24
	v_mul_hi_i32 v49, v48, s35
	v_lshrrev_b32_e32 v51, 31, v49
	v_ashrrev_i32_e32 v49, 11, v49
	v_add_u32_e32 v49, v49, v51
	v_mad_i32_i24 v51, v49, s33, v48
	v_lshlrev_b32_e32 v53, 13, v49
	v_cmp_lt_i32_e64 s[24:25], s82, v51
	v_add3_u32 v78, v53, v51, s79
	s_and_saveexec_b64 s[0:1], s[24:25]
	s_xor_b64 s[0:1], exec, s[0:1]
	s_mov_b64 s[26:27], s[92:93]
	v_add3_u32 v48, v53, v51, s79
	s_or_saveexec_b64 s[0:1], s[0:1]
	s_waitcnt lgkmcnt(0)
	v_mov_b64_e32 v[80:81], s[26:27]
	v_lshl_add_u32 v79, v49, 8, v51
	s_xor_b64 exec, exec, s[0:1]
	v_lshl_add_u32 v48, v49, 8, v51
	v_mov_b64_e32 v[80:81], s[64:65]
	s_or_b64 exec, exec, s[0:1]
	v_ashrrev_i32_e32 v49, 31, v48
	v_lshlrev_b64 v[48:49], 12, v[48:49]
	v_lshl_add_u64 v[48:49], v[80:81], 0, v[48:49]
	v_lshl_add_u64 v[48:49], v[48:49], 0, v[176:177]
	v_mul_f32_e32 v51, v60, v65
	global_store_dword v[48:49], v51, off
	v_add3_u32 v48, v86, v87, 25
	v_mul_hi_i32 v49, v48, s35
	v_lshrrev_b32_e32 v51, 31, v49
	v_ashrrev_i32_e32 v49, 11, v49
	v_add_u32_e32 v49, v49, v51
	v_mad_i32_i24 v51, v49, s33, v48
	v_lshlrev_b32_e32 v53, 13, v49
	v_cmp_lt_i32_e64 s[26:27], s82, v51
	v_add3_u32 v60, v53, v51, s79
	s_and_saveexec_b64 s[0:1], s[26:27]
	s_xor_b64 s[0:1], exec, s[0:1]
	s_mov_b64 s[28:29], s[92:93]
	v_add3_u32 v48, v53, v51, s79
	s_or_saveexec_b64 s[0:1], s[0:1]
	s_waitcnt lgkmcnt(0)
	v_mov_b64_e32 v[80:81], s[28:29]
	v_lshl_add_u32 v94, v49, 8, v51
	s_xor_b64 exec, exec, s[0:1]
	v_lshl_add_u32 v48, v49, 8, v51
	v_mov_b64_e32 v[80:81], s[64:65]
	s_or_b64 exec, exec, s[0:1]
	v_ashrrev_i32_e32 v49, 31, v48
	v_lshlrev_b64 v[48:49], 12, v[48:49]
	v_lshl_add_u64 v[48:49], v[80:81], 0, v[48:49]
	v_lshl_add_u64 v[48:49], v[48:49], 0, v[176:177]
	v_mul_f32_e32 v51, v61, v65
	global_store_dword v[48:49], v51, off
	v_add3_u32 v48, v86, v87, 26
	v_mul_hi_i32 v49, v48, s35
	v_lshrrev_b32_e32 v51, 31, v49
	v_ashrrev_i32_e32 v49, 11, v49
	v_add_u32_e32 v49, v49, v51
	v_mad_i32_i24 v51, v49, s33, v48
	v_lshlrev_b32_e32 v53, 13, v49
	v_cmp_lt_i32_e64 s[28:29], s82, v51
	v_add3_u32 v80, v53, v51, s79
	s_and_saveexec_b64 s[0:1], s[28:29]
	s_xor_b64 s[0:1], exec, s[0:1]
	s_mov_b64 s[30:31], s[92:93]
	v_add3_u32 v48, v53, v51, s79
	s_or_saveexec_b64 s[0:1], s[0:1]
	s_waitcnt lgkmcnt(0)
	v_mov_b64_e32 v[82:83], s[30:31]
	v_lshl_add_u32 v81, v49, 8, v51
	s_xor_b64 exec, exec, s[0:1]
	v_lshl_add_u32 v48, v49, 8, v51
	v_mov_b64_e32 v[82:83], s[64:65]
	s_or_b64 exec, exec, s[0:1]
	v_ashrrev_i32_e32 v49, 31, v48
	v_lshlrev_b64 v[48:49], 12, v[48:49]
	v_lshl_add_u64 v[48:49], v[82:83], 0, v[48:49]
	v_lshl_add_u64 v[48:49], v[48:49], 0, v[176:177]
	v_mul_f32_e32 v51, v62, v65
	global_store_dword v[48:49], v51, off
	v_add3_u32 v48, v86, v87, 27
	v_mul_hi_i32 v49, v48, s35
	v_lshrrev_b32_e32 v51, 31, v49
	v_ashrrev_i32_e32 v49, 11, v49
	v_add_u32_e32 v49, v49, v51
	v_mad_i32_i24 v51, v49, s33, v48
	v_lshlrev_b32_e32 v53, 13, v49
	v_cmp_lt_i32_e64 s[30:31], s82, v51
	v_add3_u32 v62, v53, v51, s79
	s_and_saveexec_b64 s[0:1], s[30:31]
	s_xor_b64 s[0:1], exec, s[0:1]
	s_mov_b64 s[74:75], s[92:93]
	v_add3_u32 v48, v53, v51, s79
	s_or_saveexec_b64 s[0:1], s[0:1]
	s_waitcnt lgkmcnt(0)
	v_mov_b64_e32 v[82:83], s[74:75]
	v_lshl_add_u32 v95, v49, 8, v51
	s_xor_b64 exec, exec, s[0:1]
	v_lshl_add_u32 v48, v49, 8, v51
	v_mov_b64_e32 v[82:83], s[64:65]
	s_or_b64 exec, exec, s[0:1]
	v_ashrrev_i32_e32 v49, 31, v48
	v_lshlrev_b64 v[48:49], 12, v[48:49]
	v_lshl_add_u64 v[48:49], v[82:83], 0, v[48:49]
	v_lshl_add_u64 v[48:49], v[48:49], 0, v[176:177]
	v_mul_f32_e32 v51, v63, v65
	global_store_dword v[48:49], v51, off
	v_or_b32_e32 v48, 0x80, v176
	global_load_dword v49, v48, s[62:63]
	s_and_saveexec_b64 s[0:1], vcc
	s_xor_b64 s[0:1], exec, s[0:1]
	s_mov_b64 s[74:75], s[92:93]
	s_or_saveexec_b64 s[0:1], s[0:1]
	s_waitcnt lgkmcnt(0)
	v_mov_b64_e32 v[82:83], s[74:75]
	s_xor_b64 exec, exec, s[0:1]
	v_mov_b64_e32 v[82:83], s[64:65]
	v_mov_b32_e32 v64, v88
	s_or_b64 exec, exec, s[0:1]
	v_ashrrev_i32_e32 v65, 31, v64
	v_lshlrev_b64 v[64:65], 12, v[64:65]
	v_lshl_add_u64 v[64:65], v[82:83], 0, v[64:65]
	v_lshl_add_u64 v[64:65], v[64:65], 0, v[176:177]
	s_waitcnt vmcnt(0)
	v_mul_f32_e32 v32, v32, v49
	global_store_dword v[64:65], v32, off offset:128
	s_and_saveexec_b64 s[0:1], s[2:3]
	s_xor_b64 s[0:1], exec, s[0:1]
	s_mov_b64 s[74:75], s[92:93]
	s_or_saveexec_b64 s[0:1], s[0:1]
	s_waitcnt lgkmcnt(0)
	v_mov_b64_e32 v[64:65], s[74:75]
	s_xor_b64 exec, exec, s[0:1]
	v_mov_b64_e32 v[64:65], s[64:65]
	v_mov_b32_e32 v66, v67
	s_or_b64 exec, exec, s[0:1]
	v_ashrrev_i32_e32 v67, 31, v66
	v_lshlrev_b64 v[66:67], 12, v[66:67]
	v_lshl_add_u64 v[64:65], v[64:65], 0, v[66:67]
	v_lshl_add_u64 v[64:65], v[64:65], 0, v[176:177]
	v_mul_f32_e32 v32, v33, v49
	global_store_dword v[64:65], v32, off offset:128
	s_and_saveexec_b64 s[0:1], s[4:5]
	s_xor_b64 s[0:1], exec, s[0:1]
	s_mov_b64 s[2:3], s[92:93]
	s_or_saveexec_b64 s[0:1], s[0:1]
	s_waitcnt lgkmcnt(0)
	v_mov_b64_e32 v[32:33], s[2:3]
	s_xor_b64 exec, exec, s[0:1]
	v_mov_b64_e32 v[32:33], s[64:65]
	v_mov_b32_e32 v68, v69
	s_or_b64 exec, exec, s[0:1]
	v_ashrrev_i32_e32 v69, 31, v68
	v_lshlrev_b64 v[64:65], 12, v[68:69]
	v_lshl_add_u64 v[32:33], v[32:33], 0, v[64:65]
	v_lshl_add_u64 v[32:33], v[32:33], 0, v[176:177]
	v_mul_f32_e32 v34, v34, v49
	global_store_dword v[32:33], v34, off offset:128
	s_and_saveexec_b64 s[0:1], s[6:7]
	s_xor_b64 s[0:1], exec, s[0:1]
	s_mov_b64 s[2:3], s[92:93]
	s_or_saveexec_b64 s[0:1], s[0:1]
	s_waitcnt lgkmcnt(0)
	v_mov_b64_e32 v[32:33], s[2:3]
	s_xor_b64 exec, exec, s[0:1]
	v_mov_b64_e32 v[32:33], s[64:65]
	v_mov_b32_e32 v50, v89
	s_or_b64 exec, exec, s[0:1]
	v_ashrrev_i32_e32 v51, 31, v50
	v_lshlrev_b64 v[50:51], 12, v[50:51]
	v_lshl_add_u64 v[32:33], v[32:33], 0, v[50:51]
	v_lshl_add_u64 v[32:33], v[32:33], 0, v[176:177]
	v_mul_f32_e32 v34, v35, v49
	global_store_dword v[32:33], v34, off offset:128
	s_and_saveexec_b64 s[0:1], s[8:9]
	s_xor_b64 s[0:1], exec, s[0:1]
	s_mov_b64 s[2:3], s[92:93]
	s_or_saveexec_b64 s[0:1], s[0:1]
	s_waitcnt lgkmcnt(0)
	v_mov_b64_e32 v[32:33], s[2:3]
	s_xor_b64 exec, exec, s[0:1]
	v_mov_b64_e32 v[32:33], s[64:65]
	v_mov_b32_e32 v70, v71
	s_or_b64 exec, exec, s[0:1]
	v_ashrrev_i32_e32 v71, 31, v70
	v_lshlrev_b64 v[34:35], 12, v[70:71]
	v_lshl_add_u64 v[32:33], v[32:33], 0, v[34:35]
	v_lshl_add_u64 v[32:33], v[32:33], 0, v[176:177]
	v_mul_f32_e32 v34, v36, v49
	global_store_dword v[32:33], v34, off offset:128
	s_and_saveexec_b64 s[0:1], s[10:11]
	s_xor_b64 s[0:1], exec, s[0:1]
	s_mov_b64 s[2:3], s[92:93]
	s_or_saveexec_b64 s[0:1], s[0:1]
	s_waitcnt lgkmcnt(0)
	v_mov_b64_e32 v[32:33], s[2:3]
	s_xor_b64 exec, exec, s[0:1]
	v_mov_b64_e32 v[32:33], s[64:65]
	v_mov_b32_e32 v52, v90
	s_or_b64 exec, exec, s[0:1]
	v_ashrrev_i32_e32 v53, 31, v52
	v_lshlrev_b64 v[34:35], 12, v[52:53]
	v_lshl_add_u64 v[32:33], v[32:33], 0, v[34:35]
	v_lshl_add_u64 v[32:33], v[32:33], 0, v[176:177]
	v_mul_f32_e32 v34, v37, v49
	global_store_dword v[32:33], v34, off offset:128
	s_and_saveexec_b64 s[0:1], s[12:13]
	s_xor_b64 s[0:1], exec, s[0:1]
	s_mov_b64 s[2:3], s[92:93]
	s_or_saveexec_b64 s[0:1], s[0:1]
	s_waitcnt lgkmcnt(0)
	v_mov_b64_e32 v[32:33], s[2:3]
	s_xor_b64 exec, exec, s[0:1]
	v_mov_b64_e32 v[32:33], s[64:65]
	v_mov_b32_e32 v72, v73
	s_or_b64 exec, exec, s[0:1]
	v_ashrrev_i32_e32 v73, 31, v72
	v_lshlrev_b64 v[34:35], 12, v[72:73]
	v_lshl_add_u64 v[32:33], v[32:33], 0, v[34:35]
	v_lshl_add_u64 v[32:33], v[32:33], 0, v[176:177]
	v_mul_f32_e32 v34, v38, v49
	global_store_dword v[32:33], v34, off offset:128
	s_and_saveexec_b64 s[0:1], s[14:15]
	s_xor_b64 s[0:1], exec, s[0:1]
	s_mov_b64 s[2:3], s[92:93]
	s_or_saveexec_b64 s[0:1], s[0:1]
	s_waitcnt lgkmcnt(0)
	v_mov_b64_e32 v[32:33], s[2:3]
	s_xor_b64 exec, exec, s[0:1]
	v_mov_b64_e32 v[32:33], s[64:65]
	v_mov_b32_e32 v54, v91
	s_or_b64 exec, exec, s[0:1]
	v_ashrrev_i32_e32 v55, 31, v54
	v_lshlrev_b64 v[34:35], 12, v[54:55]
	v_lshl_add_u64 v[32:33], v[32:33], 0, v[34:35]
	v_lshl_add_u64 v[32:33], v[32:33], 0, v[176:177]
	v_mul_f32_e32 v34, v39, v49
	global_store_dword v[32:33], v34, off offset:128
	s_and_saveexec_b64 s[0:1], s[16:17]
	s_xor_b64 s[0:1], exec, s[0:1]
	s_mov_b64 s[2:3], s[92:93]
	s_or_saveexec_b64 s[0:1], s[0:1]
	s_waitcnt lgkmcnt(0)
	v_mov_b64_e32 v[32:33], s[2:3]
	s_xor_b64 exec, exec, s[0:1]
	v_mov_b64_e32 v[32:33], s[64:65]
	v_mov_b32_e32 v74, v75
	s_or_b64 exec, exec, s[0:1]
	v_ashrrev_i32_e32 v75, 31, v74
	v_lshlrev_b64 v[34:35], 12, v[74:75]
	v_lshl_add_u64 v[32:33], v[32:33], 0, v[34:35]
	v_lshl_add_u64 v[32:33], v[32:33], 0, v[176:177]
	v_mul_f32_e32 v34, v40, v49
	global_store_dword v[32:33], v34, off offset:128
	s_and_saveexec_b64 s[0:1], s[18:19]
	s_xor_b64 s[0:1], exec, s[0:1]
	s_mov_b64 s[2:3], s[92:93]
	s_or_saveexec_b64 s[0:1], s[0:1]
	s_waitcnt lgkmcnt(0)
	v_mov_b64_e32 v[32:33], s[2:3]
	s_xor_b64 exec, exec, s[0:1]
	v_mov_b64_e32 v[32:33], s[64:65]
	v_mov_b32_e32 v56, v92
	s_or_b64 exec, exec, s[0:1]
	v_ashrrev_i32_e32 v57, 31, v56
	v_lshlrev_b64 v[34:35], 12, v[56:57]
	v_lshl_add_u64 v[32:33], v[32:33], 0, v[34:35]
	v_lshl_add_u64 v[32:33], v[32:33], 0, v[176:177]
	v_mul_f32_e32 v34, v41, v49
	global_store_dword v[32:33], v34, off offset:128
	s_and_saveexec_b64 s[0:1], s[20:21]
	s_xor_b64 s[0:1], exec, s[0:1]
	s_mov_b64 s[2:3], s[92:93]
	s_or_saveexec_b64 s[0:1], s[0:1]
	s_waitcnt lgkmcnt(0)
	v_mov_b64_e32 v[32:33], s[2:3]
	s_xor_b64 exec, exec, s[0:1]
	v_mov_b64_e32 v[32:33], s[64:65]
	v_mov_b32_e32 v76, v77
	s_or_b64 exec, exec, s[0:1]
	v_ashrrev_i32_e32 v77, 31, v76
	v_lshlrev_b64 v[34:35], 12, v[76:77]
	v_lshl_add_u64 v[32:33], v[32:33], 0, v[34:35]
	v_lshl_add_u64 v[32:33], v[32:33], 0, v[176:177]
	v_mul_f32_e32 v34, v42, v49
	global_store_dword v[32:33], v34, off offset:128
	s_and_saveexec_b64 s[0:1], s[22:23]
	s_xor_b64 s[0:1], exec, s[0:1]
	s_mov_b64 s[2:3], s[92:93]
	s_or_saveexec_b64 s[0:1], s[0:1]
	s_waitcnt lgkmcnt(0)
	v_mov_b64_e32 v[32:33], s[2:3]
	s_xor_b64 exec, exec, s[0:1]
	v_mov_b64_e32 v[32:33], s[64:65]
	v_mov_b32_e32 v58, v93
	s_or_b64 exec, exec, s[0:1]
	v_ashrrev_i32_e32 v59, 31, v58
	v_lshlrev_b64 v[34:35], 12, v[58:59]
	v_lshl_add_u64 v[32:33], v[32:33], 0, v[34:35]
	v_lshl_add_u64 v[32:33], v[32:33], 0, v[176:177]
	v_mul_f32_e32 v34, v43, v49
	global_store_dword v[32:33], v34, off offset:128
	s_and_saveexec_b64 s[0:1], s[24:25]
	s_xor_b64 s[0:1], exec, s[0:1]
	s_mov_b64 s[2:3], s[92:93]
	s_or_saveexec_b64 s[0:1], s[0:1]
	s_waitcnt lgkmcnt(0)
	v_mov_b64_e32 v[32:33], s[2:3]
	s_xor_b64 exec, exec, s[0:1]
	v_mov_b64_e32 v[32:33], s[64:65]
	v_mov_b32_e32 v78, v79
	s_or_b64 exec, exec, s[0:1]
	v_ashrrev_i32_e32 v79, 31, v78
	v_lshlrev_b64 v[34:35], 12, v[78:79]
	v_lshl_add_u64 v[32:33], v[32:33], 0, v[34:35]
	v_lshl_add_u64 v[32:33], v[32:33], 0, v[176:177]
	v_mul_f32_e32 v34, v44, v49
	global_store_dword v[32:33], v34, off offset:128
	s_and_saveexec_b64 s[0:1], s[26:27]
	s_xor_b64 s[0:1], exec, s[0:1]
	s_mov_b64 s[2:3], s[92:93]
	s_or_saveexec_b64 s[0:1], s[0:1]
	s_waitcnt lgkmcnt(0)
	v_mov_b64_e32 v[32:33], s[2:3]
	s_xor_b64 exec, exec, s[0:1]
	v_mov_b64_e32 v[32:33], s[64:65]
	v_mov_b32_e32 v60, v94
	s_or_b64 exec, exec, s[0:1]
	v_ashrrev_i32_e32 v61, 31, v60
	v_lshlrev_b64 v[34:35], 12, v[60:61]
	v_lshl_add_u64 v[32:33], v[32:33], 0, v[34:35]
	v_lshl_add_u64 v[32:33], v[32:33], 0, v[176:177]
	v_mul_f32_e32 v34, v45, v49
	global_store_dword v[32:33], v34, off offset:128
	s_and_saveexec_b64 s[0:1], s[28:29]
	s_xor_b64 s[0:1], exec, s[0:1]
	s_mov_b64 s[2:3], s[92:93]
	s_or_saveexec_b64 s[0:1], s[0:1]
	s_waitcnt lgkmcnt(0)
	v_mov_b64_e32 v[32:33], s[2:3]
	s_xor_b64 exec, exec, s[0:1]
	v_mov_b64_e32 v[32:33], s[64:65]
	v_mov_b32_e32 v80, v81
	s_or_b64 exec, exec, s[0:1]
	v_ashrrev_i32_e32 v81, 31, v80
	v_lshlrev_b64 v[34:35], 12, v[80:81]
	v_lshl_add_u64 v[32:33], v[32:33], 0, v[34:35]
	v_lshl_add_u64 v[32:33], v[32:33], 0, v[176:177]
	v_mul_f32_e32 v34, v46, v49
	global_store_dword v[32:33], v34, off offset:128
	s_and_saveexec_b64 s[0:1], s[30:31]
	s_xor_b64 s[0:1], exec, s[0:1]
	s_mov_b64 s[2:3], s[92:93]
	s_or_saveexec_b64 s[0:1], s[0:1]
	s_waitcnt lgkmcnt(0)
	v_mov_b64_e32 v[32:33], s[2:3]
	s_xor_b64 exec, exec, s[0:1]
	v_mov_b64_e32 v[32:33], s[64:65]
	v_mov_b32_e32 v62, v95
	s_or_b64 exec, exec, s[0:1]
	v_ashrrev_i32_e32 v63, 31, v62
	v_lshlrev_b64 v[36:37], 12, v[62:63]
	v_lshl_add_u64 v[32:33], v[32:33], 0, v[36:37]
	v_lshl_add_u64 v[32:33], v[32:33], 0, v[176:177]
	v_mul_f32_e32 v36, v47, v49
	v_lshl_add_u64 v[34:35], s[62:63], 0, v[176:177]
	global_store_dword v[32:33], v36, off offset:128
	global_load_dword v54, v[34:35], off
	v_add3_u32 v32, v86, v87, 32
	v_mul_hi_i32 v33, v32, s35
	v_lshrrev_b32_e32 v34, 31, v33
	v_ashrrev_i32_e32 v33, 11, v33
	v_add_u32_e32 v35, v33, v34
	v_mad_i32_i24 v38, v35, s33, v32
	v_lshlrev_b32_e32 v33, 13, v35
	v_cmp_lt_i32_e32 vcc, s82, v38
	v_add3_u32 v32, v33, v38, s79
	s_and_saveexec_b64 s[0:1], vcc
	s_xor_b64 s[0:1], exec, s[0:1]
	s_mov_b64 s[2:3], s[92:93]
	v_add3_u32 v34, v33, v38, s79
	s_or_saveexec_b64 s[0:1], s[0:1]
	s_waitcnt lgkmcnt(0)
	v_mov_b64_e32 v[36:37], s[2:3]
	v_lshl_add_u32 v33, v35, 8, v38
	s_xor_b64 exec, exec, s[0:1]
	v_lshl_add_u32 v34, v35, 8, v38
	v_mov_b64_e32 v[36:37], s[64:65]
	s_or_b64 exec, exec, s[0:1]
	v_ashrrev_i32_e32 v35, 31, v34
	v_lshlrev_b64 v[34:35], 12, v[34:35]
	v_lshl_add_u64 v[34:35], v[36:37], 0, v[34:35]
	v_lshl_add_u64 v[34:35], v[34:35], 0, v[176:177]
	s_waitcnt vmcnt(0)
	v_mul_f32_e32 v16, v16, v54
	global_store_dword v[34:35], v16, off
	v_add3_u32 v16, v86, v87, 33
	v_mul_hi_i32 v34, v16, s35
	v_lshrrev_b32_e32 v35, 31, v34
	v_ashrrev_i32_e32 v34, 11, v34
	v_add_u32_e32 v35, v34, v35
	v_mad_i32_i24 v38, v35, s33, v16
	v_lshlrev_b32_e32 v36, 13, v35
	v_cmp_lt_i32_e64 s[2:3], s82, v38
	v_add3_u32 v16, v36, v38, s79
	s_and_saveexec_b64 s[0:1], s[2:3]
	s_xor_b64 s[0:1], exec, s[0:1]
	s_mov_b64 s[4:5], s[92:93]
	v_add3_u32 v34, v36, v38, s79
	s_or_saveexec_b64 s[0:1], s[0:1]
	s_waitcnt lgkmcnt(0)
	v_mov_b64_e32 v[36:37], s[4:5]
	v_lshl_add_u32 v55, v35, 8, v38
	s_xor_b64 exec, exec, s[0:1]
	v_lshl_add_u32 v34, v35, 8, v38
	v_mov_b64_e32 v[36:37], s[64:65]
	s_or_b64 exec, exec, s[0:1]
	v_ashrrev_i32_e32 v35, 31, v34
	v_lshlrev_b64 v[34:35], 12, v[34:35]
	v_lshl_add_u64 v[34:35], v[36:37], 0, v[34:35]
	v_lshl_add_u64 v[34:35], v[34:35], 0, v[176:177]
	v_mul_f32_e32 v17, v17, v54
	global_store_dword v[34:35], v17, off
	v_add3_u32 v34, v86, v87, 34
	v_mul_hi_i32 v17, v34, s35
	v_lshrrev_b32_e32 v35, 31, v17
	v_ashrrev_i32_e32 v17, 11, v17
	v_add_u32_e32 v17, v17, v35
	v_mad_i32_i24 v37, v17, s33, v34
	v_lshlrev_b32_e32 v35, 13, v17
	v_cmp_lt_i32_e64 s[4:5], s82, v37
	v_add3_u32 v34, v35, v37, s79
	s_and_saveexec_b64 s[0:1], s[4:5]
	s_xor_b64 s[0:1], exec, s[0:1]
	s_mov_b64 s[6:7], s[92:93]
	v_add3_u32 v36, v35, v37, s79
	s_or_saveexec_b64 s[0:1], s[0:1]
	s_waitcnt lgkmcnt(0)
	v_mov_b64_e32 v[38:39], s[6:7]
	v_lshl_add_u32 v35, v17, 8, v37
	s_xor_b64 exec, exec, s[0:1]
	v_lshl_add_u32 v36, v17, 8, v37
	v_mov_b64_e32 v[38:39], s[64:65]
	s_or_b64 exec, exec, s[0:1]
	v_ashrrev_i32_e32 v37, 31, v36
	v_lshlrev_b64 v[36:37], 12, v[36:37]
	v_lshl_add_u64 v[36:37], v[38:39], 0, v[36:37]
	v_lshl_add_u64 v[36:37], v[36:37], 0, v[176:177]
	v_mul_f32_e32 v17, v18, v54
	global_store_dword v[36:37], v17, off
	v_add3_u32 v18, v86, v87, 35
	v_mul_hi_i32 v17, v18, s35
	v_lshrrev_b32_e32 v36, 31, v17
	v_ashrrev_i32_e32 v17, 11, v17
	v_add_u32_e32 v17, v17, v36
	v_mad_i32_i24 v37, v17, s33, v18
	v_lshlrev_b32_e32 v38, 13, v17
	v_cmp_lt_i32_e64 s[6:7], s82, v37
	v_add3_u32 v18, v38, v37, s79
	s_and_saveexec_b64 s[0:1], s[6:7]
	s_xor_b64 s[0:1], exec, s[0:1]
	s_mov_b64 s[8:9], s[92:93]
	v_add3_u32 v36, v38, v37, s79
	s_or_saveexec_b64 s[0:1], s[0:1]
	s_waitcnt lgkmcnt(0)
	v_mov_b64_e32 v[38:39], s[8:9]
	v_lshl_add_u32 v56, v17, 8, v37
	s_xor_b64 exec, exec, s[0:1]
	v_lshl_add_u32 v36, v17, 8, v37
	v_mov_b64_e32 v[38:39], s[64:65]
	s_or_b64 exec, exec, s[0:1]
	v_ashrrev_i32_e32 v37, 31, v36
	v_lshlrev_b64 v[36:37], 12, v[36:37]
	v_lshl_add_u64 v[36:37], v[38:39], 0, v[36:37]
	v_lshl_add_u64 v[36:37], v[36:37], 0, v[176:177]
	v_mul_f32_e32 v17, v19, v54
	global_store_dword v[36:37], v17, off
	v_add3_u32 v19, v86, v87, 40
	v_mul_hi_i32 v17, v19, s35
	v_lshrrev_b32_e32 v36, 31, v17
	v_ashrrev_i32_e32 v17, 11, v17
	v_add_u32_e32 v17, v17, v36
	v_mad_i32_i24 v19, v17, s33, v19
	v_lshlrev_b32_e32 v37, 13, v17
	v_cmp_lt_i32_e64 s[8:9], s82, v19
	v_add3_u32 v36, v37, v19, s79
	s_and_saveexec_b64 s[0:1], s[8:9]
	s_xor_b64 s[0:1], exec, s[0:1]
	s_mov_b64 s[10:11], s[92:93]
	v_add3_u32 v38, v37, v19, s79
	s_or_saveexec_b64 s[0:1], s[0:1]
	s_waitcnt lgkmcnt(0)
	v_mov_b64_e32 v[40:41], s[10:11]
	v_lshl_add_u32 v37, v17, 8, v19
	s_xor_b64 exec, exec, s[0:1]
	v_lshl_add_u32 v38, v17, 8, v19
	v_mov_b64_e32 v[40:41], s[64:65]
	s_or_b64 exec, exec, s[0:1]
	v_ashrrev_i32_e32 v39, 31, v38
	v_lshlrev_b64 v[38:39], 12, v[38:39]
	v_lshl_add_u64 v[38:39], v[40:41], 0, v[38:39]
	v_lshl_add_u64 v[38:39], v[38:39], 0, v[176:177]
	v_mul_f32_e32 v17, v20, v54
	global_store_dword v[38:39], v17, off
	v_add3_u32 v19, v86, v87, 41
	v_mul_hi_i32 v17, v19, s35
	v_lshrrev_b32_e32 v20, 31, v17
	v_ashrrev_i32_e32 v17, 11, v17
	v_add_u32_e32 v17, v17, v20
	v_mad_i32_i24 v19, v17, s33, v19
	v_lshlrev_b32_e32 v39, 13, v17
	v_cmp_lt_i32_e64 s[10:11], s82, v19
	v_add3_u32 v20, v39, v19, s79
	s_and_saveexec_b64 s[0:1], s[10:11]
	s_xor_b64 s[0:1], exec, s[0:1]
	s_mov_b64 s[12:13], s[92:93]
	v_add3_u32 v38, v39, v19, s79
	s_or_saveexec_b64 s[0:1], s[0:1]
	s_waitcnt lgkmcnt(0)
	v_mov_b64_e32 v[40:41], s[12:13]
	v_lshl_add_u32 v57, v17, 8, v19
	s_xor_b64 exec, exec, s[0:1]
	v_lshl_add_u32 v38, v17, 8, v19
	v_mov_b64_e32 v[40:41], s[64:65]
	s_or_b64 exec, exec, s[0:1]
	v_ashrrev_i32_e32 v39, 31, v38
	v_lshlrev_b64 v[38:39], 12, v[38:39]
	v_lshl_add_u64 v[38:39], v[40:41], 0, v[38:39]
	v_lshl_add_u64 v[38:39], v[38:39], 0, v[176:177]
	v_mul_f32_e32 v17, v21, v54
	global_store_dword v[38:39], v17, off
	v_add3_u32 v19, v86, v87, 42
	v_mul_hi_i32 v17, v19, s35
	v_lshrrev_b32_e32 v21, 31, v17
	v_ashrrev_i32_e32 v17, 11, v17
	v_add_u32_e32 v17, v17, v21
	v_mad_i32_i24 v19, v17, s33, v19
	v_lshlrev_b32_e32 v21, 13, v17
	v_cmp_lt_i32_e64 s[12:13], s82, v19
	v_add3_u32 v38, v21, v19, s79
	s_and_saveexec_b64 s[0:1], s[12:13]
	s_xor_b64 s[0:1], exec, s[0:1]
	s_mov_b64 s[14:15], s[92:93]
	v_add3_u32 v40, v21, v19, s79
	s_or_saveexec_b64 s[0:1], s[0:1]
	s_waitcnt lgkmcnt(0)
	v_mov_b64_e32 v[42:43], s[14:15]
	v_lshl_add_u32 v39, v17, 8, v19
	s_xor_b64 exec, exec, s[0:1]
	v_lshl_add_u32 v40, v17, 8, v19
	v_mov_b64_e32 v[42:43], s[64:65]
	s_or_b64 exec, exec, s[0:1]
	v_ashrrev_i32_e32 v41, 31, v40
	v_lshlrev_b64 v[40:41], 12, v[40:41]
	v_lshl_add_u64 v[40:41], v[42:43], 0, v[40:41]
	v_lshl_add_u64 v[40:41], v[40:41], 0, v[176:177]
	v_mul_f32_e32 v17, v22, v54
	global_store_dword v[40:41], v17, off
	v_add3_u32 v19, v86, v87, 43
	v_mul_hi_i32 v17, v19, s35
	v_lshrrev_b32_e32 v21, 31, v17
	v_ashrrev_i32_e32 v17, 11, v17
	v_add_u32_e32 v17, v17, v21
	v_mad_i32_i24 v19, v17, s33, v19
	v_lshlrev_b32_e32 v21, 13, v17
	v_cmp_lt_i32_e64 s[14:15], s82, v19
	v_add3_u32 v22, v21, v19, s79
	s_and_saveexec_b64 s[0:1], s[14:15]
	s_xor_b64 s[0:1], exec, s[0:1]
	s_mov_b64 s[16:17], s[92:93]
	v_add3_u32 v40, v21, v19, s79
	s_or_saveexec_b64 s[0:1], s[0:1]
	s_waitcnt lgkmcnt(0)
	v_mov_b64_e32 v[42:43], s[16:17]
	v_lshl_add_u32 v58, v17, 8, v19
	s_xor_b64 exec, exec, s[0:1]
	v_lshl_add_u32 v40, v17, 8, v19
	v_mov_b64_e32 v[42:43], s[64:65]
	s_or_b64 exec, exec, s[0:1]
	v_ashrrev_i32_e32 v41, 31, v40
	v_lshlrev_b64 v[40:41], 12, v[40:41]
	v_lshl_add_u64 v[40:41], v[42:43], 0, v[40:41]
	v_lshl_add_u64 v[40:41], v[40:41], 0, v[176:177]
	v_mul_f32_e32 v17, v23, v54
	global_store_dword v[40:41], v17, off
	v_add3_u32 v19, v86, v87, 48
	v_mul_hi_i32 v17, v19, s35
	v_lshrrev_b32_e32 v21, 31, v17
	v_ashrrev_i32_e32 v17, 11, v17
	v_add_u32_e32 v17, v17, v21
	v_mad_i32_i24 v19, v17, s33, v19
	v_lshlrev_b32_e32 v21, 13, v17
	v_cmp_lt_i32_e64 s[16:17], s82, v19
	v_add3_u32 v40, v21, v19, s79
	s_and_saveexec_b64 s[0:1], s[16:17]
	s_xor_b64 s[0:1], exec, s[0:1]
	s_mov_b64 s[18:19], s[92:93]
	v_add3_u32 v42, v21, v19, s79
	s_or_saveexec_b64 s[0:1], s[0:1]
	s_waitcnt lgkmcnt(0)
	v_mov_b64_e32 v[44:45], s[18:19]
	v_lshl_add_u32 v41, v17, 8, v19
	s_xor_b64 exec, exec, s[0:1]
	v_lshl_add_u32 v42, v17, 8, v19
	v_mov_b64_e32 v[44:45], s[64:65]
	s_or_b64 exec, exec, s[0:1]
	v_ashrrev_i32_e32 v43, 31, v42
	v_lshlrev_b64 v[42:43], 12, v[42:43]
	v_lshl_add_u64 v[42:43], v[44:45], 0, v[42:43]
	v_lshl_add_u64 v[42:43], v[42:43], 0, v[176:177]
	v_mul_f32_e32 v17, v24, v54
	global_store_dword v[42:43], v17, off
	v_add3_u32 v19, v86, v87, 49
	v_mul_hi_i32 v17, v19, s35
	v_lshrrev_b32_e32 v21, 31, v17
	v_ashrrev_i32_e32 v17, 11, v17
	v_add_u32_e32 v17, v17, v21
	v_mad_i32_i24 v19, v17, s33, v19
	v_lshlrev_b32_e32 v21, 13, v17
	v_cmp_lt_i32_e64 s[18:19], s82, v19
	v_add3_u32 v24, v21, v19, s79
	s_and_saveexec_b64 s[0:1], s[18:19]
	s_xor_b64 s[0:1], exec, s[0:1]
	s_mov_b64 s[20:21], s[92:93]
	v_add3_u32 v42, v21, v19, s79
	s_or_saveexec_b64 s[0:1], s[0:1]
	s_waitcnt lgkmcnt(0)
	v_mov_b64_e32 v[44:45], s[20:21]
	v_lshl_add_u32 v59, v17, 8, v19
	s_xor_b64 exec, exec, s[0:1]
	v_lshl_add_u32 v42, v17, 8, v19
	v_mov_b64_e32 v[44:45], s[64:65]
	s_or_b64 exec, exec, s[0:1]
	v_ashrrev_i32_e32 v43, 31, v42
	v_lshlrev_b64 v[42:43], 12, v[42:43]
	v_lshl_add_u64 v[42:43], v[44:45], 0, v[42:43]
	v_lshl_add_u64 v[42:43], v[42:43], 0, v[176:177]
	v_mul_f32_e32 v17, v25, v54
	global_store_dword v[42:43], v17, off
	v_add3_u32 v19, v86, v87, 50
	v_mul_hi_i32 v17, v19, s35
	v_lshrrev_b32_e32 v21, 31, v17
	v_ashrrev_i32_e32 v17, 11, v17
	v_add_u32_e32 v17, v17, v21
	v_mad_i32_i24 v19, v17, s33, v19
	v_lshlrev_b32_e32 v21, 13, v17
	v_cmp_lt_i32_e64 s[20:21], s82, v19
	v_add3_u32 v42, v21, v19, s79
	s_and_saveexec_b64 s[0:1], s[20:21]
	s_xor_b64 s[0:1], exec, s[0:1]
	s_mov_b64 s[22:23], s[92:93]
	v_add3_u32 v44, v21, v19, s79
	s_or_saveexec_b64 s[0:1], s[0:1]
	s_waitcnt lgkmcnt(0)
	v_mov_b64_e32 v[46:47], s[22:23]
	v_lshl_add_u32 v43, v17, 8, v19
	s_xor_b64 exec, exec, s[0:1]
	v_lshl_add_u32 v44, v17, 8, v19
	v_mov_b64_e32 v[46:47], s[64:65]
	s_or_b64 exec, exec, s[0:1]
	v_ashrrev_i32_e32 v45, 31, v44
	v_lshlrev_b64 v[44:45], 12, v[44:45]
	v_lshl_add_u64 v[44:45], v[46:47], 0, v[44:45]
	v_lshl_add_u64 v[44:45], v[44:45], 0, v[176:177]
	v_mul_f32_e32 v17, v26, v54
	global_store_dword v[44:45], v17, off
	v_add3_u32 v19, v86, v87, 51
	v_mul_hi_i32 v17, v19, s35
	v_lshrrev_b32_e32 v21, 31, v17
	v_ashrrev_i32_e32 v17, 11, v17
	v_add_u32_e32 v17, v17, v21
	v_mad_i32_i24 v19, v17, s33, v19
	v_lshlrev_b32_e32 v21, 13, v17
	v_cmp_lt_i32_e64 s[22:23], s82, v19
	v_add3_u32 v26, v21, v19, s79
	s_and_saveexec_b64 s[0:1], s[22:23]
	s_xor_b64 s[0:1], exec, s[0:1]
	s_mov_b64 s[24:25], s[92:93]
	v_add3_u32 v44, v21, v19, s79
	s_or_saveexec_b64 s[0:1], s[0:1]
	s_waitcnt lgkmcnt(0)
	v_mov_b64_e32 v[46:47], s[24:25]
	v_lshl_add_u32 v60, v17, 8, v19
	s_xor_b64 exec, exec, s[0:1]
	v_lshl_add_u32 v44, v17, 8, v19
	v_mov_b64_e32 v[46:47], s[64:65]
	s_or_b64 exec, exec, s[0:1]
	v_ashrrev_i32_e32 v45, 31, v44
	v_lshlrev_b64 v[44:45], 12, v[44:45]
	v_lshl_add_u64 v[44:45], v[46:47], 0, v[44:45]
	v_lshl_add_u64 v[44:45], v[44:45], 0, v[176:177]
	v_mul_f32_e32 v17, v27, v54
	global_store_dword v[44:45], v17, off
	v_add3_u32 v19, v86, v87, 56
	v_mul_hi_i32 v17, v19, s35
	v_lshrrev_b32_e32 v21, 31, v17
	v_ashrrev_i32_e32 v17, 11, v17
	v_add_u32_e32 v17, v17, v21
	v_mad_i32_i24 v19, v17, s33, v19
	v_lshlrev_b32_e32 v21, 13, v17
	v_cmp_lt_i32_e64 s[24:25], s82, v19
	v_add3_u32 v44, v21, v19, s79
	s_and_saveexec_b64 s[0:1], s[24:25]
	s_xor_b64 s[0:1], exec, s[0:1]
	s_mov_b64 s[26:27], s[92:93]
	v_add3_u32 v46, v21, v19, s79
	s_or_saveexec_b64 s[0:1], s[0:1]
	s_waitcnt lgkmcnt(0)
	v_mov_b64_e32 v[50:51], s[26:27]
	v_lshl_add_u32 v45, v17, 8, v19
	s_xor_b64 exec, exec, s[0:1]
	v_lshl_add_u32 v46, v17, 8, v19
	v_mov_b64_e32 v[50:51], s[64:65]
	s_or_b64 exec, exec, s[0:1]
	v_ashrrev_i32_e32 v47, 31, v46
	v_lshlrev_b64 v[46:47], 12, v[46:47]
	v_lshl_add_u64 v[46:47], v[50:51], 0, v[46:47]
	v_lshl_add_u64 v[46:47], v[46:47], 0, v[176:177]
	v_mul_f32_e32 v17, v28, v54
	global_store_dword v[46:47], v17, off
	v_add3_u32 v19, v86, v87, 57
	v_mul_hi_i32 v17, v19, s35
	v_lshrrev_b32_e32 v21, 31, v17
	v_ashrrev_i32_e32 v17, 11, v17
	v_add_u32_e32 v17, v17, v21
	v_mad_i32_i24 v19, v17, s33, v19
	v_lshlrev_b32_e32 v21, 13, v17
	v_cmp_lt_i32_e64 s[26:27], s82, v19
	v_add3_u32 v28, v21, v19, s79
	s_and_saveexec_b64 s[0:1], s[26:27]
	s_xor_b64 s[0:1], exec, s[0:1]
	s_mov_b64 s[28:29], s[92:93]
	v_add3_u32 v46, v21, v19, s79
	s_or_saveexec_b64 s[0:1], s[0:1]
	s_waitcnt lgkmcnt(0)
	v_mov_b64_e32 v[50:51], s[28:29]
	v_lshl_add_u32 v61, v17, 8, v19
	s_xor_b64 exec, exec, s[0:1]
	v_lshl_add_u32 v46, v17, 8, v19
	v_mov_b64_e32 v[50:51], s[64:65]
	s_or_b64 exec, exec, s[0:1]
	v_ashrrev_i32_e32 v47, 31, v46
	v_lshlrev_b64 v[46:47], 12, v[46:47]
	v_lshl_add_u64 v[46:47], v[50:51], 0, v[46:47]
	v_lshl_add_u64 v[46:47], v[46:47], 0, v[176:177]
	v_mul_f32_e32 v17, v29, v54
	global_store_dword v[46:47], v17, off
	v_add3_u32 v19, v86, v87, 58
	v_mul_hi_i32 v17, v19, s35
	v_lshrrev_b32_e32 v21, 31, v17
	v_ashrrev_i32_e32 v17, 11, v17
	v_add_u32_e32 v17, v17, v21
	v_mad_i32_i24 v19, v17, s33, v19
	v_lshlrev_b32_e32 v21, 13, v17
	v_cmp_lt_i32_e64 s[28:29], s82, v19
	v_add3_u32 v46, v21, v19, s79
	s_and_saveexec_b64 s[0:1], s[28:29]
	s_xor_b64 s[0:1], exec, s[0:1]
	s_mov_b64 s[30:31], s[92:93]
	v_add3_u32 v50, v21, v19, s79
	s_or_saveexec_b64 s[0:1], s[0:1]
	s_waitcnt lgkmcnt(0)
	v_mov_b64_e32 v[52:53], s[30:31]
	v_lshl_add_u32 v47, v17, 8, v19
	s_xor_b64 exec, exec, s[0:1]
	v_lshl_add_u32 v50, v17, 8, v19
	v_mov_b64_e32 v[52:53], s[64:65]
	s_or_b64 exec, exec, s[0:1]
	v_ashrrev_i32_e32 v51, 31, v50
	v_lshlrev_b64 v[50:51], 12, v[50:51]
	v_lshl_add_u64 v[50:51], v[52:53], 0, v[50:51]
	v_lshl_add_u64 v[50:51], v[50:51], 0, v[176:177]
	v_mul_f32_e32 v17, v30, v54
	global_store_dword v[50:51], v17, off
	v_add3_u32 v19, v86, v87, 59
	v_mul_hi_i32 v17, v19, s35
	v_lshrrev_b32_e32 v21, 31, v17
	v_ashrrev_i32_e32 v17, 11, v17
	v_add_u32_e32 v17, v17, v21
	v_mad_i32_i24 v19, v17, s33, v19
	v_lshlrev_b32_e32 v21, 13, v17
	v_cmp_lt_i32_e64 s[30:31], s82, v19
	v_add3_u32 v30, v21, v19, s79
	s_and_saveexec_b64 s[0:1], s[30:31]
	s_xor_b64 s[0:1], exec, s[0:1]
	s_mov_b64 s[74:75], s[92:93]
	v_add3_u32 v50, v21, v19, s79
	s_or_saveexec_b64 s[0:1], s[0:1]
	s_waitcnt lgkmcnt(0)
	v_mov_b64_e32 v[52:53], s[74:75]
	v_lshl_add_u32 v62, v17, 8, v19
	s_xor_b64 exec, exec, s[0:1]
	v_lshl_add_u32 v50, v17, 8, v19
	v_mov_b64_e32 v[52:53], s[64:65]
	s_or_b64 exec, exec, s[0:1]
	v_ashrrev_i32_e32 v51, 31, v50
	v_lshlrev_b64 v[50:51], 12, v[50:51]
	v_lshl_add_u64 v[50:51], v[52:53], 0, v[50:51]
	v_mov_b32_e32 v49, v177
	v_lshl_add_u64 v[50:51], v[50:51], 0, v[176:177]
	v_mul_f32_e32 v17, v31, v54
	v_lshl_add_u64 v[48:49], s[62:63], 0, v[48:49]
	global_store_dword v[50:51], v17, off
	global_load_dword v50, v[48:49], off
	s_and_saveexec_b64 s[0:1], vcc
	s_xor_b64 s[0:1], exec, s[0:1]
	s_mov_b64 s[74:75], s[92:93]
	s_or_saveexec_b64 s[0:1], s[0:1]
	s_waitcnt lgkmcnt(0)
	v_mov_b64_e32 v[48:49], s[74:75]
	s_xor_b64 exec, exec, s[0:1]
	v_mov_b64_e32 v[48:49], s[64:65]
	v_mov_b32_e32 v32, v33
	s_or_b64 exec, exec, s[0:1]
	v_ashrrev_i32_e32 v33, 31, v32
	v_lshlrev_b64 v[32:33], 12, v[32:33]
	v_lshl_add_u64 v[32:33], v[48:49], 0, v[32:33]
	v_lshl_add_u64 v[32:33], v[32:33], 0, v[176:177]
	s_waitcnt vmcnt(0)
	v_mul_f32_e32 v0, v0, v50
	global_store_dword v[32:33], v0, off offset:128
	s_and_saveexec_b64 s[0:1], s[2:3]
	s_xor_b64 s[0:1], exec, s[0:1]
	s_mov_b64 s[74:75], s[92:93]
	s_or_saveexec_b64 s[0:1], s[0:1]
	s_waitcnt lgkmcnt(0)
	v_mov_b64_e32 v[32:33], s[74:75]
	s_xor_b64 exec, exec, s[0:1]
	v_mov_b64_e32 v[32:33], s[64:65]
	v_mov_b32_e32 v16, v55
	s_or_b64 exec, exec, s[0:1]
	v_ashrrev_i32_e32 v17, 31, v16
	v_lshlrev_b64 v[16:17], 12, v[16:17]
	v_lshl_add_u64 v[16:17], v[32:33], 0, v[16:17]
	v_lshl_add_u64 v[16:17], v[16:17], 0, v[176:177]
	v_mul_f32_e32 v0, v1, v50
	global_store_dword v[16:17], v0, off offset:128
	s_and_saveexec_b64 s[0:1], s[4:5]
	s_xor_b64 s[0:1], exec, s[0:1]
	s_mov_b64 s[2:3], s[92:93]
	s_or_saveexec_b64 s[0:1], s[0:1]
	s_waitcnt lgkmcnt(0)
	v_mov_b64_e32 v[0:1], s[2:3]
	s_xor_b64 exec, exec, s[0:1]
	v_mov_b64_e32 v[0:1], s[64:65]
	v_mov_b32_e32 v34, v35
	s_or_b64 exec, exec, s[0:1]
	v_ashrrev_i32_e32 v35, 31, v34
	v_lshlrev_b64 v[16:17], 12, v[34:35]
	v_lshl_add_u64 v[0:1], v[0:1], 0, v[16:17]
	v_lshl_add_u64 v[0:1], v[0:1], 0, v[176:177]
	v_mul_f32_e32 v2, v2, v50
	global_store_dword v[0:1], v2, off offset:128
	s_and_saveexec_b64 s[0:1], s[6:7]
	s_xor_b64 s[0:1], exec, s[0:1]
	s_mov_b64 s[2:3], s[92:93]
	s_or_saveexec_b64 s[0:1], s[0:1]
	s_waitcnt lgkmcnt(0)
	v_mov_b64_e32 v[0:1], s[2:3]
	s_xor_b64 exec, exec, s[0:1]
	v_mov_b64_e32 v[0:1], s[64:65]
	v_mov_b32_e32 v18, v56
	s_or_b64 exec, exec, s[0:1]
	v_ashrrev_i32_e32 v19, 31, v18
	v_lshlrev_b64 v[16:17], 12, v[18:19]
	v_lshl_add_u64 v[0:1], v[0:1], 0, v[16:17]
	v_lshl_add_u64 v[0:1], v[0:1], 0, v[176:177]
	v_mul_f32_e32 v2, v3, v50
	global_store_dword v[0:1], v2, off offset:128
	s_and_saveexec_b64 s[0:1], s[8:9]
	s_xor_b64 s[0:1], exec, s[0:1]
	s_mov_b64 s[2:3], s[92:93]
	s_or_saveexec_b64 s[0:1], s[0:1]
	s_waitcnt lgkmcnt(0)
	v_mov_b64_e32 v[0:1], s[2:3]
	s_xor_b64 exec, exec, s[0:1]
	v_mov_b64_e32 v[0:1], s[64:65]
	v_mov_b32_e32 v36, v37
	s_or_b64 exec, exec, s[0:1]
	v_ashrrev_i32_e32 v37, 31, v36
	v_lshlrev_b64 v[2:3], 12, v[36:37]
	v_lshl_add_u64 v[0:1], v[0:1], 0, v[2:3]
	v_lshl_add_u64 v[0:1], v[0:1], 0, v[176:177]
	v_mul_f32_e32 v2, v4, v50
	global_store_dword v[0:1], v2, off offset:128
	s_and_saveexec_b64 s[0:1], s[10:11]
	s_xor_b64 s[0:1], exec, s[0:1]
	s_mov_b64 s[2:3], s[92:93]
	s_or_saveexec_b64 s[0:1], s[0:1]
	s_waitcnt lgkmcnt(0)
	v_mov_b64_e32 v[0:1], s[2:3]
	s_xor_b64 exec, exec, s[0:1]
	v_mov_b64_e32 v[0:1], s[64:65]
	v_mov_b32_e32 v20, v57
	s_or_b64 exec, exec, s[0:1]
	v_ashrrev_i32_e32 v21, 31, v20
	v_lshlrev_b64 v[2:3], 12, v[20:21]
	v_lshl_add_u64 v[0:1], v[0:1], 0, v[2:3]
	v_lshl_add_u64 v[0:1], v[0:1], 0, v[176:177]
	v_mul_f32_e32 v2, v5, v50
	global_store_dword v[0:1], v2, off offset:128
	s_and_saveexec_b64 s[0:1], s[12:13]
	s_xor_b64 s[0:1], exec, s[0:1]
	s_mov_b64 s[2:3], s[92:93]
	s_or_saveexec_b64 s[0:1], s[0:1]
	s_waitcnt lgkmcnt(0)
	v_mov_b64_e32 v[0:1], s[2:3]
	s_xor_b64 exec, exec, s[0:1]
	v_mov_b64_e32 v[0:1], s[64:65]
	v_mov_b32_e32 v38, v39
	s_or_b64 exec, exec, s[0:1]
	v_ashrrev_i32_e32 v39, 31, v38
	v_lshlrev_b64 v[2:3], 12, v[38:39]
	v_lshl_add_u64 v[0:1], v[0:1], 0, v[2:3]
	v_lshl_add_u64 v[0:1], v[0:1], 0, v[176:177]
	v_mul_f32_e32 v2, v6, v50
	global_store_dword v[0:1], v2, off offset:128
	s_and_saveexec_b64 s[0:1], s[14:15]
	s_xor_b64 s[0:1], exec, s[0:1]
	s_mov_b64 s[2:3], s[92:93]
	s_or_saveexec_b64 s[0:1], s[0:1]
	s_waitcnt lgkmcnt(0)
	v_mov_b64_e32 v[0:1], s[2:3]
	s_xor_b64 exec, exec, s[0:1]
	v_mov_b64_e32 v[0:1], s[64:65]
	v_mov_b32_e32 v22, v58
	s_or_b64 exec, exec, s[0:1]
	v_ashrrev_i32_e32 v23, 31, v22
	v_lshlrev_b64 v[2:3], 12, v[22:23]
	v_lshl_add_u64 v[0:1], v[0:1], 0, v[2:3]
	v_lshl_add_u64 v[0:1], v[0:1], 0, v[176:177]
	v_mul_f32_e32 v2, v7, v50
	global_store_dword v[0:1], v2, off offset:128
	s_and_saveexec_b64 s[0:1], s[16:17]
	s_xor_b64 s[0:1], exec, s[0:1]
	s_mov_b64 s[2:3], s[92:93]
	s_or_saveexec_b64 s[0:1], s[0:1]
	s_waitcnt lgkmcnt(0)
	v_mov_b64_e32 v[0:1], s[2:3]
	s_xor_b64 exec, exec, s[0:1]
	v_mov_b64_e32 v[0:1], s[64:65]
	v_mov_b32_e32 v40, v41
	s_or_b64 exec, exec, s[0:1]
	v_ashrrev_i32_e32 v41, 31, v40
	v_lshlrev_b64 v[2:3], 12, v[40:41]
	v_lshl_add_u64 v[0:1], v[0:1], 0, v[2:3]
	v_lshl_add_u64 v[0:1], v[0:1], 0, v[176:177]
	v_mul_f32_e32 v2, v8, v50
	global_store_dword v[0:1], v2, off offset:128
	s_and_saveexec_b64 s[0:1], s[18:19]
	s_xor_b64 s[0:1], exec, s[0:1]
	s_mov_b64 s[2:3], s[92:93]
	s_or_saveexec_b64 s[0:1], s[0:1]
	s_waitcnt lgkmcnt(0)
	v_mov_b64_e32 v[0:1], s[2:3]
	s_xor_b64 exec, exec, s[0:1]
	v_mov_b64_e32 v[0:1], s[64:65]
	v_mov_b32_e32 v24, v59
	s_or_b64 exec, exec, s[0:1]
	v_ashrrev_i32_e32 v25, 31, v24
	v_lshlrev_b64 v[2:3], 12, v[24:25]
	v_lshl_add_u64 v[0:1], v[0:1], 0, v[2:3]
	v_lshl_add_u64 v[0:1], v[0:1], 0, v[176:177]
	v_mul_f32_e32 v2, v9, v50
	global_store_dword v[0:1], v2, off offset:128
	s_and_saveexec_b64 s[0:1], s[20:21]
	s_xor_b64 s[0:1], exec, s[0:1]
	s_mov_b64 s[2:3], s[92:93]
	s_or_saveexec_b64 s[0:1], s[0:1]
	s_waitcnt lgkmcnt(0)
	v_mov_b64_e32 v[0:1], s[2:3]
	s_xor_b64 exec, exec, s[0:1]
	v_mov_b64_e32 v[0:1], s[64:65]
	v_mov_b32_e32 v42, v43
	s_or_b64 exec, exec, s[0:1]
	v_ashrrev_i32_e32 v43, 31, v42
	v_lshlrev_b64 v[2:3], 12, v[42:43]
	v_lshl_add_u64 v[0:1], v[0:1], 0, v[2:3]
	v_lshl_add_u64 v[0:1], v[0:1], 0, v[176:177]
	v_mul_f32_e32 v2, v10, v50
	global_store_dword v[0:1], v2, off offset:128
	s_and_saveexec_b64 s[0:1], s[22:23]
	s_xor_b64 s[0:1], exec, s[0:1]
	s_mov_b64 s[2:3], s[92:93]
	s_or_saveexec_b64 s[0:1], s[0:1]
	s_waitcnt lgkmcnt(0)
	v_mov_b64_e32 v[0:1], s[2:3]
	s_xor_b64 exec, exec, s[0:1]
	v_mov_b64_e32 v[0:1], s[64:65]
	v_mov_b32_e32 v26, v60
	s_or_b64 exec, exec, s[0:1]
	v_ashrrev_i32_e32 v27, 31, v26
	v_lshlrev_b64 v[2:3], 12, v[26:27]
	v_lshl_add_u64 v[0:1], v[0:1], 0, v[2:3]
	v_lshl_add_u64 v[0:1], v[0:1], 0, v[176:177]
	v_mul_f32_e32 v2, v11, v50
	global_store_dword v[0:1], v2, off offset:128
	s_and_saveexec_b64 s[0:1], s[24:25]
	s_xor_b64 s[0:1], exec, s[0:1]
	s_mov_b64 s[2:3], s[92:93]
	s_or_saveexec_b64 s[0:1], s[0:1]
	s_waitcnt lgkmcnt(0)
	v_mov_b64_e32 v[0:1], s[2:3]
	s_xor_b64 exec, exec, s[0:1]
	v_mov_b64_e32 v[0:1], s[64:65]
	v_mov_b32_e32 v44, v45
	s_or_b64 exec, exec, s[0:1]
	v_ashrrev_i32_e32 v45, 31, v44
	v_lshlrev_b64 v[2:3], 12, v[44:45]
	v_lshl_add_u64 v[0:1], v[0:1], 0, v[2:3]
	v_lshl_add_u64 v[0:1], v[0:1], 0, v[176:177]
	v_mul_f32_e32 v2, v12, v50
	global_store_dword v[0:1], v2, off offset:128
	s_and_saveexec_b64 s[0:1], s[26:27]
	s_xor_b64 s[0:1], exec, s[0:1]
	s_mov_b64 s[2:3], s[92:93]
	s_or_saveexec_b64 s[0:1], s[0:1]
	s_waitcnt lgkmcnt(0)
	v_mov_b64_e32 v[0:1], s[2:3]
	s_xor_b64 exec, exec, s[0:1]
	v_mov_b64_e32 v[0:1], s[64:65]
	v_mov_b32_e32 v28, v61
	s_or_b64 exec, exec, s[0:1]
	v_ashrrev_i32_e32 v29, 31, v28
	v_lshlrev_b64 v[2:3], 12, v[28:29]
	v_lshl_add_u64 v[0:1], v[0:1], 0, v[2:3]
	v_lshl_add_u64 v[0:1], v[0:1], 0, v[176:177]
	v_mul_f32_e32 v2, v13, v50
	global_store_dword v[0:1], v2, off offset:128
	s_and_saveexec_b64 s[0:1], s[28:29]
	s_xor_b64 s[0:1], exec, s[0:1]
	s_mov_b64 s[2:3], s[92:93]
	s_or_saveexec_b64 s[0:1], s[0:1]
	s_waitcnt lgkmcnt(0)
	v_mov_b64_e32 v[0:1], s[2:3]
	s_xor_b64 exec, exec, s[0:1]
	v_mov_b64_e32 v[0:1], s[64:65]
	v_mov_b32_e32 v46, v47
	s_or_b64 exec, exec, s[0:1]
	v_ashrrev_i32_e32 v47, 31, v46
	v_lshlrev_b64 v[2:3], 12, v[46:47]
	v_lshl_add_u64 v[0:1], v[0:1], 0, v[2:3]
	v_lshl_add_u64 v[0:1], v[0:1], 0, v[176:177]
	v_mul_f32_e32 v2, v14, v50
	global_store_dword v[0:1], v2, off offset:128
	s_and_saveexec_b64 s[0:1], s[30:31]
	s_xor_b64 s[0:1], exec, s[0:1]
	s_mov_b64 s[2:3], s[92:93]
	s_or_saveexec_b64 s[0:1], s[0:1]
	s_waitcnt lgkmcnt(0)
	v_mov_b64_e32 v[0:1], s[2:3]
	s_xor_b64 exec, exec, s[0:1]
	s_cbranch_execz .LBB0_687
	v_mov_b64_e32 v[0:1], s[64:65]
	v_mov_b32_e32 v30, v62
	s_branch .LBB0_687

.LBB0_1001:
	v_mul_hi_i32 v0, v16, s35
	v_lshrrev_b32_e32 v1, 31, v0
	v_ashrrev_i32_e32 v0, 11, v0
	v_add_u32_e32 v19, v0, v1
	v_mad_i32_i24 v1, v19, s33, v16
	v_cmp_gt_i32_e64 s[2:3], s95, v1
	s_and_b64 s[0:1], s[56:57], s[2:3]
	v_cmp_lt_i32_e64 s[4:5], s82, v1
	s_xor_b64 s[0:1], s[0:1], -1
	s_and_saveexec_b64 s[18:19], s[0:1]
	s_cbranch_execz .LBB0_1000
	s_and_saveexec_b64 s[0:1], s[4:5]
	s_xor_b64 s[0:1], exec, s[0:1]
	s_load_dwordx2 s[20:21], s[6:7], 0xe8
	v_mul_i32_i24_e32 v0, 0xffffdf00, v19
	v_lshl_add_u32 v0, v19, 13, v0
	v_add3_u32 v0, v16, v0, s79
	s_or_saveexec_b64 s[0:1], s[0:1]
	s_waitcnt lgkmcnt(0)
	v_mov_b64_e32 v[2:3], s[20:21]
	s_xor_b64 exec, exec, s[0:1]
	v_lshl_add_u32 v0, v19, 8, v1
	v_mov_b64_e32 v[2:3], s[12:13]
	s_or_b64 exec, exec, s[0:1]
	v_ashrrev_i32_e32 v1, 31, v0
	v_lshlrev_b64 v[0:1], 12, v[0:1]
	v_lshl_add_u64 v[0:1], v[2:3], 0, v[0:1]
	v_lshlrev_b32_e32 v176, 2, v18
	v_lshl_add_u64 v[32:33], v[0:1], 0, v[176:177]
	s_cmp_eq_u64 s[2:3], 0
	s_cbranch_scc1 .Lctxp_ln1_a
	s_mov_b32 s22, 0x8e40000
	s_mov_b32 s23, 0
	v_lshl_add_u64 v[178:179], v[32:33], 0, s[22:23]
	global_load_dwordx4 v[56:59], v[178:179], off
	global_load_dwordx4 v[60:63], v[178:179], off offset:1024
	global_load_dwordx4 v[64:67], v[178:179], off offset:2048
	global_load_dwordx4 v[68:71], v[178:179], off offset:3072
	s_add_u32 s22, s22, 0x200000
	v_lshl_add_u64 v[178:179], v[32:33], 0, s[22:23]
	global_load_dwordx4 v[72:75], v[178:179], off
	global_load_dwordx4 v[76:79], v[178:179], off offset:1024
	global_load_dwordx4 v[102:105], v[178:179], off offset:2048
	global_load_dwordx4 v[106:109], v[178:179], off offset:3072
	s_add_u32 s22, s22, 0x200000
	v_lshl_add_u64 v[178:179], v[32:33], 0, s[22:23]
	global_load_dwordx4 v[110:113], v[178:179], off
	global_load_dwordx4 v[114:117], v[178:179], off offset:1024
	global_load_dwordx4 v[118:121], v[178:179], off offset:2048
	global_load_dwordx4 v[122:125], v[178:179], off offset:3072
	s_add_u32 s22, s22, 0x200000
	v_lshl_add_u64 v[178:179], v[32:33], 0, s[22:23]
	global_load_dwordx4 v[126:129], v[178:179], off
	global_load_dwordx4 v[130:133], v[178:179], off offset:1024
	global_load_dwordx4 v[134:137], v[178:179], off offset:2048
	global_load_dwordx4 v[172:175], v[178:179], off offset:3072
.Lctxp_ln1_a:
	global_load_dwordx4 v[12:15], v[32:33], off
	global_load_dwordx4 v[8:11], v[32:33], off offset:1024
	global_load_dwordx4 v[4:7], v[32:33], off offset:2048
	global_load_dwordx4 v[0:3], v[32:33], off offset:3072
	v_and_b32_e32 v27, 64, v196
	v_add_u32_e32 v27, 64, v27
	v_xor_b32_e32 v29, 32, v196
	v_cmp_lt_i32_e64 s[4:5], v29, v27
	s_mov_b32 s0, 0x800000
	s_cmp_eq_u64 s[2:3], 0
	s_cbranch_scc1 .Lctxp_ln1_b
	s_waitcnt vmcnt(0)
	v_pk_add_f32 v[56:57], v[56:57], v[72:73]
	v_pk_add_f32 v[110:111], v[110:111], v[126:127]
	v_pk_add_f32 v[56:57], v[56:57], v[110:111]
	v_pk_add_f32 v[12:13], v[12:13], v[56:57]
	v_pk_add_f32 v[58:59], v[58:59], v[74:75]
	v_pk_add_f32 v[112:113], v[112:113], v[128:129]
	v_pk_add_f32 v[58:59], v[58:59], v[112:113]
	v_pk_add_f32 v[14:15], v[14:15], v[58:59]
	v_pk_add_f32 v[60:61], v[60:61], v[76:77]
	v_pk_add_f32 v[114:115], v[114:115], v[130:131]
	v_pk_add_f32 v[60:61], v[60:61], v[114:115]
	v_pk_add_f32 v[8:9], v[8:9], v[60:61]
	v_pk_add_f32 v[62:63], v[62:63], v[78:79]
	v_pk_add_f32 v[116:117], v[116:117], v[132:133]
	v_pk_add_f32 v[62:63], v[62:63], v[116:117]
	v_pk_add_f32 v[10:11], v[10:11], v[62:63]
	v_pk_add_f32 v[64:65], v[64:65], v[102:103]
	v_pk_add_f32 v[118:119], v[118:119], v[134:135]
	v_pk_add_f32 v[64:65], v[64:65], v[118:119]
	v_pk_add_f32 v[4:5], v[4:5], v[64:65]
	v_pk_add_f32 v[66:67], v[66:67], v[104:105]
	v_pk_add_f32 v[120:121], v[120:121], v[136:137]
	v_pk_add_f32 v[66:67], v[66:67], v[120:121]
	v_pk_add_f32 v[6:7], v[6:7], v[66:67]
	v_pk_add_f32 v[68:69], v[68:69], v[106:107]
	v_pk_add_f32 v[122:123], v[122:123], v[172:173]
	v_pk_add_f32 v[68:69], v[68:69], v[122:123]
	v_pk_add_f32 v[0:1], v[0:1], v[68:69]
	v_pk_add_f32 v[70:71], v[70:71], v[108:109]
	v_pk_add_f32 v[124:125], v[124:125], v[174:175]
	v_pk_add_f32 v[70:71], v[70:71], v[124:125]
	v_pk_add_f32 v[2:3], v[2:3], v[70:71]
.Lctxp_ln1_b:
	s_waitcnt vmcnt(3)
	v_mov_b32_e32 v34, v13
	v_mov_b32_e32 v35, v14
	v_mov_b32_e32 v36, v12
	v_mov_b32_e32 v37, v15
	v_pk_add_f32 v[34:35], v[34:35], v[36:37]
	s_waitcnt vmcnt(2)
	v_mov_b32_e32 v36, v9
	v_mov_b32_e32 v37, v10
	v_mov_b32_e32 v38, v8
	v_mov_b32_e32 v39, v11
	v_pk_add_f32 v[36:37], v[36:37], v[38:39]
	v_add_f32_e32 v17, v34, v35
	v_pk_add_f32 v[36:37], v[36:37], v[36:37] op_sel:[0,1] op_sel_hi:[1,0]
	v_add_f32_e32 v34, 0, v17
	s_waitcnt vmcnt(1)
	v_add_f32_e32 v38, v4, v5
	v_add_f32_e32 v40, v6, v7
	s_waitcnt vmcnt(0)
	v_mov_b32_e32 v35, v0
	v_mov_b32_e32 v37, v1
	v_mov_b32_e32 v39, v2
	v_mov_b32_e32 v41, v3
	v_pk_add_f32 v[34:35], v[34:35], v[36:37]
	v_pk_add_f32 v[36:37], v[38:39], v[40:41]
	v_cndmask_b32_e64 v29, v196, v29, s[4:5]
	v_pk_add_f32 v[34:35], v[34:35], v[36:37]
	v_lshlrev_b32_e32 v29, 2, v29
	v_add_f32_e32 v17, v34, v35
	ds_bpermute_b32 v31, v29, v17
	s_waitcnt lgkmcnt(0)
	v_add_f32_e32 v17, v17, v31
	v_xor_b32_e32 v31, 16, v196
	v_cmp_lt_i32_e64 s[4:5], v31, v27
	s_nop 1
	v_cndmask_b32_e64 v31, v196, v31, s[4:5]
	v_lshlrev_b32_e32 v31, 2, v31
	ds_bpermute_b32 v34, v31, v17
	s_waitcnt lgkmcnt(0)
	v_add_f32_e32 v17, v17, v34
	v_xor_b32_e32 v34, 8, v196
	v_cmp_lt_i32_e64 s[4:5], v34, v27
	s_nop 1
	v_cndmask_b32_e64 v34, v196, v34, s[4:5]
	v_lshlrev_b32_e32 v42, 2, v34
	ds_bpermute_b32 v34, v42, v17
	s_waitcnt lgkmcnt(0)
	v_add_f32_e32 v17, v17, v34
	v_xor_b32_e32 v34, 4, v196
	v_cmp_lt_i32_e64 s[4:5], v34, v27
	s_nop 1
	v_cndmask_b32_e64 v34, v196, v34, s[4:5]
	v_lshlrev_b32_e32 v43, 2, v34
	ds_bpermute_b32 v34, v43, v17
	s_waitcnt lgkmcnt(0)
	v_add_f32_e32 v17, v17, v34
	v_xor_b32_e32 v34, 2, v196
	v_cmp_lt_i32_e64 s[4:5], v34, v27
	s_nop 1
	v_cndmask_b32_e64 v34, v196, v34, s[4:5]
	v_lshlrev_b32_e32 v44, 2, v34
	ds_bpermute_b32 v34, v44, v17
	s_waitcnt lgkmcnt(0)
	v_add_f32_e32 v17, v17, v34
	v_xor_b32_e32 v34, 1, v196
	v_cmp_lt_i32_e64 s[4:5], v34, v27
	s_nop 1
	v_cndmask_b32_e64 v27, v196, v34, s[4:5]
	v_lshlrev_b32_e32 v27, 2, v27
	ds_bpermute_b32 v34, v27, v17
	s_waitcnt lgkmcnt(0)
	v_add_f32_e32 v17, v17, v34
	v_fmamk_f32 v13, v17, 0xba800000, v13
	v_fmamk_f32 v12, v17, 0xba800000, v12
	v_fmamk_f32 v15, v17, 0xba800000, v15
	v_fmac_f32_e32 v14, 0xba800000, v17
	v_pk_mul_f32 v[34:35], v[14:15], v[14:15]
	v_pk_mul_f32 v[36:37], v[12:13], v[12:13]
	v_fmamk_f32 v9, v17, 0xba800000, v9
	v_pk_mov_b32 v[38:39], v[36:37], v[34:35] op_sel:[1,0]
	v_mov_b32_e32 v37, v35
	v_pk_add_f32 v[34:35], v[38:39], v[36:37]
	v_fmamk_f32 v8, v17, 0xba800000, v8
	v_fmamk_f32 v11, v17, 0xba800000, v11
	v_fmac_f32_e32 v10, 0xba800000, v17
	v_pk_add_f32 v[34:35], v[34:35], v[34:35] op_sel_hi:[0,1]
	v_pk_mul_f32 v[36:37], v[10:11], v[10:11]
	v_pk_mul_f32 v[38:39], v[8:9], v[8:9]
	v_fmamk_f32 v4, v17, 0xba800000, v4
	v_pk_mov_b32 v[40:41], v[38:39], v[36:37] op_sel:[1,0]
	v_mov_b32_e32 v39, v37
	v_fmamk_f32 v5, v17, 0xba800000, v5
	v_fmac_f32_e32 v6, 0xba800000, v17
	v_mul_f32_e32 v34, v4, v4
	v_pk_add_f32 v[36:37], v[40:41], v[38:39]
	v_fmamk_f32 v7, v17, 0xba800000, v7
	v_pk_fma_f32 v[38:39], v[4:5], v[4:5], v[34:35] op_sel_hi:[1,1,0]
	v_mul_f32_e32 v34, v6, v6
	v_pk_add_f32 v[36:37], v[36:37], v[36:37] op_sel_hi:[0,1]
	v_pk_fma_f32 v[40:41], v[6:7], v[6:7], v[34:35] op_sel_hi:[1,1,0]
	v_fmamk_f32 v3, v17, 0xba800000, v3
	v_fmamk_f32 v2, v17, 0xba800000, v2
	v_fmamk_f32 v1, v17, 0xba800000, v1
	v_fmac_f32_e32 v0, 0xba800000, v17
	v_mul_f32_e32 v38, v0, v0
	v_mul_f32_e32 v40, v1, v1
	v_mul_f32_e32 v34, v2, v2
	v_mul_f32_e32 v36, v3, v3
	v_pk_add_f32 v[38:39], v[38:39], v[40:41]
	v_pk_add_f32 v[34:35], v[34:35], v[36:37]
	s_nop 0
	v_pk_add_f32 v[34:35], v[38:39], v[34:35]
	s_nop 0
	v_add_f32_e32 v17, v34, v35
	ds_bpermute_b32 v29, v29, v17
	s_waitcnt lgkmcnt(0)
	v_add_f32_e32 v17, v17, v29
	ds_bpermute_b32 v29, v31, v17
	s_waitcnt lgkmcnt(0)
	v_add_f32_e32 v17, v17, v29
	ds_bpermute_b32 v29, v42, v17
	s_waitcnt lgkmcnt(0)
	v_add_f32_e32 v17, v17, v29
	ds_bpermute_b32 v29, v43, v17
	s_waitcnt lgkmcnt(0)
	v_add_f32_e32 v17, v17, v29
	ds_bpermute_b32 v29, v44, v17
	s_waitcnt lgkmcnt(0)
	v_add_f32_e32 v17, v17, v29
	ds_bpermute_b32 v27, v27, v17
	s_waitcnt lgkmcnt(0)
	v_add_f32_e32 v17, v17, v27
	v_fmamk_f32 v17, v17, 0x3a800000, v197
	v_cmp_gt_f32_e64 s[4:5], s0, v17
	v_mul_f32_e32 v27, 0x4b800000, v17
	s_nop 0
	v_cndmask_b32_e64 v17, v17, v27, s[4:5]
	v_rsq_f32_e32 v17, v17
	s_nop 0
	v_mul_f32_e32 v27, 0x45800000, v17
	v_cndmask_b32_e64 v34, v17, v27, s[4:5]
	v_pk_mul_f32 v[44:45], v[12:13], v[34:35] op_sel_hi:[1,0]
	v_pk_mul_f32 v[12:13], v[14:15], v[34:35] op_sel_hi:[1,0]
	s_and_b64 s[4:5], s[2:3], s[60:61]
	v_ashrrev_i32_e32 v17, 31, v16
	v_pk_fma_f32 v[12:13], v[142:143], v[12:13], v[146:147]
	v_pk_fma_f32 v[14:15], v[140:141], v[44:45], v[144:145]
	v_pk_mul_f32 v[44:45], v[8:9], v[34:35] op_sel_hi:[1,0]
	v_pk_mul_f32 v[8:9], v[10:11], v[34:35] op_sel_hi:[1,0]
	v_pk_fma_f32 v[10:11], v[148:149], v[44:45], v[152:153]
	v_pk_fma_f32 v[8:9], v[150:151], v[8:9], v[154:155]
	v_pk_mul_f32 v[44:45], v[4:5], v[34:35] op_sel_hi:[1,0]
	v_pk_mul_f32 v[4:5], v[6:7], v[34:35] op_sel_hi:[1,0]
	v_pk_fma_f32 v[6:7], v[156:157], v[44:45], v[160:161]
	v_pk_fma_f32 v[4:5], v[158:159], v[4:5], v[162:163]
	v_pk_mul_f32 v[44:45], v[0:1], v[34:35] op_sel_hi:[1,0]
	v_pk_mul_f32 v[0:1], v[2:3], v[34:35] op_sel_hi:[1,0]
	v_pk_fma_f32 v[2:3], v[164:165], v[44:45], v[168:169]
	v_pk_fma_f32 v[0:1], v[166:167], v[0:1], v[170:171]
	v_cndmask_b32_e64 v38, 1.0, v252, s[4:5]
	v_pk_mul_f32 v[36:37], v[38:39], v[12:13] op_sel_hi:[0,1]
	v_pk_mul_f32 v[34:35], v[38:39], v[14:15] op_sel_hi:[0,1]
	global_store_dwordx4 v[32:33], v[34:37], off
	s_nop 1
	v_pk_mul_f32 v[36:37], v[38:39], v[8:9] op_sel_hi:[0,1]
	v_pk_mul_f32 v[34:35], v[38:39], v[10:11] op_sel_hi:[0,1]
	global_store_dwordx4 v[32:33], v[34:37], off offset:1024
	s_nop 1
	v_pk_mul_f32 v[36:37], v[38:39], v[4:5] op_sel_hi:[0,1]
	v_pk_mul_f32 v[34:35], v[38:39], v[6:7] op_sel_hi:[0,1]
	global_store_dwordx4 v[32:33], v[34:37], off offset:2048
	s_nop 1
	v_pk_mul_f32 v[36:37], v[38:39], v[0:1] op_sel_hi:[0,1]
	v_pk_mul_f32 v[34:35], v[38:39], v[2:3] op_sel_hi:[0,1]
	global_store_dwordx4 v[32:33], v[34:37], off offset:3072
	s_and_saveexec_b64 s[0:1], vcc
	s_cbranch_execz .LBB0_999
	v_mov_b32_e32 v34, v177
	v_lshl_add_u64 v[32:33], v[16:17], 3, s[14:15]
	s_nop 0
	v_mov_b32_e32 v35, v34
	global_store_dwordx2 v[32:33], v[34:35], off
	s_branch .LBB0_999

.LBB0_1168:
	s_and_b64 vcc, exec, s[60:61]
	s_cbranch_vccz .LBB0_1431
	s_mov_b32 s89, s94
	s_cmp_gt_i32 s89, 63
	s_cbranch_scc1 .LBB0_1431
	s_add_u32 s58, s14, 0x11000
	s_addc_u32 s59, s15, 0
	s_mov_b64 s[52:53], s[64:65]
	s_and_b32 s64, s89, 3
	s_lshl_b32 s64, s64, 21
	s_add_u32 s64, s64, 0xbfea000
	s_add_u32 s64, s4, s64
	s_addc_u32 s65, s5, 0
	v_readlane_b32 s2, v255, 12
	v_lshrrev_b32_e32 v0, 3, v142
	s_add_u32 s62, s2, s91
	v_readlane_b32 s2, v255, 13
	v_and_b32_e32 v84, 31, v142
	v_and_b32_e32 v85, 4, v0
	s_addc_u32 s63, s2, 0
	s_lshl_b32 s90, s89, 5
	s_mov_b32 s91, s89
	s_branch .LBB0_1172
.LBB0_1171:
	s_or_b64 exec, exec, s[2:3]
	v_ashrrev_i32_e32 v31, 31, v30
	v_lshlrev_b64 v[2:3], 12, v[30:31]
	v_lshl_add_u64 v[0:1], v[0:1], 0, v[2:3]
	v_lshl_add_u64 v[0:1], v[0:1], 0, v[176:177]
	v_mul_f32_e32 v2, v15, v50
	global_store_dword v[0:1], v2, off offset:128
	v_readlane_b32 s2, v255, 11
	s_add_i32 s91, s91, s36
	s_add_i32 s90, s90, s2
	s_add_i32 s89, s89, s36
	s_cmp_lt_i32 s91, 64
	s_cbranch_scc0 .LBB0_1430

.LBB0_1173:
	s_mul_i32 s8, s5, 0xc000
	v_add_u32_e32 v87, s8, v83
	v_add_u32_e32 v90, 0x2000, v87
	v_readfirstlane_b32 s8, v87
	v_lshl_add_u64 v[88:89], v[74:75], 0, s[2:3]
	s_mov_b32 m0, s8
	v_readfirstlane_b32 s8, v90
	v_add_u32_e32 v90, 0x4000, v87
	s_waitcnt vmcnt(6)
	s_barrier
	global_load_lds_dwordx4 v[88:89], off
	v_lshl_add_u64 v[88:89], v[72:73], 0, s[2:3]
	s_mov_b32 m0, s8
	v_readfirstlane_b32 s8, v90
	v_add_u32_e32 v90, 0x6000, v87
	global_load_lds_dwordx4 v[88:89], off
	v_lshl_add_u64 v[88:89], v[70:71], 0, s[2:3]
	s_mov_b32 m0, s8
	v_readfirstlane_b32 s8, v90
	v_add_u32_e32 v90, 0x8000, v87
	global_load_lds_dwordx4 v[88:89], off
	v_lshl_add_u64 v[88:89], v[68:69], 0, s[2:3]
	s_mov_b32 m0, s8
	v_readfirstlane_b32 s8, v90
	v_add_u32_e32 v87, 0xa000, v87
	global_load_lds_dwordx4 v[88:89], off
	v_lshl_add_u64 v[88:89], v[66:67], 0, s[2:3]
	s_mov_b32 m0, s8
	v_readfirstlane_b32 s8, v87
	global_load_lds_dwordx4 v[88:89], off
	v_lshl_add_u64 v[88:89], v[64:65], 0, s[2:3]
	s_mov_b32 m0, s8
	s_mul_i32 s8, s7, 0xc000
	global_load_lds_dwordx4 v[88:89], off
	s_add_i32 s8, s8, 0
	v_add_u32_e32 v87, s8, v82
	v_add_u32_e32 v120, s8, v81
	v_add_u32_e32 v92, v87, v80
	v_add_u32_e32 v100, v120, v80
	v_add_u32_e32 v108, v87, v79
	v_add_u32_e32 v116, v120, v79
	ds_read_b128 v[88:91], v92
	ds_read_b128 v[92:95], v92 offset:4096
	ds_read_b128 v[96:99], v100 offset:32768
	ds_read_b128 v[100:103], v100 offset:36864
	ds_read_b128 v[104:107], v108
	ds_read_b128 v[108:111], v108 offset:4096
	ds_read_b128 v[112:115], v116 offset:32768
	ds_read_b128 v[116:119], v116 offset:36864
	s_waitcnt lgkmcnt(0)
	v_mfma_f32_32x32x16_bf16 v[48:63], v[88:91], v[96:99], v[48:63]
	v_mfma_f32_32x32x16_bf16 v[32:47], v[88:91], v[100:103], v[32:47]
	v_mfma_f32_32x32x16_bf16 v[16:31], v[92:95], v[96:99], v[16:31]
	v_add_u32_e32 v96, v87, v78
	ds_read_b128 v[88:91], v96
	v_mfma_f32_32x32x16_bf16 v[0:15], v[92:95], v[100:103], v[0:15]
	v_add_u32_e32 v100, v120, v78
	ds_read_b128 v[92:95], v100 offset:32768
	ds_read_b128 v[96:99], v96 offset:4096
	ds_read_b128 v[100:103], v100 offset:36864
	v_mfma_f32_32x32x16_bf16 v[48:63], v[104:107], v[112:115], v[48:63]
	v_add_u32_e32 v87, v87, v77
	v_mfma_f32_32x32x16_bf16 v[32:47], v[104:107], v[116:119], v[32:47]
	ds_read_b128 v[104:107], v87
	v_mfma_f32_32x32x16_bf16 v[16:31], v[108:111], v[112:115], v[16:31]
	v_mfma_f32_32x32x16_bf16 v[0:15], v[108:111], v[116:119], v[0:15]
	v_add_u32_e32 v116, v120, v77
	ds_read_b128 v[108:111], v116 offset:32768
	ds_read_b128 v[112:115], v87 offset:4096
	ds_read_b128 v[116:119], v116 offset:36864
	s_waitcnt lgkmcnt(0)
	v_mfma_f32_32x32x16_bf16 v[48:63], v[88:91], v[92:95], v[48:63]
	s_add_i32 s8, s7, 1
	s_cmp_lg_u32 s7, 2
	s_cselect_b32 s7, s8, 0
	s_add_i32 s8, s5, 1
	s_cmp_lg_u32 s5, 2
	s_cselect_b32 s5, s8, 0
	s_add_u32 s2, s2, 0x80
	v_mfma_f32_32x32x16_bf16 v[32:47], v[88:91], v[100:103], v[32:47]
	s_addc_u32 s3, s3, 0
	s_cmpk_eq_i32 s2, 0x480
	v_mfma_f32_32x32x16_bf16 v[16:31], v[96:99], v[92:95], v[16:31]
	v_mfma_f32_32x32x16_bf16 v[0:15], v[96:99], v[100:103], v[0:15]
	v_mfma_f32_32x32x16_bf16 v[48:63], v[104:107], v[108:111], v[48:63]
	v_mfma_f32_32x32x16_bf16 v[32:47], v[104:107], v[116:119], v[32:47]
	v_mfma_f32_32x32x16_bf16 v[16:31], v[112:115], v[108:111], v[16:31]
	v_mfma_f32_32x32x16_bf16 v[0:15], v[112:115], v[116:119], v[0:15]
	s_cbranch_scc0 .LBB0_1173
	v_add_u32_e32 v82, 0, v82
	v_add_u32_e32 v81, 0, v81
	v_add_u32_e32 v83, v82, v80
	v_add_u32_e32 v87, v81, v80
	s_waitcnt vmcnt(6)
	s_barrier
	ds_read_b128 v[64:67], v83
	ds_read_b128 v[68:71], v83 offset:4096
	ds_read_b128 v[72:75], v87 offset:32768
	ds_read_b128 v[88:91], v87 offset:36864
	v_add_u32_e32 v87, v82, v79
	v_add_u32_e32 v104, v81, v79
	ds_read_b128 v[92:95], v87
	ds_read_b128 v[96:99], v87 offset:4096
	ds_read_b128 v[100:103], v104 offset:32768
	ds_read_b128 v[104:107], v104 offset:36864
	s_waitcnt lgkmcnt(0)
	v_mfma_f32_32x32x16_bf16 v[48:63], v[64:67], v[72:75], v[48:63]
	v_add_u32_e32 v108, v82, v78
	v_mfma_f32_32x32x16_bf16 v[32:47], v[64:67], v[88:91], v[32:47]
	ds_read_b128 v[64:67], v108
	v_mfma_f32_32x32x16_bf16 v[16:31], v[68:71], v[72:75], v[16:31]
	v_mfma_f32_32x32x16_bf16 v[0:15], v[68:71], v[88:91], v[0:15]
	v_add_u32_e32 v88, v81, v78
	ds_read_b128 v[68:71], v88 offset:32768
	ds_read_b128 v[72:75], v108 offset:4096
	ds_read_b128 v[88:91], v88 offset:36864
	v_mfma_f32_32x32x16_bf16 v[48:63], v[92:95], v[100:103], v[48:63]
	v_add_u32_e32 v109, v82, v77
	v_add_u32_e32 v82, v81, v77
	v_mfma_f32_32x32x16_bf16 v[32:47], v[92:95], v[104:107], v[32:47]
	ds_read_b128 v[92:95], v109
	v_mfma_f32_32x32x16_bf16 v[16:31], v[96:99], v[100:103], v[16:31]
	v_mfma_f32_32x32x16_bf16 v[0:15], v[96:99], v[104:107], v[0:15]
	ds_read_b128 v[96:99], v82 offset:32768
	ds_read_b128 v[100:103], v109 offset:4096
	ds_read_b128 v[104:107], v82 offset:36864
	s_waitcnt lgkmcnt(0)
	v_mfma_f32_32x32x16_bf16 v[32:47], v[64:67], v[88:91], v[32:47]
	s_waitcnt vmcnt(0)
	s_barrier
	v_mfma_f32_32x32x16_bf16 v[0:15], v[72:75], v[88:91], v[0:15]
	v_mfma_f32_32x32x16_bf16 v[48:63], v[64:67], v[68:71], v[48:63]
	ds_read_b128 v[64:67], v83 offset:49152
	v_mfma_f32_32x32x16_bf16 v[16:31], v[72:75], v[68:71], v[16:31]
	v_mfma_f32_32x32x16_bf16 v[32:47], v[92:95], v[104:107], v[32:47]
	v_mfma_f32_32x32x16_bf16 v[0:15], v[100:103], v[104:107], v[0:15]
	v_add_u32_e32 v104, 0xc000, v81
	v_add_u32_e32 v80, v104, v80
	ds_read_b128 v[68:71], v80 offset:32768
	ds_read_b128 v[72:75], v83 offset:53248
	ds_read_b128 v[80:83], v80 offset:36864
	ds_read_b128 v[88:91], v87 offset:49152
	v_add_u32_e32 v79, v104, v79
	v_mfma_f32_32x32x16_bf16 v[48:63], v[92:95], v[96:99], v[48:63]
	v_mfma_f32_32x32x16_bf16 v[16:31], v[100:103], v[96:99], v[16:31]
	ds_read_b128 v[92:95], v79 offset:32768
	ds_read_b128 v[96:99], v87 offset:53248
	ds_read_b128 v[100:103], v79 offset:36864
	s_waitcnt lgkmcnt(0)
	v_mfma_f32_32x32x16_bf16 v[48:63], v[64:67], v[68:71], v[48:63]
	v_add_u32_e32 v78, v104, v78
	v_mfma_f32_32x32x16_bf16 v[32:47], v[64:67], v[80:83], v[32:47]
	ds_read_b128 v[64:67], v108 offset:49152
	v_mfma_f32_32x32x16_bf16 v[16:31], v[72:75], v[68:71], v[16:31]
	v_mfma_f32_32x32x16_bf16 v[0:15], v[72:75], v[80:83], v[0:15]
	ds_read_b128 v[68:71], v78 offset:32768
	ds_read_b128 v[72:75], v108 offset:53248
	ds_read_b128 v[78:81], v78 offset:36864
	v_mfma_f32_32x32x16_bf16 v[48:63], v[88:91], v[92:95], v[48:63]
	v_add_u32_e32 v77, v104, v77
	v_mfma_f32_32x32x16_bf16 v[32:47], v[88:91], v[100:103], v[32:47]
	ds_read_b128 v[88:91], v109 offset:49152
	v_mfma_f32_32x32x16_bf16 v[16:31], v[96:99], v[92:95], v[16:31]
	v_mfma_f32_32x32x16_bf16 v[0:15], v[96:99], v[100:103], v[0:15]
	ds_read_b128 v[92:95], v77 offset:32768
	ds_read_b128 v[96:99], v109 offset:53248
	ds_read_b128 v[100:103], v77 offset:36864
	s_waitcnt lgkmcnt(0)
	v_mfma_f32_32x32x16_bf16 v[48:63], v[64:67], v[68:71], v[48:63]
	s_waitcnt vmcnt(0)
	s_barrier
	v_mfma_f32_32x32x16_bf16 v[32:47], v[64:67], v[78:81], v[32:47]
	v_or3_b32 v64, s4, v84, v76
	v_lshlrev_b32_e32 v176, 2, v64
	global_load_dword v65, v176, s[58:59]
	v_add_u32_e32 v64, s6, v86
	v_or_b32_e32 v64, v64, v85
	v_mul_hi_i32 v66, v64, s35
	v_lshrrev_b32_e32 v67, 31, v66
	v_mfma_f32_32x32x16_bf16 v[16:31], v[72:75], v[68:71], v[16:31]
	v_ashrrev_i32_e32 v66, 11, v66
	v_add_u32_e32 v67, v66, v67
	v_mad_i32_i24 v70, v67, s33, v64
	v_lshlrev_b32_e32 v68, 13, v67
	v_cmp_lt_i32_e32 vcc, s82, v70
	v_add3_u32 v64, v68, v70, s79
	v_mfma_f32_32x32x16_bf16 v[0:15], v[72:75], v[78:81], v[0:15]
	v_mfma_f32_32x32x16_bf16 v[48:63], v[88:91], v[92:95], v[48:63]
	v_mfma_f32_32x32x16_bf16 v[32:47], v[88:91], v[100:103], v[32:47]
	v_mfma_f32_32x32x16_bf16 v[16:31], v[96:99], v[92:95], v[16:31]
	v_mfma_f32_32x32x16_bf16 v[0:15], v[96:99], v[100:103], v[0:15]
	s_load_dwordx2 s[92:93], s[0:1], 0xe8
	s_waitcnt lgkmcnt(0)
	s_and_saveexec_b64 s[2:3], vcc
	s_xor_b64 s[2:3], exec, s[2:3]
	s_mov_b64 s[4:5], s[92:93]
	v_add3_u32 v66, v68, v70, s79
	s_or_saveexec_b64 s[2:3], s[2:3]
	s_waitcnt lgkmcnt(0)
	v_mov_b64_e32 v[68:69], s[4:5]
	v_lshl_add_u32 v88, v67, 8, v70
	s_xor_b64 exec, exec, s[2:3]
	v_lshl_add_u32 v66, v67, 8, v70
	v_mov_b64_e32 v[68:69], s[64:65]
	s_or_b64 exec, exec, s[2:3]
	v_ashrrev_i32_e32 v67, 31, v66
	v_lshlrev_b64 v[66:67], 12, v[66:67]
	v_lshl_add_u64 v[66:67], v[68:69], 0, v[66:67]
	v_lshl_add_u64 v[66:67], v[66:67], 0, v[176:177]
	s_waitcnt vmcnt(0)
	v_mul_f32_e32 v48, v48, v65
	global_store_dword v[66:67], v48, off
	v_or_b32_e32 v87, s6, v85
	v_add3_u32 v66, v86, v87, 1
	v_mul_hi_i32 v48, v66, s35
	v_lshrrev_b32_e32 v67, 31, v48
	v_ashrrev_i32_e32 v48, 11, v48
	v_add_u32_e32 v48, v48, v67
	v_mad_i32_i24 v69, v48, s33, v66
	v_lshlrev_b32_e32 v67, 13, v48
	v_cmp_lt_i32_e64 s[2:3], s82, v69
	v_add3_u32 v66, v67, v69, s79
	s_and_saveexec_b64 s[4:5], s[2:3]
	s_xor_b64 s[4:5], exec, s[4:5]
	s_mov_b64 s[6:7], s[92:93]
	v_add3_u32 v68, v67, v69, s79
	s_or_saveexec_b64 s[4:5], s[4:5]
	s_waitcnt lgkmcnt(0)
	v_mov_b64_e32 v[70:71], s[6:7]
	v_lshl_add_u32 v67, v48, 8, v69
	s_xor_b64 exec, exec, s[4:5]
	v_lshl_add_u32 v68, v48, 8, v69
	v_mov_b64_e32 v[70:71], s[64:65]
	s_or_b64 exec, exec, s[4:5]
	v_ashrrev_i32_e32 v69, 31, v68
	v_lshlrev_b64 v[68:69], 12, v[68:69]
	v_lshl_add_u64 v[68:69], v[70:71], 0, v[68:69]
	v_lshl_add_u64 v[68:69], v[68:69], 0, v[176:177]
	v_mul_f32_e32 v48, v49, v65
	global_store_dword v[68:69], v48, off
	v_add3_u32 v48, v86, v87, 2
	v_mul_hi_i32 v49, v48, s35
	v_lshrrev_b32_e32 v68, 31, v49
	v_ashrrev_i32_e32 v49, 11, v49
	v_add_u32_e32 v49, v49, v68
	v_mad_i32_i24 v72, v49, s33, v48
	v_lshlrev_b32_e32 v69, 13, v49
	v_cmp_lt_i32_e64 s[4:5], s82, v72
	v_add3_u32 v68, v69, v72, s79
	s_and_saveexec_b64 s[6:7], s[4:5]
	s_xor_b64 s[6:7], exec, s[6:7]
	s_mov_b64 s[8:9], s[92:93]
	v_add3_u32 v48, v69, v72, s79
	s_or_saveexec_b64 s[6:7], s[6:7]
	s_waitcnt lgkmcnt(0)
	v_mov_b64_e32 v[70:71], s[8:9]
	v_lshl_add_u32 v69, v49, 8, v72
	s_xor_b64 exec, exec, s[6:7]
	v_lshl_add_u32 v48, v49, 8, v72
	v_mov_b64_e32 v[70:71], s[64:65]
	s_or_b64 exec, exec, s[6:7]
	v_ashrrev_i32_e32 v49, 31, v48
	v_lshlrev_b64 v[48:49], 12, v[48:49]
	v_lshl_add_u64 v[48:49], v[70:71], 0, v[48:49]
	v_lshl_add_u64 v[48:49], v[48:49], 0, v[176:177]
	v_mul_f32_e32 v50, v50, v65
	global_store_dword v[48:49], v50, off
	v_add3_u32 v48, v86, v87, 3
	v_mul_hi_i32 v49, v48, s35
	v_lshrrev_b32_e32 v50, 31, v49
	v_ashrrev_i32_e32 v49, 11, v49
	v_add_u32_e32 v49, v49, v50
	v_mad_i32_i24 v72, v49, s33, v48
	v_lshlrev_b32_e32 v70, 13, v49
	v_cmp_lt_i32_e64 s[6:7], s82, v72
	v_add3_u32 v50, v70, v72, s79
	s_and_saveexec_b64 s[8:9], s[6:7]
	s_xor_b64 s[8:9], exec, s[8:9]
	s_mov_b64 s[10:11], s[92:93]
	v_add3_u32 v48, v70, v72, s79
	s_or_saveexec_b64 s[8:9], s[8:9]
	s_waitcnt lgkmcnt(0)
	v_mov_b64_e32 v[70:71], s[10:11]
	v_lshl_add_u32 v89, v49, 8, v72
	s_xor_b64 exec, exec, s[8:9]
	v_lshl_add_u32 v48, v49, 8, v72
	v_mov_b64_e32 v[70:71], s[64:65]
	s_or_b64 exec, exec, s[8:9]
	v_ashrrev_i32_e32 v49, 31, v48
	v_lshlrev_b64 v[48:49], 12, v[48:49]
	v_lshl_add_u64 v[48:49], v[70:71], 0, v[48:49]
	v_lshl_add_u64 v[48:49], v[48:49], 0, v[176:177]
	v_mul_f32_e32 v51, v51, v65
	global_store_dword v[48:49], v51, off
	v_add3_u32 v48, v86, v87, 8
	v_mul_hi_i32 v49, v48, s35
	v_lshrrev_b32_e32 v51, 31, v49
	v_ashrrev_i32_e32 v49, 11, v49
	v_add_u32_e32 v49, v49, v51
	v_mad_i32_i24 v51, v49, s33, v48
	v_lshlrev_b32_e32 v71, 13, v49
	v_cmp_lt_i32_e64 s[8:9], s82, v51
	v_add3_u32 v70, v71, v51, s79
	s_and_saveexec_b64 s[10:11], s[8:9]
	s_xor_b64 s[10:11], exec, s[10:11]
	s_mov_b64 s[12:13], s[92:93]
	v_add3_u32 v48, v71, v51, s79
	s_or_saveexec_b64 s[10:11], s[10:11]
	s_waitcnt lgkmcnt(0)
	v_mov_b64_e32 v[72:73], s[12:13]
	v_lshl_add_u32 v71, v49, 8, v51
	s_xor_b64 exec, exec, s[10:11]
	v_lshl_add_u32 v48, v49, 8, v51
	v_mov_b64_e32 v[72:73], s[64:65]
	s_or_b64 exec, exec, s[10:11]
	v_ashrrev_i32_e32 v49, 31, v48
	v_lshlrev_b64 v[48:49], 12, v[48:49]
	v_lshl_add_u64 v[48:49], v[72:73], 0, v[48:49]
	v_lshl_add_u64 v[48:49], v[48:49], 0, v[176:177]
	v_mul_f32_e32 v51, v52, v65
	global_store_dword v[48:49], v51, off
	v_add3_u32 v48, v86, v87, 9
	v_mul_hi_i32 v49, v48, s35
	v_lshrrev_b32_e32 v51, 31, v49
	v_ashrrev_i32_e32 v49, 11, v49
	v_add_u32_e32 v49, v49, v51
	v_mad_i32_i24 v51, v49, s33, v48
	v_lshlrev_b32_e32 v72, 13, v49
	v_cmp_lt_i32_e64 s[10:11], s82, v51
	v_add3_u32 v52, v72, v51, s79
	s_and_saveexec_b64 s[12:13], s[10:11]
	s_xor_b64 s[12:13], exec, s[12:13]
	s_mov_b64 s[14:15], s[92:93]
	v_add3_u32 v48, v72, v51, s79
	s_or_saveexec_b64 s[12:13], s[12:13]
	s_waitcnt lgkmcnt(0)
	v_mov_b64_e32 v[72:73], s[14:15]
	v_lshl_add_u32 v90, v49, 8, v51
	s_xor_b64 exec, exec, s[12:13]
	v_lshl_add_u32 v48, v49, 8, v51
	v_mov_b64_e32 v[72:73], s[64:65]
	s_or_b64 exec, exec, s[12:13]
	v_ashrrev_i32_e32 v49, 31, v48
	v_lshlrev_b64 v[48:49], 12, v[48:49]
	v_lshl_add_u64 v[48:49], v[72:73], 0, v[48:49]
	v_lshl_add_u64 v[48:49], v[48:49], 0, v[176:177]
	v_mul_f32_e32 v51, v53, v65
	global_store_dword v[48:49], v51, off
	v_add3_u32 v48, v86, v87, 10
	v_mul_hi_i32 v49, v48, s35
	v_lshrrev_b32_e32 v51, 31, v49
	v_ashrrev_i32_e32 v49, 11, v49
	v_add_u32_e32 v49, v49, v51
	v_mad_i32_i24 v51, v49, s33, v48
	v_lshlrev_b32_e32 v53, 13, v49
	v_cmp_lt_i32_e64 s[12:13], s82, v51
	v_add3_u32 v72, v53, v51, s79
	s_and_saveexec_b64 s[14:15], s[12:13]
	s_xor_b64 s[14:15], exec, s[14:15]
	s_mov_b64 s[16:17], s[92:93]
	v_add3_u32 v48, v53, v51, s79
	s_or_saveexec_b64 s[14:15], s[14:15]
	s_waitcnt lgkmcnt(0)
	v_mov_b64_e32 v[74:75], s[16:17]
	v_lshl_add_u32 v73, v49, 8, v51
	s_xor_b64 exec, exec, s[14:15]
	v_lshl_add_u32 v48, v49, 8, v51
	v_mov_b64_e32 v[74:75], s[64:65]
	s_or_b64 exec, exec, s[14:15]
	v_ashrrev_i32_e32 v49, 31, v48
	v_lshlrev_b64 v[48:49], 12, v[48:49]
	v_lshl_add_u64 v[48:49], v[74:75], 0, v[48:49]
	v_lshl_add_u64 v[48:49], v[48:49], 0, v[176:177]
	v_mul_f32_e32 v51, v54, v65
	global_store_dword v[48:49], v51, off
	v_add3_u32 v48, v86, v87, 11
	v_mul_hi_i32 v49, v48, s35
	v_lshrrev_b32_e32 v51, 31, v49
	v_ashrrev_i32_e32 v49, 11, v49
	v_add_u32_e32 v49, v49, v51
	v_mad_i32_i24 v51, v49, s33, v48
	v_lshlrev_b32_e32 v53, 13, v49
	v_cmp_lt_i32_e64 s[14:15], s82, v51
	v_add3_u32 v54, v53, v51, s79
	s_and_saveexec_b64 s[16:17], s[14:15]
	s_xor_b64 s[16:17], exec, s[16:17]
	s_mov_b64 s[18:19], s[92:93]
	v_add3_u32 v48, v53, v51, s79
	s_or_saveexec_b64 s[16:17], s[16:17]
	s_waitcnt lgkmcnt(0)
	v_mov_b64_e32 v[74:75], s[18:19]
	v_lshl_add_u32 v91, v49, 8, v51
	s_xor_b64 exec, exec, s[16:17]
	v_lshl_add_u32 v48, v49, 8, v51
	v_mov_b64_e32 v[74:75], s[64:65]
	s_or_b64 exec, exec, s[16:17]
	v_ashrrev_i32_e32 v49, 31, v48
	v_lshlrev_b64 v[48:49], 12, v[48:49]
	v_lshl_add_u64 v[48:49], v[74:75], 0, v[48:49]
	v_lshl_add_u64 v[48:49], v[48:49], 0, v[176:177]
	v_mul_f32_e32 v51, v55, v65
	global_store_dword v[48:49], v51, off
	v_add3_u32 v48, v86, v87, 16
	v_mul_hi_i32 v49, v48, s35
	v_lshrrev_b32_e32 v51, 31, v49
	v_ashrrev_i32_e32 v49, 11, v49
	v_add_u32_e32 v49, v49, v51
	v_mad_i32_i24 v51, v49, s33, v48
	v_lshlrev_b32_e32 v53, 13, v49
	v_cmp_lt_i32_e64 s[16:17], s82, v51
	v_add3_u32 v74, v53, v51, s79
	s_and_saveexec_b64 s[18:19], s[16:17]
	s_xor_b64 s[18:19], exec, s[18:19]
	s_mov_b64 s[20:21], s[92:93]
	v_add3_u32 v48, v53, v51, s79
	s_or_saveexec_b64 s[18:19], s[18:19]
	s_waitcnt lgkmcnt(0)
	v_mov_b64_e32 v[76:77], s[20:21]
	v_lshl_add_u32 v75, v49, 8, v51
	s_xor_b64 exec, exec, s[18:19]
	v_lshl_add_u32 v48, v49, 8, v51
	v_mov_b64_e32 v[76:77], s[64:65]
	s_or_b64 exec, exec, s[18:19]
	v_ashrrev_i32_e32 v49, 31, v48
	v_lshlrev_b64 v[48:49], 12, v[48:49]
	v_lshl_add_u64 v[48:49], v[76:77], 0, v[48:49]
	v_lshl_add_u64 v[48:49], v[48:49], 0, v[176:177]
	v_mul_f32_e32 v51, v56, v65
	global_store_dword v[48:49], v51, off
	v_add3_u32 v48, v86, v87, 17
	v_mul_hi_i32 v49, v48, s35
	v_lshrrev_b32_e32 v51, 31, v49
	v_ashrrev_i32_e32 v49, 11, v49
	v_add_u32_e32 v49, v49, v51
	v_mad_i32_i24 v51, v49, s33, v48
	v_lshlrev_b32_e32 v53, 13, v49
	v_cmp_lt_i32_e64 s[18:19], s82, v51
	v_add3_u32 v56, v53, v51, s79
	s_and_saveexec_b64 s[20:21], s[18:19]
	s_xor_b64 s[20:21], exec, s[20:21]
	s_mov_b64 s[22:23], s[92:93]
	v_add3_u32 v48, v53, v51, s79
	s_or_saveexec_b64 s[20:21], s[20:21]
	s_waitcnt lgkmcnt(0)
	v_mov_b64_e32 v[76:77], s[22:23]
	v_lshl_add_u32 v92, v49, 8, v51
	s_xor_b64 exec, exec, s[20:21]
	v_lshl_add_u32 v48, v49, 8, v51
	v_mov_b64_e32 v[76:77], s[64:65]
	s_or_b64 exec, exec, s[20:21]
	v_ashrrev_i32_e32 v49, 31, v48
	v_lshlrev_b64 v[48:49], 12, v[48:49]
	v_lshl_add_u64 v[48:49], v[76:77], 0, v[48:49]
	v_lshl_add_u64 v[48:49], v[48:49], 0, v[176:177]
	v_mul_f32_e32 v51, v57, v65
	global_store_dword v[48:49], v51, off
	v_add3_u32 v48, v86, v87, 18
	v_mul_hi_i32 v49, v48, s35
	v_lshrrev_b32_e32 v51, 31, v49
	v_ashrrev_i32_e32 v49, 11, v49
	v_add_u32_e32 v49, v49, v51
	v_mad_i32_i24 v51, v49, s33, v48
	v_lshlrev_b32_e32 v53, 13, v49
	v_cmp_lt_i32_e64 s[20:21], s82, v51
	v_add3_u32 v76, v53, v51, s79
	s_and_saveexec_b64 s[22:23], s[20:21]
	s_xor_b64 s[22:23], exec, s[22:23]
	s_mov_b64 s[24:25], s[92:93]
	v_add3_u32 v48, v53, v51, s79
	s_or_saveexec_b64 s[22:23], s[22:23]
	s_waitcnt lgkmcnt(0)
	v_mov_b64_e32 v[78:79], s[24:25]
	v_lshl_add_u32 v77, v49, 8, v51
	s_xor_b64 exec, exec, s[22:23]
	v_lshl_add_u32 v48, v49, 8, v51
	v_mov_b64_e32 v[78:79], s[64:65]
	s_or_b64 exec, exec, s[22:23]
	v_ashrrev_i32_e32 v49, 31, v48
	v_lshlrev_b64 v[48:49], 12, v[48:49]
	v_lshl_add_u64 v[48:49], v[78:79], 0, v[48:49]
	v_lshl_add_u64 v[48:49], v[48:49], 0, v[176:177]
	v_mul_f32_e32 v51, v58, v65
	global_store_dword v[48:49], v51, off
	v_add3_u32 v48, v86, v87, 19
	v_mul_hi_i32 v49, v48, s35
	v_lshrrev_b32_e32 v51, 31, v49
	v_ashrrev_i32_e32 v49, 11, v49
	v_add_u32_e32 v49, v49, v51
	v_mad_i32_i24 v51, v49, s33, v48
	v_lshlrev_b32_e32 v53, 13, v49
	v_cmp_lt_i32_e64 s[22:23], s82, v51
	v_add3_u32 v58, v53, v51, s79
	s_and_saveexec_b64 s[24:25], s[22:23]
	s_xor_b64 s[24:25], exec, s[24:25]
	s_mov_b64 s[26:27], s[92:93]
	v_add3_u32 v48, v53, v51, s79
	s_or_saveexec_b64 s[24:25], s[24:25]
	s_waitcnt lgkmcnt(0)
	v_mov_b64_e32 v[78:79], s[26:27]
	v_lshl_add_u32 v93, v49, 8, v51
	s_xor_b64 exec, exec, s[24:25]
	v_lshl_add_u32 v48, v49, 8, v51
	v_mov_b64_e32 v[78:79], s[64:65]
	s_or_b64 exec, exec, s[24:25]
	v_ashrrev_i32_e32 v49, 31, v48
	v_lshlrev_b64 v[48:49], 12, v[48:49]
	v_lshl_add_u64 v[48:49], v[78:79], 0, v[48:49]
	v_lshl_add_u64 v[48:49], v[48:49], 0, v[176:177]
	v_mul_f32_e32 v51, v59, v65
	global_store_dword v[48:49], v51, off
	v_add3_u32 v48, v86, v87, 24
	v_mul_hi_i32 v49, v48, s35
	v_lshrrev_b32_e32 v51, 31, v49
	v_ashrrev_i32_e32 v49, 11, v49
	v_add_u32_e32 v49, v49, v51
	v_mad_i32_i24 v51, v49, s33, v48
	v_lshlrev_b32_e32 v53, 13, v49
	v_cmp_lt_i32_e64 s[24:25], s82, v51
	v_add3_u32 v78, v53, v51, s79
	s_and_saveexec_b64 s[26:27], s[24:25]
	s_xor_b64 s[26:27], exec, s[26:27]
	s_mov_b64 s[28:29], s[92:93]
	v_add3_u32 v48, v53, v51, s79
	s_or_saveexec_b64 s[26:27], s[26:27]
	s_waitcnt lgkmcnt(0)
	v_mov_b64_e32 v[80:81], s[28:29]
	v_lshl_add_u32 v79, v49, 8, v51
	s_xor_b64 exec, exec, s[26:27]
	v_lshl_add_u32 v48, v49, 8, v51
	v_mov_b64_e32 v[80:81], s[64:65]
	s_or_b64 exec, exec, s[26:27]
	v_ashrrev_i32_e32 v49, 31, v48
	v_lshlrev_b64 v[48:49], 12, v[48:49]
	v_lshl_add_u64 v[48:49], v[80:81], 0, v[48:49]
	v_lshl_add_u64 v[48:49], v[48:49], 0, v[176:177]
	v_mul_f32_e32 v51, v60, v65
	global_store_dword v[48:49], v51, off
	v_add3_u32 v48, v86, v87, 25
	v_mul_hi_i32 v49, v48, s35
	v_lshrrev_b32_e32 v51, 31, v49
	v_ashrrev_i32_e32 v49, 11, v49
	v_add_u32_e32 v49, v49, v51
	v_mad_i32_i24 v51, v49, s33, v48
	v_lshlrev_b32_e32 v53, 13, v49
	v_cmp_lt_i32_e64 s[26:27], s82, v51
	v_add3_u32 v60, v53, v51, s79
	s_and_saveexec_b64 s[28:29], s[26:27]
	s_xor_b64 s[28:29], exec, s[28:29]
	s_mov_b64 s[30:31], s[92:93]
	v_add3_u32 v48, v53, v51, s79
	s_or_saveexec_b64 s[28:29], s[28:29]
	s_waitcnt lgkmcnt(0)
	v_mov_b64_e32 v[80:81], s[30:31]
	v_lshl_add_u32 v94, v49, 8, v51
	s_xor_b64 exec, exec, s[28:29]
	v_lshl_add_u32 v48, v49, 8, v51
	v_mov_b64_e32 v[80:81], s[64:65]
	s_or_b64 exec, exec, s[28:29]
	v_ashrrev_i32_e32 v49, 31, v48
	v_lshlrev_b64 v[48:49], 12, v[48:49]
	v_lshl_add_u64 v[48:49], v[80:81], 0, v[48:49]
	v_lshl_add_u64 v[48:49], v[48:49], 0, v[176:177]
	v_mul_f32_e32 v51, v61, v65
	global_store_dword v[48:49], v51, off
	v_add3_u32 v48, v86, v87, 26
	v_mul_hi_i32 v49, v48, s35
	v_lshrrev_b32_e32 v51, 31, v49
	v_ashrrev_i32_e32 v49, 11, v49
	v_add_u32_e32 v49, v49, v51
	v_mad_i32_i24 v51, v49, s33, v48
	v_lshlrev_b32_e32 v53, 13, v49
	v_cmp_lt_i32_e64 s[28:29], s82, v51
	v_add3_u32 v80, v53, v51, s79
	s_and_saveexec_b64 s[30:31], s[28:29]
	s_xor_b64 s[30:31], exec, s[30:31]
	s_mov_b64 s[74:75], s[92:93]
	v_add3_u32 v48, v53, v51, s79
	s_or_saveexec_b64 s[30:31], s[30:31]
	s_waitcnt lgkmcnt(0)
	v_mov_b64_e32 v[82:83], s[74:75]
	v_lshl_add_u32 v81, v49, 8, v51
	s_xor_b64 exec, exec, s[30:31]
	v_lshl_add_u32 v48, v49, 8, v51
	v_mov_b64_e32 v[82:83], s[64:65]
	s_or_b64 exec, exec, s[30:31]
	v_ashrrev_i32_e32 v49, 31, v48
	v_lshlrev_b64 v[48:49], 12, v[48:49]
	v_lshl_add_u64 v[48:49], v[82:83], 0, v[48:49]
	v_lshl_add_u64 v[48:49], v[48:49], 0, v[176:177]
	v_mul_f32_e32 v51, v62, v65
	global_store_dword v[48:49], v51, off
	v_add3_u32 v48, v86, v87, 27
	v_mul_hi_i32 v49, v48, s35
	v_lshrrev_b32_e32 v51, 31, v49
	v_ashrrev_i32_e32 v49, 11, v49
	v_add_u32_e32 v49, v49, v51
	v_mad_i32_i24 v51, v49, s33, v48
	v_lshlrev_b32_e32 v53, 13, v49
	v_cmp_lt_i32_e64 s[30:31], s82, v51
	v_add3_u32 v62, v53, v51, s79
	s_and_saveexec_b64 s[74:75], s[30:31]
	s_xor_b64 s[74:75], exec, s[74:75]
	s_mov_b64 s[76:77], s[92:93]
	v_add3_u32 v48, v53, v51, s79
	s_or_saveexec_b64 s[74:75], s[74:75]
	s_waitcnt lgkmcnt(0)
	v_mov_b64_e32 v[82:83], s[76:77]
	v_lshl_add_u32 v95, v49, 8, v51
	s_xor_b64 exec, exec, s[74:75]
	v_lshl_add_u32 v48, v49, 8, v51
	v_mov_b64_e32 v[82:83], s[64:65]
	s_or_b64 exec, exec, s[74:75]
	v_ashrrev_i32_e32 v49, 31, v48
	v_lshlrev_b64 v[48:49], 12, v[48:49]
	v_lshl_add_u64 v[48:49], v[82:83], 0, v[48:49]
	v_lshl_add_u64 v[48:49], v[48:49], 0, v[176:177]
	v_mul_f32_e32 v51, v63, v65
	global_store_dword v[48:49], v51, off
	v_or_b32_e32 v48, 0x80, v176
	global_load_dword v49, v48, s[58:59]
	s_and_saveexec_b64 s[74:75], vcc
	s_xor_b64 s[74:75], exec, s[74:75]
	s_mov_b64 s[76:77], s[92:93]
	s_or_saveexec_b64 s[74:75], s[74:75]
	s_waitcnt lgkmcnt(0)
	v_mov_b64_e32 v[82:83], s[76:77]
	s_xor_b64 exec, exec, s[74:75]
	v_mov_b64_e32 v[82:83], s[64:65]
	v_mov_b32_e32 v64, v88
	s_or_b64 exec, exec, s[74:75]
	v_ashrrev_i32_e32 v65, 31, v64
	v_lshlrev_b64 v[64:65], 12, v[64:65]
	v_lshl_add_u64 v[64:65], v[82:83], 0, v[64:65]
	v_lshl_add_u64 v[64:65], v[64:65], 0, v[176:177]
	s_waitcnt vmcnt(0)
	v_mul_f32_e32 v32, v32, v49
	global_store_dword v[64:65], v32, off offset:128
	s_and_saveexec_b64 s[76:77], s[2:3]
	s_xor_b64 s[2:3], exec, s[76:77]
	s_mov_b64 s[74:75], s[92:93]
	s_or_saveexec_b64 s[2:3], s[2:3]
	s_waitcnt lgkmcnt(0)
	v_mov_b64_e32 v[64:65], s[74:75]
	s_xor_b64 exec, exec, s[2:3]
	v_mov_b64_e32 v[64:65], s[64:65]
	v_mov_b32_e32 v66, v67
	s_or_b64 exec, exec, s[2:3]
	v_ashrrev_i32_e32 v67, 31, v66
	v_lshlrev_b64 v[66:67], 12, v[66:67]
	v_lshl_add_u64 v[64:65], v[64:65], 0, v[66:67]
	v_lshl_add_u64 v[64:65], v[64:65], 0, v[176:177]
	v_mul_f32_e32 v32, v33, v49
	global_store_dword v[64:65], v32, off offset:128
	s_and_saveexec_b64 s[2:3], s[4:5]
	s_xor_b64 s[2:3], exec, s[2:3]
	s_mov_b64 s[74:75], s[92:93]
	s_or_saveexec_b64 s[2:3], s[2:3]
	s_waitcnt lgkmcnt(0)
	v_mov_b64_e32 v[32:33], s[74:75]
	s_xor_b64 exec, exec, s[2:3]
	v_mov_b64_e32 v[32:33], s[64:65]
	v_mov_b32_e32 v68, v69
	s_or_b64 exec, exec, s[2:3]
	v_ashrrev_i32_e32 v69, 31, v68
	v_lshlrev_b64 v[64:65], 12, v[68:69]
	v_lshl_add_u64 v[32:33], v[32:33], 0, v[64:65]
	v_lshl_add_u64 v[32:33], v[32:33], 0, v[176:177]
	v_mul_f32_e32 v34, v34, v49
	global_store_dword v[32:33], v34, off offset:128
	s_and_saveexec_b64 s[2:3], s[6:7]
	s_xor_b64 s[2:3], exec, s[2:3]
	s_mov_b64 s[4:5], s[92:93]
	s_or_saveexec_b64 s[2:3], s[2:3]
	s_waitcnt lgkmcnt(0)
	v_mov_b64_e32 v[32:33], s[4:5]
	s_xor_b64 exec, exec, s[2:3]
	v_mov_b64_e32 v[32:33], s[64:65]
	v_mov_b32_e32 v50, v89
	s_or_b64 exec, exec, s[2:3]
	v_ashrrev_i32_e32 v51, 31, v50
	v_lshlrev_b64 v[50:51], 12, v[50:51]
	v_lshl_add_u64 v[32:33], v[32:33], 0, v[50:51]
	v_lshl_add_u64 v[32:33], v[32:33], 0, v[176:177]
	v_mul_f32_e32 v34, v35, v49
	global_store_dword v[32:33], v34, off offset:128
	s_and_saveexec_b64 s[2:3], s[8:9]
	s_xor_b64 s[2:3], exec, s[2:3]
	s_mov_b64 s[4:5], s[92:93]
	s_or_saveexec_b64 s[2:3], s[2:3]
	s_waitcnt lgkmcnt(0)
	v_mov_b64_e32 v[32:33], s[4:5]
	s_xor_b64 exec, exec, s[2:3]
	v_mov_b64_e32 v[32:33], s[64:65]
	v_mov_b32_e32 v70, v71
	s_or_b64 exec, exec, s[2:3]
	v_ashrrev_i32_e32 v71, 31, v70
	v_lshlrev_b64 v[34:35], 12, v[70:71]
	v_lshl_add_u64 v[32:33], v[32:33], 0, v[34:35]
	v_lshl_add_u64 v[32:33], v[32:33], 0, v[176:177]
	v_mul_f32_e32 v34, v36, v49
	global_store_dword v[32:33], v34, off offset:128
	s_and_saveexec_b64 s[2:3], s[10:11]
	s_xor_b64 s[2:3], exec, s[2:3]
	s_mov_b64 s[4:5], s[92:93]
	s_or_saveexec_b64 s[2:3], s[2:3]
	s_waitcnt lgkmcnt(0)
	v_mov_b64_e32 v[32:33], s[4:5]
	s_xor_b64 exec, exec, s[2:3]
	v_mov_b64_e32 v[32:33], s[64:65]
	v_mov_b32_e32 v52, v90
	s_or_b64 exec, exec, s[2:3]
	v_ashrrev_i32_e32 v53, 31, v52
	v_lshlrev_b64 v[34:35], 12, v[52:53]
	v_lshl_add_u64 v[32:33], v[32:33], 0, v[34:35]
	v_lshl_add_u64 v[32:33], v[32:33], 0, v[176:177]
	v_mul_f32_e32 v34, v37, v49
	global_store_dword v[32:33], v34, off offset:128
	s_and_saveexec_b64 s[2:3], s[12:13]
	s_xor_b64 s[2:3], exec, s[2:3]
	s_mov_b64 s[4:5], s[92:93]
	s_or_saveexec_b64 s[2:3], s[2:3]
	s_waitcnt lgkmcnt(0)
	v_mov_b64_e32 v[32:33], s[4:5]
	s_xor_b64 exec, exec, s[2:3]
	v_mov_b64_e32 v[32:33], s[64:65]
	v_mov_b32_e32 v72, v73
	s_or_b64 exec, exec, s[2:3]
	v_ashrrev_i32_e32 v73, 31, v72
	v_lshlrev_b64 v[34:35], 12, v[72:73]
	v_lshl_add_u64 v[32:33], v[32:33], 0, v[34:35]
	v_lshl_add_u64 v[32:33], v[32:33], 0, v[176:177]
	v_mul_f32_e32 v34, v38, v49
	global_store_dword v[32:33], v34, off offset:128
	s_and_saveexec_b64 s[2:3], s[14:15]
	s_xor_b64 s[2:3], exec, s[2:3]
	s_mov_b64 s[4:5], s[92:93]
	s_or_saveexec_b64 s[2:3], s[2:3]
	s_waitcnt lgkmcnt(0)
	v_mov_b64_e32 v[32:33], s[4:5]
	s_xor_b64 exec, exec, s[2:3]
	v_mov_b64_e32 v[32:33], s[64:65]
	v_mov_b32_e32 v54, v91
	s_or_b64 exec, exec, s[2:3]
	v_ashrrev_i32_e32 v55, 31, v54
	v_lshlrev_b64 v[34:35], 12, v[54:55]
	v_lshl_add_u64 v[32:33], v[32:33], 0, v[34:35]
	v_lshl_add_u64 v[32:33], v[32:33], 0, v[176:177]
	v_mul_f32_e32 v34, v39, v49
	global_store_dword v[32:33], v34, off offset:128
	s_and_saveexec_b64 s[2:3], s[16:17]
	s_xor_b64 s[2:3], exec, s[2:3]
	s_mov_b64 s[4:5], s[92:93]
	s_or_saveexec_b64 s[2:3], s[2:3]
	s_waitcnt lgkmcnt(0)
	v_mov_b64_e32 v[32:33], s[4:5]
	s_xor_b64 exec, exec, s[2:3]
	v_mov_b64_e32 v[32:33], s[64:65]
	v_mov_b32_e32 v74, v75
	s_or_b64 exec, exec, s[2:3]
	v_ashrrev_i32_e32 v75, 31, v74
	v_lshlrev_b64 v[34:35], 12, v[74:75]
	v_lshl_add_u64 v[32:33], v[32:33], 0, v[34:35]
	v_lshl_add_u64 v[32:33], v[32:33], 0, v[176:177]
	v_mul_f32_e32 v34, v40, v49
	global_store_dword v[32:33], v34, off offset:128
	s_and_saveexec_b64 s[2:3], s[18:19]
	s_xor_b64 s[2:3], exec, s[2:3]
	s_mov_b64 s[4:5], s[92:93]
	s_or_saveexec_b64 s[2:3], s[2:3]
	s_waitcnt lgkmcnt(0)
	v_mov_b64_e32 v[32:33], s[4:5]
	s_xor_b64 exec, exec, s[2:3]
	v_mov_b64_e32 v[32:33], s[64:65]
	v_mov_b32_e32 v56, v92
	s_or_b64 exec, exec, s[2:3]
	v_ashrrev_i32_e32 v57, 31, v56
	v_lshlrev_b64 v[34:35], 12, v[56:57]
	v_lshl_add_u64 v[32:33], v[32:33], 0, v[34:35]
	v_lshl_add_u64 v[32:33], v[32:33], 0, v[176:177]
	v_mul_f32_e32 v34, v41, v49
	global_store_dword v[32:33], v34, off offset:128
	s_and_saveexec_b64 s[2:3], s[20:21]
	s_xor_b64 s[2:3], exec, s[2:3]
	s_mov_b64 s[4:5], s[92:93]
	s_or_saveexec_b64 s[2:3], s[2:3]
	s_waitcnt lgkmcnt(0)
	v_mov_b64_e32 v[32:33], s[4:5]
	s_xor_b64 exec, exec, s[2:3]
	v_mov_b64_e32 v[32:33], s[64:65]
	v_mov_b32_e32 v76, v77
	s_or_b64 exec, exec, s[2:3]
	v_ashrrev_i32_e32 v77, 31, v76
	v_lshlrev_b64 v[34:35], 12, v[76:77]
	v_lshl_add_u64 v[32:33], v[32:33], 0, v[34:35]
	v_lshl_add_u64 v[32:33], v[32:33], 0, v[176:177]
	v_mul_f32_e32 v34, v42, v49
	global_store_dword v[32:33], v34, off offset:128
	s_and_saveexec_b64 s[2:3], s[22:23]
	s_xor_b64 s[2:3], exec, s[2:3]
	s_mov_b64 s[4:5], s[92:93]
	s_or_saveexec_b64 s[2:3], s[2:3]
	s_waitcnt lgkmcnt(0)
	v_mov_b64_e32 v[32:33], s[4:5]
	s_xor_b64 exec, exec, s[2:3]
	v_mov_b64_e32 v[32:33], s[64:65]
	v_mov_b32_e32 v58, v93
	s_or_b64 exec, exec, s[2:3]
	v_ashrrev_i32_e32 v59, 31, v58
	v_lshlrev_b64 v[34:35], 12, v[58:59]
	v_lshl_add_u64 v[32:33], v[32:33], 0, v[34:35]
	v_lshl_add_u64 v[32:33], v[32:33], 0, v[176:177]
	v_mul_f32_e32 v34, v43, v49
	global_store_dword v[32:33], v34, off offset:128
	s_and_saveexec_b64 s[2:3], s[24:25]
	s_xor_b64 s[2:3], exec, s[2:3]
	s_mov_b64 s[4:5], s[92:93]
	s_or_saveexec_b64 s[2:3], s[2:3]
	s_waitcnt lgkmcnt(0)
	v_mov_b64_e32 v[32:33], s[4:5]
	s_xor_b64 exec, exec, s[2:3]
	v_mov_b64_e32 v[32:33], s[64:65]
	v_mov_b32_e32 v78, v79
	s_or_b64 exec, exec, s[2:3]
	v_ashrrev_i32_e32 v79, 31, v78
	v_lshlrev_b64 v[34:35], 12, v[78:79]
	v_lshl_add_u64 v[32:33], v[32:33], 0, v[34:35]
	v_lshl_add_u64 v[32:33], v[32:33], 0, v[176:177]
	v_mul_f32_e32 v34, v44, v49
	global_store_dword v[32:33], v34, off offset:128
	s_and_saveexec_b64 s[2:3], s[26:27]
	s_xor_b64 s[2:3], exec, s[2:3]
	s_mov_b64 s[4:5], s[92:93]
	s_or_saveexec_b64 s[2:3], s[2:3]
	s_waitcnt lgkmcnt(0)
	v_mov_b64_e32 v[32:33], s[4:5]
	s_xor_b64 exec, exec, s[2:3]
	v_mov_b64_e32 v[32:33], s[64:65]
	v_mov_b32_e32 v60, v94
	s_or_b64 exec, exec, s[2:3]
	v_ashrrev_i32_e32 v61, 31, v60
	v_lshlrev_b64 v[34:35], 12, v[60:61]
	v_lshl_add_u64 v[32:33], v[32:33], 0, v[34:35]
	v_lshl_add_u64 v[32:33], v[32:33], 0, v[176:177]
	v_mul_f32_e32 v34, v45, v49
	global_store_dword v[32:33], v34, off offset:128
	s_and_saveexec_b64 s[2:3], s[28:29]
	s_xor_b64 s[2:3], exec, s[2:3]
	s_mov_b64 s[4:5], s[92:93]
	s_or_saveexec_b64 s[2:3], s[2:3]
	s_waitcnt lgkmcnt(0)
	v_mov_b64_e32 v[32:33], s[4:5]
	s_xor_b64 exec, exec, s[2:3]
	v_mov_b64_e32 v[32:33], s[64:65]
	v_mov_b32_e32 v80, v81
	s_or_b64 exec, exec, s[2:3]
	v_ashrrev_i32_e32 v81, 31, v80
	v_lshlrev_b64 v[34:35], 12, v[80:81]
	v_lshl_add_u64 v[32:33], v[32:33], 0, v[34:35]
	v_lshl_add_u64 v[32:33], v[32:33], 0, v[176:177]
	v_mul_f32_e32 v34, v46, v49
	global_store_dword v[32:33], v34, off offset:128
	s_and_saveexec_b64 s[2:3], s[30:31]
	s_xor_b64 s[2:3], exec, s[2:3]
	s_mov_b64 s[4:5], s[92:93]
	s_or_saveexec_b64 s[2:3], s[2:3]
	s_waitcnt lgkmcnt(0)
	v_mov_b64_e32 v[32:33], s[4:5]
	s_xor_b64 exec, exec, s[2:3]
	v_mov_b64_e32 v[32:33], s[64:65]
	v_mov_b32_e32 v62, v95
	s_or_b64 exec, exec, s[2:3]
	v_ashrrev_i32_e32 v63, 31, v62
	v_lshlrev_b64 v[36:37], 12, v[62:63]
	v_lshl_add_u64 v[32:33], v[32:33], 0, v[36:37]
	v_lshl_add_u64 v[32:33], v[32:33], 0, v[176:177]
	v_mul_f32_e32 v36, v47, v49
	v_lshl_add_u64 v[34:35], s[58:59], 0, v[176:177]
	global_store_dword v[32:33], v36, off offset:128
	global_load_dword v54, v[34:35], off
	v_add3_u32 v32, v86, v87, 32
	v_mul_hi_i32 v33, v32, s35
	v_lshrrev_b32_e32 v34, 31, v33
	v_ashrrev_i32_e32 v33, 11, v33
	v_add_u32_e32 v35, v33, v34
	v_mad_i32_i24 v38, v35, s33, v32
	v_lshlrev_b32_e32 v33, 13, v35
	v_cmp_lt_i32_e32 vcc, s82, v38
	v_add3_u32 v32, v33, v38, s79
	s_and_saveexec_b64 s[2:3], vcc
	s_xor_b64 s[2:3], exec, s[2:3]
	s_mov_b64 s[4:5], s[92:93]
	v_add3_u32 v34, v33, v38, s79
	s_or_saveexec_b64 s[2:3], s[2:3]
	s_waitcnt lgkmcnt(0)
	v_mov_b64_e32 v[36:37], s[4:5]
	v_lshl_add_u32 v33, v35, 8, v38
	s_xor_b64 exec, exec, s[2:3]
	v_lshl_add_u32 v34, v35, 8, v38
	v_mov_b64_e32 v[36:37], s[64:65]
	s_or_b64 exec, exec, s[2:3]
	v_ashrrev_i32_e32 v35, 31, v34
	v_lshlrev_b64 v[34:35], 12, v[34:35]
	v_lshl_add_u64 v[34:35], v[36:37], 0, v[34:35]
	v_lshl_add_u64 v[34:35], v[34:35], 0, v[176:177]
	s_waitcnt vmcnt(0)
	v_mul_f32_e32 v16, v16, v54
	global_store_dword v[34:35], v16, off
	v_add3_u32 v16, v86, v87, 33
	v_mul_hi_i32 v34, v16, s35
	v_lshrrev_b32_e32 v35, 31, v34
	v_ashrrev_i32_e32 v34, 11, v34
	v_add_u32_e32 v35, v34, v35
	v_mad_i32_i24 v38, v35, s33, v16
	v_lshlrev_b32_e32 v36, 13, v35
	v_cmp_lt_i32_e64 s[2:3], s82, v38
	v_add3_u32 v16, v36, v38, s79
	s_and_saveexec_b64 s[4:5], s[2:3]
	s_xor_b64 s[4:5], exec, s[4:5]
	s_mov_b64 s[6:7], s[92:93]
	v_add3_u32 v34, v36, v38, s79
	s_or_saveexec_b64 s[4:5], s[4:5]
	s_waitcnt lgkmcnt(0)
	v_mov_b64_e32 v[36:37], s[6:7]
	v_lshl_add_u32 v55, v35, 8, v38
	s_xor_b64 exec, exec, s[4:5]
	v_lshl_add_u32 v34, v35, 8, v38
	v_mov_b64_e32 v[36:37], s[64:65]
	s_or_b64 exec, exec, s[4:5]
	v_ashrrev_i32_e32 v35, 31, v34
	v_lshlrev_b64 v[34:35], 12, v[34:35]
	v_lshl_add_u64 v[34:35], v[36:37], 0, v[34:35]
	v_lshl_add_u64 v[34:35], v[34:35], 0, v[176:177]
	v_mul_f32_e32 v17, v17, v54
	global_store_dword v[34:35], v17, off
	v_add3_u32 v34, v86, v87, 34
	v_mul_hi_i32 v17, v34, s35
	v_lshrrev_b32_e32 v35, 31, v17
	v_ashrrev_i32_e32 v17, 11, v17
	v_add_u32_e32 v17, v17, v35
	v_mad_i32_i24 v37, v17, s33, v34
	v_lshlrev_b32_e32 v35, 13, v17
	v_cmp_lt_i32_e64 s[4:5], s82, v37
	v_add3_u32 v34, v35, v37, s79
	s_and_saveexec_b64 s[6:7], s[4:5]
	s_xor_b64 s[6:7], exec, s[6:7]
	s_mov_b64 s[8:9], s[92:93]
	v_add3_u32 v36, v35, v37, s79
	s_or_saveexec_b64 s[6:7], s[6:7]
	s_waitcnt lgkmcnt(0)
	v_mov_b64_e32 v[38:39], s[8:9]
	v_lshl_add_u32 v35, v17, 8, v37
	s_xor_b64 exec, exec, s[6:7]
	v_lshl_add_u32 v36, v17, 8, v37
	v_mov_b64_e32 v[38:39], s[64:65]
	s_or_b64 exec, exec, s[6:7]
	v_ashrrev_i32_e32 v37, 31, v36
	v_lshlrev_b64 v[36:37], 12, v[36:37]
	v_lshl_add_u64 v[36:37], v[38:39], 0, v[36:37]
	v_lshl_add_u64 v[36:37], v[36:37], 0, v[176:177]
	v_mul_f32_e32 v17, v18, v54
	global_store_dword v[36:37], v17, off
	v_add3_u32 v18, v86, v87, 35
	v_mul_hi_i32 v17, v18, s35
	v_lshrrev_b32_e32 v36, 31, v17
	v_ashrrev_i32_e32 v17, 11, v17
	v_add_u32_e32 v17, v17, v36
	v_mad_i32_i24 v37, v17, s33, v18
	v_lshlrev_b32_e32 v38, 13, v17
	v_cmp_lt_i32_e64 s[6:7], s82, v37
	v_add3_u32 v18, v38, v37, s79
	s_and_saveexec_b64 s[8:9], s[6:7]
	s_xor_b64 s[8:9], exec, s[8:9]
	s_mov_b64 s[10:11], s[92:93]
	v_add3_u32 v36, v38, v37, s79
	s_or_saveexec_b64 s[8:9], s[8:9]
	s_waitcnt lgkmcnt(0)
	v_mov_b64_e32 v[38:39], s[10:11]
	v_lshl_add_u32 v56, v17, 8, v37
	s_xor_b64 exec, exec, s[8:9]
	v_lshl_add_u32 v36, v17, 8, v37
	v_mov_b64_e32 v[38:39], s[64:65]
	s_or_b64 exec, exec, s[8:9]
	v_ashrrev_i32_e32 v37, 31, v36
	v_lshlrev_b64 v[36:37], 12, v[36:37]
	v_lshl_add_u64 v[36:37], v[38:39], 0, v[36:37]
	v_lshl_add_u64 v[36:37], v[36:37], 0, v[176:177]
	v_mul_f32_e32 v17, v19, v54
	global_store_dword v[36:37], v17, off
	v_add3_u32 v19, v86, v87, 40
	v_mul_hi_i32 v17, v19, s35
	v_lshrrev_b32_e32 v36, 31, v17
	v_ashrrev_i32_e32 v17, 11, v17
	v_add_u32_e32 v17, v17, v36
	v_mad_i32_i24 v19, v17, s33, v19
	v_lshlrev_b32_e32 v37, 13, v17
	v_cmp_lt_i32_e64 s[8:9], s82, v19
	v_add3_u32 v36, v37, v19, s79
	s_and_saveexec_b64 s[10:11], s[8:9]
	s_xor_b64 s[10:11], exec, s[10:11]
	s_mov_b64 s[12:13], s[92:93]
	v_add3_u32 v38, v37, v19, s79
	s_or_saveexec_b64 s[10:11], s[10:11]
	s_waitcnt lgkmcnt(0)
	v_mov_b64_e32 v[40:41], s[12:13]
	v_lshl_add_u32 v37, v17, 8, v19
	s_xor_b64 exec, exec, s[10:11]
	v_lshl_add_u32 v38, v17, 8, v19
	v_mov_b64_e32 v[40:41], s[64:65]
	s_or_b64 exec, exec, s[10:11]
	v_ashrrev_i32_e32 v39, 31, v38
	v_lshlrev_b64 v[38:39], 12, v[38:39]
	v_lshl_add_u64 v[38:39], v[40:41], 0, v[38:39]
	v_lshl_add_u64 v[38:39], v[38:39], 0, v[176:177]
	v_mul_f32_e32 v17, v20, v54
	global_store_dword v[38:39], v17, off
	v_add3_u32 v19, v86, v87, 41
	v_mul_hi_i32 v17, v19, s35
	v_lshrrev_b32_e32 v20, 31, v17
	v_ashrrev_i32_e32 v17, 11, v17
	v_add_u32_e32 v17, v17, v20
	v_mad_i32_i24 v19, v17, s33, v19
	v_lshlrev_b32_e32 v39, 13, v17
	v_cmp_lt_i32_e64 s[10:11], s82, v19
	v_add3_u32 v20, v39, v19, s79
	s_and_saveexec_b64 s[12:13], s[10:11]
	s_xor_b64 s[12:13], exec, s[12:13]
	s_mov_b64 s[14:15], s[92:93]
	v_add3_u32 v38, v39, v19, s79
	s_or_saveexec_b64 s[12:13], s[12:13]
	s_waitcnt lgkmcnt(0)
	v_mov_b64_e32 v[40:41], s[14:15]
	v_lshl_add_u32 v57, v17, 8, v19
	s_xor_b64 exec, exec, s[12:13]
	v_lshl_add_u32 v38, v17, 8, v19
	v_mov_b64_e32 v[40:41], s[64:65]
	s_or_b64 exec, exec, s[12:13]
	v_ashrrev_i32_e32 v39, 31, v38
	v_lshlrev_b64 v[38:39], 12, v[38:39]
	v_lshl_add_u64 v[38:39], v[40:41], 0, v[38:39]
	v_lshl_add_u64 v[38:39], v[38:39], 0, v[176:177]
	v_mul_f32_e32 v17, v21, v54
	global_store_dword v[38:39], v17, off
	v_add3_u32 v19, v86, v87, 42
	v_mul_hi_i32 v17, v19, s35
	v_lshrrev_b32_e32 v21, 31, v17
	v_ashrrev_i32_e32 v17, 11, v17
	v_add_u32_e32 v17, v17, v21
	v_mad_i32_i24 v19, v17, s33, v19
	v_lshlrev_b32_e32 v21, 13, v17
	v_cmp_lt_i32_e64 s[12:13], s82, v19
	v_add3_u32 v38, v21, v19, s79
	s_and_saveexec_b64 s[14:15], s[12:13]
	s_xor_b64 s[14:15], exec, s[14:15]
	s_mov_b64 s[16:17], s[92:93]
	v_add3_u32 v40, v21, v19, s79
	s_or_saveexec_b64 s[14:15], s[14:15]
	s_waitcnt lgkmcnt(0)
	v_mov_b64_e32 v[42:43], s[16:17]
	v_lshl_add_u32 v39, v17, 8, v19
	s_xor_b64 exec, exec, s[14:15]
	v_lshl_add_u32 v40, v17, 8, v19
	v_mov_b64_e32 v[42:43], s[64:65]
	s_or_b64 exec, exec, s[14:15]
	v_ashrrev_i32_e32 v41, 31, v40
	v_lshlrev_b64 v[40:41], 12, v[40:41]
	v_lshl_add_u64 v[40:41], v[42:43], 0, v[40:41]
	v_lshl_add_u64 v[40:41], v[40:41], 0, v[176:177]
	v_mul_f32_e32 v17, v22, v54
	global_store_dword v[40:41], v17, off
	v_add3_u32 v19, v86, v87, 43
	v_mul_hi_i32 v17, v19, s35
	v_lshrrev_b32_e32 v21, 31, v17
	v_ashrrev_i32_e32 v17, 11, v17
	v_add_u32_e32 v17, v17, v21
	v_mad_i32_i24 v19, v17, s33, v19
	v_lshlrev_b32_e32 v21, 13, v17
	v_cmp_lt_i32_e64 s[14:15], s82, v19
	v_add3_u32 v22, v21, v19, s79
	s_and_saveexec_b64 s[16:17], s[14:15]
	s_xor_b64 s[16:17], exec, s[16:17]
	s_mov_b64 s[18:19], s[92:93]
	v_add3_u32 v40, v21, v19, s79
	s_or_saveexec_b64 s[16:17], s[16:17]
	s_waitcnt lgkmcnt(0)
	v_mov_b64_e32 v[42:43], s[18:19]
	v_lshl_add_u32 v58, v17, 8, v19
	s_xor_b64 exec, exec, s[16:17]
	v_lshl_add_u32 v40, v17, 8, v19
	v_mov_b64_e32 v[42:43], s[64:65]
	s_or_b64 exec, exec, s[16:17]
	v_ashrrev_i32_e32 v41, 31, v40
	v_lshlrev_b64 v[40:41], 12, v[40:41]
	v_lshl_add_u64 v[40:41], v[42:43], 0, v[40:41]
	v_lshl_add_u64 v[40:41], v[40:41], 0, v[176:177]
	v_mul_f32_e32 v17, v23, v54
	global_store_dword v[40:41], v17, off
	v_add3_u32 v19, v86, v87, 48
	v_mul_hi_i32 v17, v19, s35
	v_lshrrev_b32_e32 v21, 31, v17
	v_ashrrev_i32_e32 v17, 11, v17
	v_add_u32_e32 v17, v17, v21
	v_mad_i32_i24 v19, v17, s33, v19
	v_lshlrev_b32_e32 v21, 13, v17
	v_cmp_lt_i32_e64 s[16:17], s82, v19
	v_add3_u32 v40, v21, v19, s79
	s_and_saveexec_b64 s[18:19], s[16:17]
	s_xor_b64 s[18:19], exec, s[18:19]
	s_mov_b64 s[20:21], s[92:93]
	v_add3_u32 v42, v21, v19, s79
	s_or_saveexec_b64 s[18:19], s[18:19]
	s_waitcnt lgkmcnt(0)
	v_mov_b64_e32 v[44:45], s[20:21]
	v_lshl_add_u32 v41, v17, 8, v19
	s_xor_b64 exec, exec, s[18:19]
	v_lshl_add_u32 v42, v17, 8, v19
	v_mov_b64_e32 v[44:45], s[64:65]
	s_or_b64 exec, exec, s[18:19]
	v_ashrrev_i32_e32 v43, 31, v42
	v_lshlrev_b64 v[42:43], 12, v[42:43]
	v_lshl_add_u64 v[42:43], v[44:45], 0, v[42:43]
	v_lshl_add_u64 v[42:43], v[42:43], 0, v[176:177]
	v_mul_f32_e32 v17, v24, v54
	global_store_dword v[42:43], v17, off
	v_add3_u32 v19, v86, v87, 49
	v_mul_hi_i32 v17, v19, s35
	v_lshrrev_b32_e32 v21, 31, v17
	v_ashrrev_i32_e32 v17, 11, v17
	v_add_u32_e32 v17, v17, v21
	v_mad_i32_i24 v19, v17, s33, v19
	v_lshlrev_b32_e32 v21, 13, v17
	v_cmp_lt_i32_e64 s[18:19], s82, v19
	v_add3_u32 v24, v21, v19, s79
	s_and_saveexec_b64 s[20:21], s[18:19]
	s_xor_b64 s[20:21], exec, s[20:21]
	s_mov_b64 s[22:23], s[92:93]
	v_add3_u32 v42, v21, v19, s79
	s_or_saveexec_b64 s[20:21], s[20:21]
	s_waitcnt lgkmcnt(0)
	v_mov_b64_e32 v[44:45], s[22:23]
	v_lshl_add_u32 v59, v17, 8, v19
	s_xor_b64 exec, exec, s[20:21]
	v_lshl_add_u32 v42, v17, 8, v19
	v_mov_b64_e32 v[44:45], s[64:65]
	s_or_b64 exec, exec, s[20:21]
	v_ashrrev_i32_e32 v43, 31, v42
	v_lshlrev_b64 v[42:43], 12, v[42:43]
	v_lshl_add_u64 v[42:43], v[44:45], 0, v[42:43]
	v_lshl_add_u64 v[42:43], v[42:43], 0, v[176:177]
	v_mul_f32_e32 v17, v25, v54
	global_store_dword v[42:43], v17, off
	v_add3_u32 v19, v86, v87, 50
	v_mul_hi_i32 v17, v19, s35
	v_lshrrev_b32_e32 v21, 31, v17
	v_ashrrev_i32_e32 v17, 11, v17
	v_add_u32_e32 v17, v17, v21
	v_mad_i32_i24 v19, v17, s33, v19
	v_lshlrev_b32_e32 v21, 13, v17
	v_cmp_lt_i32_e64 s[20:21], s82, v19
	v_add3_u32 v42, v21, v19, s79
	s_and_saveexec_b64 s[22:23], s[20:21]
	s_xor_b64 s[22:23], exec, s[22:23]
	s_mov_b64 s[24:25], s[92:93]
	v_add3_u32 v44, v21, v19, s79
	s_or_saveexec_b64 s[22:23], s[22:23]
	s_waitcnt lgkmcnt(0)
	v_mov_b64_e32 v[46:47], s[24:25]
	v_lshl_add_u32 v43, v17, 8, v19
	s_xor_b64 exec, exec, s[22:23]
	v_lshl_add_u32 v44, v17, 8, v19
	v_mov_b64_e32 v[46:47], s[64:65]
	s_or_b64 exec, exec, s[22:23]
	v_ashrrev_i32_e32 v45, 31, v44
	v_lshlrev_b64 v[44:45], 12, v[44:45]
	v_lshl_add_u64 v[44:45], v[46:47], 0, v[44:45]
	v_lshl_add_u64 v[44:45], v[44:45], 0, v[176:177]
	v_mul_f32_e32 v17, v26, v54
	global_store_dword v[44:45], v17, off
	v_add3_u32 v19, v86, v87, 51
	v_mul_hi_i32 v17, v19, s35
	v_lshrrev_b32_e32 v21, 31, v17
	v_ashrrev_i32_e32 v17, 11, v17
	v_add_u32_e32 v17, v17, v21
	v_mad_i32_i24 v19, v17, s33, v19
	v_lshlrev_b32_e32 v21, 13, v17
	v_cmp_lt_i32_e64 s[22:23], s82, v19
	v_add3_u32 v26, v21, v19, s79
	s_and_saveexec_b64 s[24:25], s[22:23]
	s_xor_b64 s[24:25], exec, s[24:25]
	s_mov_b64 s[26:27], s[92:93]
	v_add3_u32 v44, v21, v19, s79
	s_or_saveexec_b64 s[24:25], s[24:25]
	s_waitcnt lgkmcnt(0)
	v_mov_b64_e32 v[46:47], s[26:27]
	v_lshl_add_u32 v60, v17, 8, v19
	s_xor_b64 exec, exec, s[24:25]
	v_lshl_add_u32 v44, v17, 8, v19
	v_mov_b64_e32 v[46:47], s[64:65]
	s_or_b64 exec, exec, s[24:25]
	v_ashrrev_i32_e32 v45, 31, v44
	v_lshlrev_b64 v[44:45], 12, v[44:45]
	v_lshl_add_u64 v[44:45], v[46:47], 0, v[44:45]
	v_lshl_add_u64 v[44:45], v[44:45], 0, v[176:177]
	v_mul_f32_e32 v17, v27, v54
	global_store_dword v[44:45], v17, off
	v_add3_u32 v19, v86, v87, 56
	v_mul_hi_i32 v17, v19, s35
	v_lshrrev_b32_e32 v21, 31, v17
	v_ashrrev_i32_e32 v17, 11, v17
	v_add_u32_e32 v17, v17, v21
	v_mad_i32_i24 v19, v17, s33, v19
	v_lshlrev_b32_e32 v21, 13, v17
	v_cmp_lt_i32_e64 s[24:25], s82, v19
	v_add3_u32 v44, v21, v19, s79
	s_and_saveexec_b64 s[26:27], s[24:25]
	s_xor_b64 s[26:27], exec, s[26:27]
	s_mov_b64 s[28:29], s[92:93]
	v_add3_u32 v46, v21, v19, s79
	s_or_saveexec_b64 s[26:27], s[26:27]
	s_waitcnt lgkmcnt(0)
	v_mov_b64_e32 v[50:51], s[28:29]
	v_lshl_add_u32 v45, v17, 8, v19
	s_xor_b64 exec, exec, s[26:27]
	v_lshl_add_u32 v46, v17, 8, v19
	v_mov_b64_e32 v[50:51], s[64:65]
	s_or_b64 exec, exec, s[26:27]
	v_ashrrev_i32_e32 v47, 31, v46
	v_lshlrev_b64 v[46:47], 12, v[46:47]
	v_lshl_add_u64 v[46:47], v[50:51], 0, v[46:47]
	v_lshl_add_u64 v[46:47], v[46:47], 0, v[176:177]
	v_mul_f32_e32 v17, v28, v54
	global_store_dword v[46:47], v17, off
	v_add3_u32 v19, v86, v87, 57
	v_mul_hi_i32 v17, v19, s35
	v_lshrrev_b32_e32 v21, 31, v17
	v_ashrrev_i32_e32 v17, 11, v17
	v_add_u32_e32 v17, v17, v21
	v_mad_i32_i24 v19, v17, s33, v19
	v_lshlrev_b32_e32 v21, 13, v17
	v_cmp_lt_i32_e64 s[26:27], s82, v19
	v_add3_u32 v28, v21, v19, s79
	s_and_saveexec_b64 s[28:29], s[26:27]
	s_xor_b64 s[28:29], exec, s[28:29]
	s_mov_b64 s[30:31], s[92:93]
	v_add3_u32 v46, v21, v19, s79
	s_or_saveexec_b64 s[28:29], s[28:29]
	s_waitcnt lgkmcnt(0)
	v_mov_b64_e32 v[50:51], s[30:31]
	v_lshl_add_u32 v61, v17, 8, v19
	s_xor_b64 exec, exec, s[28:29]
	v_lshl_add_u32 v46, v17, 8, v19
	v_mov_b64_e32 v[50:51], s[64:65]
	s_or_b64 exec, exec, s[28:29]
	v_ashrrev_i32_e32 v47, 31, v46
	v_lshlrev_b64 v[46:47], 12, v[46:47]
	v_lshl_add_u64 v[46:47], v[50:51], 0, v[46:47]
	v_lshl_add_u64 v[46:47], v[46:47], 0, v[176:177]
	v_mul_f32_e32 v17, v29, v54
	global_store_dword v[46:47], v17, off
	v_add3_u32 v19, v86, v87, 58
	v_mul_hi_i32 v17, v19, s35
	v_lshrrev_b32_e32 v21, 31, v17
	v_ashrrev_i32_e32 v17, 11, v17
	v_add_u32_e32 v17, v17, v21
	v_mad_i32_i24 v19, v17, s33, v19
	v_lshlrev_b32_e32 v21, 13, v17
	v_cmp_lt_i32_e64 s[28:29], s82, v19
	v_add3_u32 v46, v21, v19, s79
	s_and_saveexec_b64 s[30:31], s[28:29]
	s_xor_b64 s[30:31], exec, s[30:31]
	s_mov_b64 s[74:75], s[92:93]
	v_add3_u32 v50, v21, v19, s79
	s_or_saveexec_b64 s[30:31], s[30:31]
	s_waitcnt lgkmcnt(0)
	v_mov_b64_e32 v[52:53], s[74:75]
	v_lshl_add_u32 v47, v17, 8, v19
	s_xor_b64 exec, exec, s[30:31]
	v_lshl_add_u32 v50, v17, 8, v19
	v_mov_b64_e32 v[52:53], s[64:65]
	s_or_b64 exec, exec, s[30:31]
	v_ashrrev_i32_e32 v51, 31, v50
	v_lshlrev_b64 v[50:51], 12, v[50:51]
	v_lshl_add_u64 v[50:51], v[52:53], 0, v[50:51]
	v_lshl_add_u64 v[50:51], v[50:51], 0, v[176:177]
	v_mul_f32_e32 v17, v30, v54
	global_store_dword v[50:51], v17, off
	v_add3_u32 v19, v86, v87, 59
	v_mul_hi_i32 v17, v19, s35
	v_lshrrev_b32_e32 v21, 31, v17
	v_ashrrev_i32_e32 v17, 11, v17
	v_add_u32_e32 v17, v17, v21
	v_mad_i32_i24 v19, v17, s33, v19
	v_lshlrev_b32_e32 v21, 13, v17
	v_cmp_lt_i32_e64 s[30:31], s82, v19
	v_add3_u32 v30, v21, v19, s79
	s_and_saveexec_b64 s[74:75], s[30:31]
	s_xor_b64 s[74:75], exec, s[74:75]
	s_mov_b64 s[76:77], s[92:93]
	v_add3_u32 v50, v21, v19, s79
	s_or_saveexec_b64 s[74:75], s[74:75]
	s_waitcnt lgkmcnt(0)
	v_mov_b64_e32 v[52:53], s[76:77]
	v_lshl_add_u32 v62, v17, 8, v19
	s_xor_b64 exec, exec, s[74:75]
	v_lshl_add_u32 v50, v17, 8, v19
	v_mov_b64_e32 v[52:53], s[64:65]
	s_or_b64 exec, exec, s[74:75]
	v_ashrrev_i32_e32 v51, 31, v50
	v_lshlrev_b64 v[50:51], 12, v[50:51]
	v_lshl_add_u64 v[50:51], v[52:53], 0, v[50:51]
	v_mov_b32_e32 v49, v177
	v_lshl_add_u64 v[50:51], v[50:51], 0, v[176:177]
	v_mul_f32_e32 v17, v31, v54
	v_lshl_add_u64 v[48:49], s[58:59], 0, v[48:49]
	global_store_dword v[50:51], v17, off
	global_load_dword v50, v[48:49], off
	s_and_saveexec_b64 s[74:75], vcc
	s_xor_b64 s[74:75], exec, s[74:75]
	s_mov_b64 s[76:77], s[92:93]
	s_or_saveexec_b64 s[74:75], s[74:75]
	s_waitcnt lgkmcnt(0)
	v_mov_b64_e32 v[48:49], s[76:77]
	s_xor_b64 exec, exec, s[74:75]
	v_mov_b64_e32 v[48:49], s[64:65]
	v_mov_b32_e32 v32, v33
	s_or_b64 exec, exec, s[74:75]
	v_ashrrev_i32_e32 v33, 31, v32
	v_lshlrev_b64 v[32:33], 12, v[32:33]
	v_lshl_add_u64 v[32:33], v[48:49], 0, v[32:33]
	v_lshl_add_u64 v[32:33], v[32:33], 0, v[176:177]
	s_waitcnt vmcnt(0)
	v_mul_f32_e32 v0, v0, v50
	global_store_dword v[32:33], v0, off offset:128
	s_and_saveexec_b64 s[76:77], s[2:3]
	s_xor_b64 s[2:3], exec, s[76:77]
	s_mov_b64 s[74:75], s[92:93]
	s_or_saveexec_b64 s[2:3], s[2:3]
	s_waitcnt lgkmcnt(0)
	v_mov_b64_e32 v[32:33], s[74:75]
	s_xor_b64 exec, exec, s[2:3]
	v_mov_b64_e32 v[32:33], s[64:65]
	v_mov_b32_e32 v16, v55
	s_or_b64 exec, exec, s[2:3]
	v_ashrrev_i32_e32 v17, 31, v16
	v_lshlrev_b64 v[16:17], 12, v[16:17]
	v_lshl_add_u64 v[16:17], v[32:33], 0, v[16:17]
	v_lshl_add_u64 v[16:17], v[16:17], 0, v[176:177]
	v_mul_f32_e32 v0, v1, v50
	global_store_dword v[16:17], v0, off offset:128
	s_and_saveexec_b64 s[2:3], s[4:5]
	s_xor_b64 s[2:3], exec, s[2:3]
	s_mov_b64 s[74:75], s[92:93]
	s_or_saveexec_b64 s[2:3], s[2:3]
	s_waitcnt lgkmcnt(0)
	v_mov_b64_e32 v[0:1], s[74:75]
	s_xor_b64 exec, exec, s[2:3]
	v_mov_b64_e32 v[0:1], s[64:65]
	v_mov_b32_e32 v34, v35
	s_or_b64 exec, exec, s[2:3]
	v_ashrrev_i32_e32 v35, 31, v34
	v_lshlrev_b64 v[16:17], 12, v[34:35]
	v_lshl_add_u64 v[0:1], v[0:1], 0, v[16:17]
	v_lshl_add_u64 v[0:1], v[0:1], 0, v[176:177]
	v_mul_f32_e32 v2, v2, v50
	global_store_dword v[0:1], v2, off offset:128
	s_and_saveexec_b64 s[2:3], s[6:7]
	s_xor_b64 s[2:3], exec, s[2:3]
	s_mov_b64 s[4:5], s[92:93]
	s_or_saveexec_b64 s[2:3], s[2:3]
	s_waitcnt lgkmcnt(0)
	v_mov_b64_e32 v[0:1], s[4:5]
	s_xor_b64 exec, exec, s[2:3]
	v_mov_b64_e32 v[0:1], s[64:65]
	v_mov_b32_e32 v18, v56
	s_or_b64 exec, exec, s[2:3]
	v_ashrrev_i32_e32 v19, 31, v18
	v_lshlrev_b64 v[16:17], 12, v[18:19]
	v_lshl_add_u64 v[0:1], v[0:1], 0, v[16:17]
	v_lshl_add_u64 v[0:1], v[0:1], 0, v[176:177]
	v_mul_f32_e32 v2, v3, v50
	global_store_dword v[0:1], v2, off offset:128
	s_and_saveexec_b64 s[2:3], s[8:9]
	s_xor_b64 s[2:3], exec, s[2:3]
	s_mov_b64 s[4:5], s[92:93]
	s_or_saveexec_b64 s[2:3], s[2:3]
	s_waitcnt lgkmcnt(0)
	v_mov_b64_e32 v[0:1], s[4:5]
	s_xor_b64 exec, exec, s[2:3]
	v_mov_b64_e32 v[0:1], s[64:65]
	v_mov_b32_e32 v36, v37
	s_or_b64 exec, exec, s[2:3]
	v_ashrrev_i32_e32 v37, 31, v36
	v_lshlrev_b64 v[2:3], 12, v[36:37]
	v_lshl_add_u64 v[0:1], v[0:1], 0, v[2:3]
	v_lshl_add_u64 v[0:1], v[0:1], 0, v[176:177]
	v_mul_f32_e32 v2, v4, v50
	global_store_dword v[0:1], v2, off offset:128
	s_and_saveexec_b64 s[2:3], s[10:11]
	s_xor_b64 s[2:3], exec, s[2:3]
	s_mov_b64 s[4:5], s[92:93]
	s_or_saveexec_b64 s[2:3], s[2:3]
	s_waitcnt lgkmcnt(0)
	v_mov_b64_e32 v[0:1], s[4:5]
	s_xor_b64 exec, exec, s[2:3]
	v_mov_b64_e32 v[0:1], s[64:65]
	v_mov_b32_e32 v20, v57
	s_or_b64 exec, exec, s[2:3]
	v_ashrrev_i32_e32 v21, 31, v20
	v_lshlrev_b64 v[2:3], 12, v[20:21]
	v_lshl_add_u64 v[0:1], v[0:1], 0, v[2:3]
	v_lshl_add_u64 v[0:1], v[0:1], 0, v[176:177]
	v_mul_f32_e32 v2, v5, v50
	global_store_dword v[0:1], v2, off offset:128
	s_and_saveexec_b64 s[2:3], s[12:13]
	s_xor_b64 s[2:3], exec, s[2:3]
	s_mov_b64 s[4:5], s[92:93]
	s_or_saveexec_b64 s[2:3], s[2:3]
	s_waitcnt lgkmcnt(0)
	v_mov_b64_e32 v[0:1], s[4:5]
	s_xor_b64 exec, exec, s[2:3]
	v_mov_b64_e32 v[0:1], s[64:65]
	v_mov_b32_e32 v38, v39
	s_or_b64 exec, exec, s[2:3]
	v_ashrrev_i32_e32 v39, 31, v38
	v_lshlrev_b64 v[2:3], 12, v[38:39]
	v_lshl_add_u64 v[0:1], v[0:1], 0, v[2:3]
	v_lshl_add_u64 v[0:1], v[0:1], 0, v[176:177]
	v_mul_f32_e32 v2, v6, v50
	global_store_dword v[0:1], v2, off offset:128
	s_and_saveexec_b64 s[2:3], s[14:15]
	s_xor_b64 s[2:3], exec, s[2:3]
	s_mov_b64 s[4:5], s[92:93]
	s_or_saveexec_b64 s[2:3], s[2:3]
	s_waitcnt lgkmcnt(0)
	v_mov_b64_e32 v[0:1], s[4:5]
	s_xor_b64 exec, exec, s[2:3]
	v_mov_b64_e32 v[0:1], s[64:65]
	v_mov_b32_e32 v22, v58
	s_or_b64 exec, exec, s[2:3]
	v_ashrrev_i32_e32 v23, 31, v22
	v_lshlrev_b64 v[2:3], 12, v[22:23]
	v_lshl_add_u64 v[0:1], v[0:1], 0, v[2:3]
	v_lshl_add_u64 v[0:1], v[0:1], 0, v[176:177]
	v_mul_f32_e32 v2, v7, v50
	global_store_dword v[0:1], v2, off offset:128
	s_and_saveexec_b64 s[2:3], s[16:17]
	s_xor_b64 s[2:3], exec, s[2:3]
	s_mov_b64 s[4:5], s[92:93]
	s_or_saveexec_b64 s[2:3], s[2:3]
	s_waitcnt lgkmcnt(0)
	v_mov_b64_e32 v[0:1], s[4:5]
	s_xor_b64 exec, exec, s[2:3]
	v_mov_b64_e32 v[0:1], s[64:65]
	v_mov_b32_e32 v40, v41
	s_or_b64 exec, exec, s[2:3]
	v_ashrrev_i32_e32 v41, 31, v40
	v_lshlrev_b64 v[2:3], 12, v[40:41]
	v_lshl_add_u64 v[0:1], v[0:1], 0, v[2:3]
	v_lshl_add_u64 v[0:1], v[0:1], 0, v[176:177]
	v_mul_f32_e32 v2, v8, v50
	global_store_dword v[0:1], v2, off offset:128
	s_and_saveexec_b64 s[2:3], s[18:19]
	s_xor_b64 s[2:3], exec, s[2:3]
	s_mov_b64 s[4:5], s[92:93]
	s_or_saveexec_b64 s[2:3], s[2:3]
	s_waitcnt lgkmcnt(0)
	v_mov_b64_e32 v[0:1], s[4:5]
	s_xor_b64 exec, exec, s[2:3]
	v_mov_b64_e32 v[0:1], s[64:65]
	v_mov_b32_e32 v24, v59
	s_or_b64 exec, exec, s[2:3]
	v_ashrrev_i32_e32 v25, 31, v24
	v_lshlrev_b64 v[2:3], 12, v[24:25]
	v_lshl_add_u64 v[0:1], v[0:1], 0, v[2:3]
	v_lshl_add_u64 v[0:1], v[0:1], 0, v[176:177]
	v_mul_f32_e32 v2, v9, v50
	global_store_dword v[0:1], v2, off offset:128
	s_and_saveexec_b64 s[2:3], s[20:21]
	s_xor_b64 s[2:3], exec, s[2:3]
	s_mov_b64 s[4:5], s[92:93]
	s_or_saveexec_b64 s[2:3], s[2:3]
	s_waitcnt lgkmcnt(0)
	v_mov_b64_e32 v[0:1], s[4:5]
	s_xor_b64 exec, exec, s[2:3]
	v_mov_b64_e32 v[0:1], s[64:65]
	v_mov_b32_e32 v42, v43
	s_or_b64 exec, exec, s[2:3]
	v_ashrrev_i32_e32 v43, 31, v42
	v_lshlrev_b64 v[2:3], 12, v[42:43]
	v_lshl_add_u64 v[0:1], v[0:1], 0, v[2:3]
	v_lshl_add_u64 v[0:1], v[0:1], 0, v[176:177]
	v_mul_f32_e32 v2, v10, v50
	global_store_dword v[0:1], v2, off offset:128
	s_and_saveexec_b64 s[2:3], s[22:23]
	s_xor_b64 s[2:3], exec, s[2:3]
	s_mov_b64 s[4:5], s[92:93]
	s_or_saveexec_b64 s[2:3], s[2:3]
	s_waitcnt lgkmcnt(0)
	v_mov_b64_e32 v[0:1], s[4:5]
	s_xor_b64 exec, exec, s[2:3]
	v_mov_b64_e32 v[0:1], s[64:65]
	v_mov_b32_e32 v26, v60
	s_or_b64 exec, exec, s[2:3]
	v_ashrrev_i32_e32 v27, 31, v26
	v_lshlrev_b64 v[2:3], 12, v[26:27]
	v_lshl_add_u64 v[0:1], v[0:1], 0, v[2:3]
	v_lshl_add_u64 v[0:1], v[0:1], 0, v[176:177]
	v_mul_f32_e32 v2, v11, v50
	global_store_dword v[0:1], v2, off offset:128
	s_and_saveexec_b64 s[2:3], s[24:25]
	s_xor_b64 s[2:3], exec, s[2:3]
	s_mov_b64 s[4:5], s[92:93]
	s_or_saveexec_b64 s[2:3], s[2:3]
	s_waitcnt lgkmcnt(0)
	v_mov_b64_e32 v[0:1], s[4:5]
	s_xor_b64 exec, exec, s[2:3]
	v_mov_b64_e32 v[0:1], s[64:65]
	v_mov_b32_e32 v44, v45
	s_or_b64 exec, exec, s[2:3]
	v_ashrrev_i32_e32 v45, 31, v44
	v_lshlrev_b64 v[2:3], 12, v[44:45]
	v_lshl_add_u64 v[0:1], v[0:1], 0, v[2:3]
	v_lshl_add_u64 v[0:1], v[0:1], 0, v[176:177]
	v_mul_f32_e32 v2, v12, v50
	global_store_dword v[0:1], v2, off offset:128
	s_and_saveexec_b64 s[2:3], s[26:27]
	s_xor_b64 s[2:3], exec, s[2:3]
	s_mov_b64 s[4:5], s[92:93]
	s_or_saveexec_b64 s[2:3], s[2:3]
	s_waitcnt lgkmcnt(0)
	v_mov_b64_e32 v[0:1], s[4:5]
	s_xor_b64 exec, exec, s[2:3]
	v_mov_b64_e32 v[0:1], s[64:65]
	v_mov_b32_e32 v28, v61
	s_or_b64 exec, exec, s[2:3]
	v_ashrrev_i32_e32 v29, 31, v28
	v_lshlrev_b64 v[2:3], 12, v[28:29]
	v_lshl_add_u64 v[0:1], v[0:1], 0, v[2:3]
	v_lshl_add_u64 v[0:1], v[0:1], 0, v[176:177]
	v_mul_f32_e32 v2, v13, v50
	global_store_dword v[0:1], v2, off offset:128
	s_and_saveexec_b64 s[2:3], s[28:29]
	s_xor_b64 s[2:3], exec, s[2:3]
	s_mov_b64 s[4:5], s[92:93]
	s_or_saveexec_b64 s[2:3], s[2:3]
	s_waitcnt lgkmcnt(0)
	v_mov_b64_e32 v[0:1], s[4:5]
	s_xor_b64 exec, exec, s[2:3]
	v_mov_b64_e32 v[0:1], s[64:65]
	v_mov_b32_e32 v46, v47
	s_or_b64 exec, exec, s[2:3]
	v_ashrrev_i32_e32 v47, 31, v46
	v_lshlrev_b64 v[2:3], 12, v[46:47]
	v_lshl_add_u64 v[0:1], v[0:1], 0, v[2:3]
	v_lshl_add_u64 v[0:1], v[0:1], 0, v[176:177]
	v_mul_f32_e32 v2, v14, v50
	global_store_dword v[0:1], v2, off offset:128
	s_and_saveexec_b64 s[2:3], s[30:31]
	s_xor_b64 s[2:3], exec, s[2:3]
	s_mov_b64 s[4:5], s[92:93]
	s_or_saveexec_b64 s[2:3], s[2:3]
	s_waitcnt lgkmcnt(0)
	v_mov_b64_e32 v[0:1], s[4:5]
	s_xor_b64 exec, exec, s[2:3]
	s_cbranch_execz .LBB0_1171
	v_mov_b64_e32 v[0:1], s[64:65]
	v_mov_b32_e32 v30, v62
	s_branch .LBB0_1171

.LBB0_1487:
	v_mul_hi_i32 v0, v16, s35
	v_lshrrev_b32_e32 v1, 31, v0
	v_ashrrev_i32_e32 v0, 11, v0
	v_add_u32_e32 v19, v0, v1
	v_mad_i32_i24 v1, v19, s33, v16
	v_cmp_gt_i32_e64 s[4:5], s95, v1
	s_and_b64 s[16:17], s[56:57], s[4:5]
	v_cmp_lt_i32_e32 vcc, s82, v1
	s_xor_b64 s[18:19], s[16:17], -1
	s_and_saveexec_b64 s[16:17], s[18:19]
	s_cbranch_execz .LBB0_1486
	s_and_saveexec_b64 s[18:19], vcc
	s_xor_b64 s[18:19], exec, s[18:19]
	s_load_dwordx2 s[20:21], s[0:1], 0xe8
	v_mul_i32_i24_e32 v0, 0xffffdf00, v19
	v_lshl_add_u32 v0, v19, 13, v0
	v_add3_u32 v0, v16, v0, s79
	s_or_saveexec_b64 s[18:19], s[18:19]
	s_waitcnt lgkmcnt(0)
	v_mov_b64_e32 v[2:3], s[20:21]
	s_xor_b64 exec, exec, s[18:19]
	v_lshl_add_u32 v0, v19, 8, v1
	v_mov_b64_e32 v[2:3], s[10:11]
	s_or_b64 exec, exec, s[18:19]
	v_ashrrev_i32_e32 v1, 31, v0
	v_lshlrev_b64 v[0:1], 12, v[0:1]
	v_lshl_add_u64 v[0:1], v[2:3], 0, v[0:1]
	v_lshlrev_b32_e32 v176, 2, v18
	v_lshl_add_u64 v[32:33], v[0:1], 0, v[176:177]
	s_cmp_eq_u64 s[4:5], 0
	s_cbranch_scc1 .Lctxp_ln2_a
	s_mov_b32 s22, 0x8e40000
	s_mov_b32 s23, 0
	v_lshl_add_u64 v[178:179], v[32:33], 0, s[22:23]
	global_load_dwordx4 v[56:59], v[178:179], off
	global_load_dwordx4 v[60:63], v[178:179], off offset:1024
	global_load_dwordx4 v[64:67], v[178:179], off offset:2048
	global_load_dwordx4 v[68:71], v[178:179], off offset:3072
	s_add_u32 s22, s22, 0x200000
	v_lshl_add_u64 v[178:179], v[32:33], 0, s[22:23]
	global_load_dwordx4 v[72:75], v[178:179], off
	global_load_dwordx4 v[76:79], v[178:179], off offset:1024
	global_load_dwordx4 v[102:105], v[178:179], off offset:2048
	global_load_dwordx4 v[106:109], v[178:179], off offset:3072
	s_add_u32 s22, s22, 0x200000
	v_lshl_add_u64 v[178:179], v[32:33], 0, s[22:23]
	global_load_dwordx4 v[110:113], v[178:179], off
	global_load_dwordx4 v[114:117], v[178:179], off offset:1024
	global_load_dwordx4 v[118:121], v[178:179], off offset:2048
	global_load_dwordx4 v[122:125], v[178:179], off offset:3072
	s_add_u32 s22, s22, 0x200000
	v_lshl_add_u64 v[178:179], v[32:33], 0, s[22:23]
	global_load_dwordx4 v[126:129], v[178:179], off
	global_load_dwordx4 v[130:133], v[178:179], off offset:1024
	global_load_dwordx4 v[134:137], v[178:179], off offset:2048
	global_load_dwordx4 v[172:175], v[178:179], off offset:3072
.Lctxp_ln2_a:
	global_load_dwordx4 v[12:15], v[32:33], off
	global_load_dwordx4 v[8:11], v[32:33], off offset:1024
	global_load_dwordx4 v[4:7], v[32:33], off offset:2048
	global_load_dwordx4 v[0:3], v[32:33], off offset:3072
	v_and_b32_e32 v27, 64, v196
	v_add_u32_e32 v27, 64, v27
	v_xor_b32_e32 v29, 32, v196
	v_cmp_lt_i32_e32 vcc, v29, v27
	s_mov_b32 s18, 0x800000
	s_cmp_eq_u64 s[4:5], 0
	s_cbranch_scc1 .Lctxp_ln2_b
	s_waitcnt vmcnt(0)
	v_pk_add_f32 v[56:57], v[56:57], v[72:73]
	v_pk_add_f32 v[110:111], v[110:111], v[126:127]
	v_pk_add_f32 v[56:57], v[56:57], v[110:111]
	v_pk_add_f32 v[12:13], v[12:13], v[56:57]
	v_pk_add_f32 v[58:59], v[58:59], v[74:75]
	v_pk_add_f32 v[112:113], v[112:113], v[128:129]
	v_pk_add_f32 v[58:59], v[58:59], v[112:113]
	v_pk_add_f32 v[14:15], v[14:15], v[58:59]
	v_pk_add_f32 v[60:61], v[60:61], v[76:77]
	v_pk_add_f32 v[114:115], v[114:115], v[130:131]
	v_pk_add_f32 v[60:61], v[60:61], v[114:115]
	v_pk_add_f32 v[8:9], v[8:9], v[60:61]
	v_pk_add_f32 v[62:63], v[62:63], v[78:79]
	v_pk_add_f32 v[116:117], v[116:117], v[132:133]
	v_pk_add_f32 v[62:63], v[62:63], v[116:117]
	v_pk_add_f32 v[10:11], v[10:11], v[62:63]
	v_pk_add_f32 v[64:65], v[64:65], v[102:103]
	v_pk_add_f32 v[118:119], v[118:119], v[134:135]
	v_pk_add_f32 v[64:65], v[64:65], v[118:119]
	v_pk_add_f32 v[4:5], v[4:5], v[64:65]
	v_pk_add_f32 v[66:67], v[66:67], v[104:105]
	v_pk_add_f32 v[120:121], v[120:121], v[136:137]
	v_pk_add_f32 v[66:67], v[66:67], v[120:121]
	v_pk_add_f32 v[6:7], v[6:7], v[66:67]
	v_pk_add_f32 v[68:69], v[68:69], v[106:107]
	v_pk_add_f32 v[122:123], v[122:123], v[172:173]
	v_pk_add_f32 v[68:69], v[68:69], v[122:123]
	v_pk_add_f32 v[0:1], v[0:1], v[68:69]
	v_pk_add_f32 v[70:71], v[70:71], v[108:109]
	v_pk_add_f32 v[124:125], v[124:125], v[174:175]
	v_pk_add_f32 v[70:71], v[70:71], v[124:125]
	v_pk_add_f32 v[2:3], v[2:3], v[70:71]
.Lctxp_ln2_b:
	s_waitcnt vmcnt(3)
	v_mov_b32_e32 v34, v13
	v_mov_b32_e32 v35, v14
	v_mov_b32_e32 v36, v12
	v_mov_b32_e32 v37, v15
	v_pk_add_f32 v[34:35], v[34:35], v[36:37]
	s_waitcnt vmcnt(2)
	v_mov_b32_e32 v36, v9
	v_mov_b32_e32 v37, v10
	v_mov_b32_e32 v38, v8
	v_mov_b32_e32 v39, v11
	v_pk_add_f32 v[36:37], v[36:37], v[38:39]
	v_add_f32_e32 v17, v34, v35
	v_pk_add_f32 v[36:37], v[36:37], v[36:37] op_sel:[0,1] op_sel_hi:[1,0]
	v_add_f32_e32 v34, 0, v17
	s_waitcnt vmcnt(1)
	v_add_f32_e32 v38, v4, v5
	v_add_f32_e32 v40, v6, v7
	s_waitcnt vmcnt(0)
	v_mov_b32_e32 v35, v0
	v_mov_b32_e32 v37, v1
	v_mov_b32_e32 v39, v2
	v_mov_b32_e32 v41, v3
	v_pk_add_f32 v[34:35], v[34:35], v[36:37]
	v_pk_add_f32 v[36:37], v[38:39], v[40:41]
	v_cndmask_b32_e32 v29, v196, v29, vcc
	v_pk_add_f32 v[34:35], v[34:35], v[36:37]
	v_lshlrev_b32_e32 v29, 2, v29
	v_add_f32_e32 v17, v34, v35
	ds_bpermute_b32 v31, v29, v17
	s_waitcnt lgkmcnt(0)
	v_add_f32_e32 v17, v17, v31
	v_xor_b32_e32 v31, 16, v196
	v_cmp_lt_i32_e32 vcc, v31, v27
	s_nop 1
	v_cndmask_b32_e32 v31, v196, v31, vcc
	v_lshlrev_b32_e32 v31, 2, v31
	ds_bpermute_b32 v34, v31, v17
	s_waitcnt lgkmcnt(0)
	v_add_f32_e32 v17, v17, v34
	v_xor_b32_e32 v34, 8, v196
	v_cmp_lt_i32_e32 vcc, v34, v27
	s_nop 1
	v_cndmask_b32_e32 v34, v196, v34, vcc
	v_lshlrev_b32_e32 v42, 2, v34
	ds_bpermute_b32 v34, v42, v17
	s_waitcnt lgkmcnt(0)
	v_add_f32_e32 v17, v17, v34
	v_xor_b32_e32 v34, 4, v196
	v_cmp_lt_i32_e32 vcc, v34, v27
	s_nop 1
	v_cndmask_b32_e32 v34, v196, v34, vcc
	v_lshlrev_b32_e32 v43, 2, v34
	ds_bpermute_b32 v34, v43, v17
	s_waitcnt lgkmcnt(0)
	v_add_f32_e32 v17, v17, v34
	v_xor_b32_e32 v34, 2, v196
	v_cmp_lt_i32_e32 vcc, v34, v27
	s_nop 1
	v_cndmask_b32_e32 v34, v196, v34, vcc
	v_lshlrev_b32_e32 v44, 2, v34
	ds_bpermute_b32 v34, v44, v17
	s_waitcnt lgkmcnt(0)
	v_add_f32_e32 v17, v17, v34
	v_xor_b32_e32 v34, 1, v196
	v_cmp_lt_i32_e32 vcc, v34, v27
	s_nop 1
	v_cndmask_b32_e32 v27, v196, v34, vcc
	v_lshlrev_b32_e32 v27, 2, v27
	ds_bpermute_b32 v34, v27, v17
	s_waitcnt lgkmcnt(0)
	v_add_f32_e32 v17, v17, v34
	v_fmamk_f32 v13, v17, 0xba800000, v13
	v_fmamk_f32 v12, v17, 0xba800000, v12
	v_fmamk_f32 v15, v17, 0xba800000, v15
	v_fmac_f32_e32 v14, 0xba800000, v17
	v_pk_mul_f32 v[34:35], v[14:15], v[14:15]
	v_pk_mul_f32 v[36:37], v[12:13], v[12:13]
	v_fmamk_f32 v9, v17, 0xba800000, v9
	v_pk_mov_b32 v[38:39], v[36:37], v[34:35] op_sel:[1,0]
	v_mov_b32_e32 v37, v35
	v_pk_add_f32 v[34:35], v[38:39], v[36:37]
	v_fmamk_f32 v8, v17, 0xba800000, v8
	v_fmamk_f32 v11, v17, 0xba800000, v11
	v_fmac_f32_e32 v10, 0xba800000, v17
	v_pk_add_f32 v[34:35], v[34:35], v[34:35] op_sel_hi:[0,1]
	v_pk_mul_f32 v[36:37], v[10:11], v[10:11]
	v_pk_mul_f32 v[38:39], v[8:9], v[8:9]
	v_fmamk_f32 v4, v17, 0xba800000, v4
	v_pk_mov_b32 v[40:41], v[38:39], v[36:37] op_sel:[1,0]
	v_mov_b32_e32 v39, v37
	v_fmamk_f32 v5, v17, 0xba800000, v5
	v_fmac_f32_e32 v6, 0xba800000, v17
	v_mul_f32_e32 v34, v4, v4
	v_pk_add_f32 v[36:37], v[40:41], v[38:39]
	v_fmamk_f32 v7, v17, 0xba800000, v7
	v_pk_fma_f32 v[38:39], v[4:5], v[4:5], v[34:35] op_sel_hi:[1,1,0]
	v_mul_f32_e32 v34, v6, v6
	v_pk_add_f32 v[36:37], v[36:37], v[36:37] op_sel_hi:[0,1]
	v_pk_fma_f32 v[40:41], v[6:7], v[6:7], v[34:35] op_sel_hi:[1,1,0]
	v_fmamk_f32 v3, v17, 0xba800000, v3
	v_fmamk_f32 v2, v17, 0xba800000, v2
	v_fmamk_f32 v1, v17, 0xba800000, v1
	v_fmac_f32_e32 v0, 0xba800000, v17
	v_mul_f32_e32 v38, v0, v0
	v_mul_f32_e32 v40, v1, v1
	v_mul_f32_e32 v34, v2, v2
	v_mul_f32_e32 v36, v3, v3
	v_pk_add_f32 v[38:39], v[38:39], v[40:41]
	v_pk_add_f32 v[34:35], v[34:35], v[36:37]
	s_nop 0
	v_pk_add_f32 v[34:35], v[38:39], v[34:35]
	s_nop 0
	v_add_f32_e32 v17, v34, v35
	ds_bpermute_b32 v29, v29, v17
	s_waitcnt lgkmcnt(0)
	v_add_f32_e32 v17, v17, v29
	ds_bpermute_b32 v29, v31, v17
	s_waitcnt lgkmcnt(0)
	v_add_f32_e32 v17, v17, v29
	ds_bpermute_b32 v29, v42, v17
	s_waitcnt lgkmcnt(0)
	v_add_f32_e32 v17, v17, v29
	ds_bpermute_b32 v29, v43, v17
	s_waitcnt lgkmcnt(0)
	v_add_f32_e32 v17, v17, v29
	ds_bpermute_b32 v29, v44, v17
	s_waitcnt lgkmcnt(0)
	v_add_f32_e32 v17, v17, v29
	ds_bpermute_b32 v27, v27, v17
	s_waitcnt lgkmcnt(0)
	v_add_f32_e32 v17, v17, v27
	v_fmamk_f32 v17, v17, 0x3a800000, v197
	v_cmp_gt_f32_e32 vcc, s18, v17
	v_mul_f32_e32 v27, 0x4b800000, v17
	s_nop 0
	v_cndmask_b32_e32 v17, v17, v27, vcc
	v_rsq_f32_e32 v17, v17
	s_nop 0
	v_mul_f32_e32 v27, 0x45800000, v17
	v_cndmask_b32_e32 v34, v17, v27, vcc
	v_pk_mul_f32 v[12:13], v[12:13], v[34:35] op_sel_hi:[1,0]
	v_pk_mul_f32 v[14:15], v[14:15], v[34:35] op_sel_hi:[1,0]
	v_pk_mul_f32 v[8:9], v[8:9], v[34:35] op_sel_hi:[1,0]
	v_pk_mul_f32 v[10:11], v[10:11], v[34:35] op_sel_hi:[1,0]
	v_pk_mul_f32 v[4:5], v[4:5], v[34:35] op_sel_hi:[1,0]
	v_pk_mul_f32 v[6:7], v[6:7], v[34:35] op_sel_hi:[1,0]
	v_pk_mul_f32 v[0:1], v[0:1], v[34:35] op_sel_hi:[1,0]
	v_pk_mul_f32 v[2:3], v[2:3], v[34:35] op_sel_hi:[1,0]
	s_andn2_b64 vcc, exec, s[60:61]
	v_pk_fma_f32 v[14:15], v[142:143], v[14:15], v[146:147]
	v_pk_fma_f32 v[12:13], v[140:141], v[12:13], v[144:145]
	v_pk_fma_f32 v[10:11], v[150:151], v[10:11], v[154:155]
	v_pk_fma_f32 v[8:9], v[148:149], v[8:9], v[152:153]
	v_pk_fma_f32 v[6:7], v[158:159], v[6:7], v[162:163]
	v_pk_fma_f32 v[4:5], v[156:157], v[4:5], v[160:161]
	v_pk_fma_f32 v[2:3], v[166:167], v[2:3], v[170:171]
	v_pk_fma_f32 v[0:1], v[164:165], v[0:1], v[168:169]
	global_store_dwordx4 v[32:33], v[12:15], off
	global_store_dwordx4 v[32:33], v[8:11], off offset:1024
	global_store_dwordx4 v[32:33], v[4:7], off offset:2048
	global_store_dwordx4 v[32:33], v[0:3], off offset:3072
	s_cbranch_vccnz .LBB0_1486
	v_ashrrev_i32_e32 v17, 31, v16
	s_and_saveexec_b64 s[18:19], s[2:3]
	s_cbranch_execz .LBB0_1485
	v_mov_b32_e32 v34, v177
	v_lshl_add_u64 v[32:33], v[16:17], 3, s[12:13]
	s_nop 0
	v_mov_b32_e32 v35, v34
	global_store_dwordx2 v[32:33], v[34:35], off
	s_branch .LBB0_1485
